# ctx Resid epilogues pipelined (sites B,D) + split-phase rmsnorm row loop: g preloaded, all row loads issued together; sc1 write-through resid stores; chain state-update LDS reads pipelined
# speedup vs baseline: 1.0211x; 1.0087x over previous
;     ...
;         const bool has_next = S.next(ui + 1, nxt);
;         const char* nA = has_next ? (const char*)gA + (size_t)nxt.pm * tstep : cA; const char* nB = has_next ? (const char*)gBt + (size_t)nxt.pn * tstep : cB;
;     ...
; #pragma unroll
;         for (int a = 0; a < 2; ++a)
; #pragma unroll
;             for (int b = 0; b < 2; ++b)
; #pragma unroll
;                 for (int m = 0; m < 4; ++m)
; #pragma unroll
;                     for (int n = 0; n < 2; ++n) acc[a][b][m][n] = (f32x4){0.f, 0.f, 0.f, 0.f};
;         cur = nxt; cA = nA; cB = nB; ++ui;
.LBB0_160:
	s_ashr_i32 s53, s52, 31
	v_cmp_lt_i64_e32 vcc, s[14:15], v[136:137]
	s_lshl_b64 s[14:15], s[52:53], 19
	s_add_u32 s54, s24, s14
	s_addc_u32 s55, s25, s15
	s_and_b64 s[14:15], vcc, exec
	s_cselect_b32 s4, s55, s11
	s_cselect_b32 s7, s54, s10
	s_ashr_i32 s51, s50, 31
	s_lshl_b64 s[14:15], s[50:51], 19
	v_readlane_b32 s0, v251, 54
	v_readlane_b32 s1, v251, 55
	s_waitcnt lgkmcnt(0)
	s_add_u32 s56, s0, s14
	s_addc_u32 s57, s1, s15
	s_and_b64 s[14:15], vcc, exec
	s_cselect_b32 s18, s57, s13
	s_cselect_b32 s19, s56, s12
	s_add_u32 s10, s10, 0x40080
	s_addc_u32 s11, s11, 0
	s_add_u32 s22, s12, 0x100
	v_mov_b32_e32 v2, 0
	s_addc_u32 s23, s13, 0
	s_mov_b32 s28, -2
	v_mov_b32_e32 v3, v2
	v_mov_b32_e32 v4, v2
	v_mov_b32_e32 v5, v2
	v_mov_b32_e32 v18, v2
	v_mov_b32_e32 v19, v2
	v_mov_b32_e32 v20, v2
	v_mov_b32_e32 v21, v2
	v_mov_b32_e32 v6, v2
	v_mov_b32_e32 v7, v2
	v_mov_b32_e32 v8, v2
	v_mov_b32_e32 v9, v2
	v_mov_b32_e32 v22, v2
	v_mov_b32_e32 v23, v2
	v_mov_b32_e32 v24, v2
	v_mov_b32_e32 v25, v2
	v_mov_b32_e32 v10, v2
	v_mov_b32_e32 v11, v2
	v_mov_b32_e32 v12, v2
	v_mov_b32_e32 v13, v2
	v_mov_b32_e32 v26, v2
	v_mov_b32_e32 v27, v2
	v_mov_b32_e32 v28, v2
	v_mov_b32_e32 v29, v2
	v_mov_b32_e32 v14, v2
	v_mov_b32_e32 v15, v2
	v_mov_b32_e32 v16, v2
	v_mov_b32_e32 v17, v2
	v_mov_b32_e32 v34, v2
	v_mov_b32_e32 v35, v2
	v_mov_b32_e32 v36, v2
	v_mov_b32_e32 v37, v2
	v_mov_b32_e32 v46, v2
	v_mov_b32_e32 v47, v2
	v_mov_b32_e32 v48, v2
	v_mov_b32_e32 v49, v2
	v_mov_b32_e32 v78, v2
	v_mov_b32_e32 v79, v2
	v_mov_b32_e32 v80, v2
	v_mov_b32_e32 v81, v2
	v_mov_b32_e32 v54, v2
	v_mov_b32_e32 v55, v2
	v_mov_b32_e32 v56, v2
	v_mov_b32_e32 v57, v2
	v_mov_b32_e32 v86, v2
	v_mov_b32_e32 v87, v2
	v_mov_b32_e32 v88, v2
	v_mov_b32_e32 v89, v2
	v_mov_b32_e32 v62, v2
	v_mov_b32_e32 v63, v2
	v_mov_b32_e32 v64, v2
	v_mov_b32_e32 v65, v2
	v_mov_b32_e32 v90, v2
	v_mov_b32_e32 v91, v2
	v_mov_b32_e32 v92, v2
	v_mov_b32_e32 v93, v2
	v_mov_b32_e32 v70, v2
	v_mov_b32_e32 v71, v2
	v_mov_b32_e32 v72, v2
	v_mov_b32_e32 v73, v2
	v_mov_b32_e32 v98, v2
	v_mov_b32_e32 v99, v2
	v_mov_b32_e32 v100, v2
	v_mov_b32_e32 v101, v2
	v_mov_b32_e32 v30, v2
	v_mov_b32_e32 v31, v2
	v_mov_b32_e32 v32, v2
	v_mov_b32_e32 v33, v2
	v_mov_b32_e32 v58, v2
	v_mov_b32_e32 v59, v2
	v_mov_b32_e32 v60, v2
	v_mov_b32_e32 v61, v2
	v_mov_b32_e32 v38, v2
	v_mov_b32_e32 v39, v2
	v_mov_b32_e32 v40, v2
	v_mov_b32_e32 v41, v2
	v_mov_b32_e32 v66, v2
	v_mov_b32_e32 v67, v2
	v_mov_b32_e32 v68, v2
	v_mov_b32_e32 v69, v2
	v_mov_b32_e32 v42, v2
	v_mov_b32_e32 v43, v2
	v_mov_b32_e32 v44, v2
	v_mov_b32_e32 v45, v2
	v_mov_b32_e32 v74, v2
	v_mov_b32_e32 v75, v2
	v_mov_b32_e32 v76, v2
	v_mov_b32_e32 v77, v2
	v_mov_b32_e32 v50, v2
	v_mov_b32_e32 v51, v2
	v_mov_b32_e32 v52, v2
	v_mov_b32_e32 v53, v2
	v_mov_b32_e32 v82, v2
	v_mov_b32_e32 v83, v2
	v_mov_b32_e32 v84, v2
	v_mov_b32_e32 v85, v2
	v_mov_b32_e32 v94, v2
	v_mov_b32_e32 v95, v2
	v_mov_b32_e32 v96, v2
	v_mov_b32_e32 v97, v2
	v_mov_b32_e32 v114, v2
	v_mov_b32_e32 v115, v2
	v_mov_b32_e32 v116, v2
	v_mov_b32_e32 v117, v2
	v_mov_b32_e32 v102, v2
	v_mov_b32_e32 v103, v2
	v_mov_b32_e32 v104, v2
	v_mov_b32_e32 v105, v2
	v_mov_b32_e32 v118, v2
	v_mov_b32_e32 v119, v2
	v_mov_b32_e32 v120, v2
	v_mov_b32_e32 v121, v2
	v_mov_b32_e32 v106, v2
	v_mov_b32_e32 v107, v2
	v_mov_b32_e32 v108, v2
	v_mov_b32_e32 v109, v2
	v_mov_b32_e32 v122, v2
	v_mov_b32_e32 v123, v2
	v_mov_b32_e32 v124, v2
	v_mov_b32_e32 v125, v2
	v_mov_b32_e32 v110, v2
	v_mov_b32_e32 v111, v2
	v_mov_b32_e32 v112, v2
	v_mov_b32_e32 v113, v2
	v_mov_b32_e32 v126, v2
	v_mov_b32_e32 v127, v2
	v_mov_b32_e32 v128, v2
	v_mov_b32_e32 v129, v2

;     ...
;         const bool has_next = S.next(ui + 1, nxt);
;         const char* nA = has_next ? (const char*)gA + (size_t)nxt.pm * tstep : cA; const char* nB = has_next ? (const char*)gBt + (size_t)nxt.pn * tstep : cB;
;     ...
; #pragma unroll
;         for (int a = 0; a < 2; ++a)
; #pragma unroll
;             for (int b = 0; b < 2; ++b)
; #pragma unroll
;                 for (int m = 0; m < 4; ++m)
; #pragma unroll
;                     for (int n = 0; n < 2; ++n) acc[a][b][m][n] = (f32x4){0.f, 0.f, 0.f, 0.f};
;         cur = nxt; cA = nA; cB = nB; ++ui;
.LBB0_481:
	s_ashr_i32 s59, s58, 31
	v_cmp_lt_i64_e32 vcc, s[14:15], v[140:141]
	s_lshl_b64 s[14:15], s[58:59], 19
	s_add_u32 s60, s24, s14
	s_addc_u32 s61, s25, s15
	s_and_b64 s[14:15], vcc, exec
	s_cselect_b32 s4, s61, s11
	s_cselect_b32 s7, s60, s10
	s_waitcnt lgkmcnt(0)
	s_ashr_i32 s57, s56, 31
	s_lshl_b64 s[14:15], s[56:57], 19
	s_add_u32 s62, s17, s14
	s_addc_u32 s63, s20, s15
	s_and_b64 s[14:15], vcc, exec
	s_cselect_b32 s18, s63, s13
	s_cselect_b32 s19, s62, s12
	s_add_u32 s10, s10, 0x40080
	s_addc_u32 s11, s11, 0
	s_add_u32 s22, s12, 0x100
	v_mov_b32_e32 v2, 0
	s_addc_u32 s23, s13, 0
	s_mov_b32 s28, -2
	v_mov_b32_e32 v3, v2
	v_mov_b32_e32 v4, v2
	v_mov_b32_e32 v5, v2
	v_mov_b32_e32 v18, v2
	v_mov_b32_e32 v19, v2
	v_mov_b32_e32 v20, v2
	v_mov_b32_e32 v21, v2
	v_mov_b32_e32 v6, v2
	v_mov_b32_e32 v7, v2
	v_mov_b32_e32 v8, v2
	v_mov_b32_e32 v9, v2
	v_mov_b32_e32 v22, v2
	v_mov_b32_e32 v23, v2
	v_mov_b32_e32 v24, v2
	v_mov_b32_e32 v25, v2
	v_mov_b32_e32 v10, v2
	v_mov_b32_e32 v11, v2
	v_mov_b32_e32 v12, v2
	v_mov_b32_e32 v13, v2
	v_mov_b32_e32 v26, v2
	v_mov_b32_e32 v27, v2
	v_mov_b32_e32 v28, v2
	v_mov_b32_e32 v29, v2
	v_mov_b32_e32 v14, v2
	v_mov_b32_e32 v15, v2
	v_mov_b32_e32 v16, v2
	v_mov_b32_e32 v17, v2
	v_mov_b32_e32 v34, v2
	v_mov_b32_e32 v35, v2
	v_mov_b32_e32 v36, v2
	v_mov_b32_e32 v37, v2
	v_mov_b32_e32 v46, v2
	v_mov_b32_e32 v47, v2
	v_mov_b32_e32 v48, v2
	v_mov_b32_e32 v49, v2
	v_mov_b32_e32 v78, v2
	v_mov_b32_e32 v79, v2
	v_mov_b32_e32 v80, v2
	v_mov_b32_e32 v81, v2
	v_mov_b32_e32 v54, v2
	v_mov_b32_e32 v55, v2
	v_mov_b32_e32 v56, v2
	v_mov_b32_e32 v57, v2
	v_mov_b32_e32 v86, v2
	v_mov_b32_e32 v87, v2
	v_mov_b32_e32 v88, v2
	v_mov_b32_e32 v89, v2
	v_mov_b32_e32 v62, v2
	v_mov_b32_e32 v63, v2
	v_mov_b32_e32 v64, v2
	v_mov_b32_e32 v65, v2
	v_mov_b32_e32 v90, v2
	v_mov_b32_e32 v91, v2
	v_mov_b32_e32 v92, v2
	v_mov_b32_e32 v93, v2
	v_mov_b32_e32 v70, v2
	v_mov_b32_e32 v71, v2
	v_mov_b32_e32 v72, v2
	v_mov_b32_e32 v73, v2
	v_mov_b32_e32 v98, v2
	v_mov_b32_e32 v99, v2
	v_mov_b32_e32 v100, v2
	v_mov_b32_e32 v101, v2
	v_mov_b32_e32 v30, v2
	v_mov_b32_e32 v31, v2
	v_mov_b32_e32 v32, v2
	v_mov_b32_e32 v33, v2
	v_mov_b32_e32 v58, v2
	v_mov_b32_e32 v59, v2
	v_mov_b32_e32 v60, v2
	v_mov_b32_e32 v61, v2
	v_mov_b32_e32 v38, v2
	v_mov_b32_e32 v39, v2
	v_mov_b32_e32 v40, v2
	v_mov_b32_e32 v41, v2
	v_mov_b32_e32 v66, v2
	v_mov_b32_e32 v67, v2
	v_mov_b32_e32 v68, v2
	v_mov_b32_e32 v69, v2
	v_mov_b32_e32 v42, v2
	v_mov_b32_e32 v43, v2
	v_mov_b32_e32 v44, v2
	v_mov_b32_e32 v45, v2
	v_mov_b32_e32 v74, v2
	v_mov_b32_e32 v75, v2
	v_mov_b32_e32 v76, v2
	v_mov_b32_e32 v77, v2
	v_mov_b32_e32 v50, v2
	v_mov_b32_e32 v51, v2
	v_mov_b32_e32 v52, v2
	v_mov_b32_e32 v53, v2
	v_mov_b32_e32 v82, v2
	v_mov_b32_e32 v83, v2
	v_mov_b32_e32 v84, v2
	v_mov_b32_e32 v85, v2
	v_mov_b32_e32 v94, v2
	v_mov_b32_e32 v95, v2
	v_mov_b32_e32 v96, v2
	v_mov_b32_e32 v97, v2
	v_mov_b32_e32 v114, v2
	v_mov_b32_e32 v115, v2
	v_mov_b32_e32 v116, v2
	v_mov_b32_e32 v117, v2
	v_mov_b32_e32 v102, v2
	v_mov_b32_e32 v103, v2
	v_mov_b32_e32 v104, v2
	v_mov_b32_e32 v105, v2
	v_mov_b32_e32 v118, v2
	v_mov_b32_e32 v119, v2
	v_mov_b32_e32 v120, v2
	v_mov_b32_e32 v121, v2
	v_mov_b32_e32 v106, v2
	v_mov_b32_e32 v107, v2
	v_mov_b32_e32 v108, v2
	v_mov_b32_e32 v109, v2
	v_mov_b32_e32 v122, v2
	v_mov_b32_e32 v123, v2
	v_mov_b32_e32 v124, v2
	v_mov_b32_e32 v125, v2
	v_mov_b32_e32 v110, v2
	v_mov_b32_e32 v111, v2
	v_mov_b32_e32 v112, v2
	v_mov_b32_e32 v113, v2
	v_mov_b32_e32 v126, v2
	v_mov_b32_e32 v127, v2
	v_mov_b32_e32 v128, v2
	v_mov_b32_e32 v129, v2

; #define LAS __attribute__((address_space(3)))
; __device__ __forceinline__ void hg_chain_phase(const Params& p, const bf16_t* qt, const bf16_t* kt, const bf16_t* vT, bf16_t* ob, char* smem) {
;     ...
; #pragma unroll
;             for (int m = 0; m < 2; ++m)
; #pragma unroll
;                 for (int tt = 0; tt < 4; ++tt) {
;                     const bool skip = (dir == 0) ? (m == 1 && tt < 2) : (m == 0 && tt >= 2);
;                     if (!skip) {
;                         const bf16x8 pf = *(const LAS bf16x8*)(Pb + plane + (m * 4) * 1040 + tt * 256);
;                         o[tt] = mfma16(vf[m], pf, o[tt]);
;                     }
;                 }
;             bf16_t* op = ob + ((size_t)dir * T_ALL + row0) * 512 + hh * 128 + dvq * 32 + w * 16 + fq * 4;
; #pragma unroll
;             for (int tt = 0; tt < 4; ++tt) {
;                 u32x2 ov = {pack2(o[tt][0], o[tt][1]), pack2(o[tt][2], o[tt][3])};
;                 *reinterpret_cast<u32x2*>(op + (size_t)(tt * 16 + fr) * 512) = ov;
;             }
; #pragma unroll
;             for (int dkt = 0; dkt < 8; ++dkt) {
; #pragma unroll
;                 for (int k2 = 0; k2 < 2; ++k2)
;                     S[dkt] = mfma16(*(const LAS bf16x8*)(Tb + (dkt * 2 + k2) * 1024), vf[k2], S[dkt]);
;                 const f32x4 dd = *(const LAS f32x4*)(Db + dkt * 64 + fq * 16);
;                 S[dkt][0] *= dd[0]; S[dkt][1] *= dd[1]; S[dkt][2] *= dd[2]; S[dkt][3] *= dd[3];
;             }
.LBB0_576:
	s_cmp_gt_u32 s30, 3
	s_cselect_b32 s0, 0x43, 3
	s_add_i32 s0, s0, s7
	s_add_i32 s17, s0, 2
	s_and_b64 s[0:1], s[42:43], exec
	s_cselect_b32 s0, s30, s17
	s_lshl_b32 s1, s0, 6
	ds_read_b128 v[56:59], v1 offset:4672
	s_cmp_lt_i32 s0, 4
	s_movk_i32 s17, 0xff00
	s_cselect_b32 s0, 8, 12
	s_cselect_b32 s17, 0x8000, s17
	s_lshl_b32 s0, s6, s0
	s_add_i32 s1, s17, s1
	s_add_i32 s1, s1, s0
	s_waitcnt lgkmcnt(0)
	v_mfma_f32_16x16x32_bf16 v[48:51], v[36:39], v[56:59], v[48:51]
	ds_read_b128 v[56:59], v1 offset:4928
	s_ashr_i32 s17, s1, 31
	s_add_u32 s0, s85, s1
	s_addc_u32 s1, 0, s17
	s_lshl_b64 s[0:1], s[0:1], 10
	v_cvt_pk_bf16_f32 v2, v52, v53
	v_lshl_add_u64 v[52:53], v[68:69], 0, s[0:1]
	s_movk_i32 s0, 0x4000
	s_waitcnt lgkmcnt(0)
	v_mfma_f32_16x16x32_bf16 v[44:47], v[36:39], v[56:59], v[44:47]
	v_cvt_pk_bf16_f32 v3, v54, v55
	v_add_co_u32_e32 v54, vcc, s0, v52
	global_store_dwordx2 v[52:53], v[2:3], off
	v_cvt_pk_bf16_f32 v2, v60, v61
	v_cvt_pk_bf16_f32 v3, v62, v63
	v_addc_co_u32_e32 v55, vcc, 0, v53, vcc
	s_mov_b32 s0, 0x8000
	global_store_dwordx2 v[54:55], v[2:3], off
	v_cvt_pk_bf16_f32 v2, v48, v49
	v_add_co_u32_e32 v48, vcc, s0, v52
	v_cvt_pk_bf16_f32 v3, v50, v51
	s_nop 0
	v_addc_co_u32_e32 v49, vcc, 0, v53, vcc
	s_mov_b32 s0, 0xc000
	global_store_dwordx2 v[48:49], v[2:3], off
	v_cvt_pk_bf16_f32 v2, v44, v45
	v_add_co_u32_e32 v44, vcc, s0, v52
	v_cvt_pk_bf16_f32 v3, v46, v47
	s_nop 0
	v_addc_co_u32_e32 v45, vcc, 0, v53, vcc
	v_lshl_add_u32 v48, s29, 14, v79
	global_store_dwordx2 v[44:45], v[2:3], off
	v_add_u32_e32 v1, s16, v82
	ds_read_b128 v[192:195], v48
	ds_read_b128 v[196:199], v48 offset:1024
	ds_read_b128 v[200:203], v48 offset:2048
	ds_read_b128 v[204:207], v48 offset:3072
	ds_read_b128 v[208:211], v1 offset:8320
	ds_read_b128 v[212:215], v48 offset:4096
	ds_read_b128 v[216:219], v48 offset:5120
	ds_read_b128 v[220:223], v1 offset:8384
	ds_read_b128 v[224:227], v48 offset:6144
	ds_read_b128 v[228:231], v48 offset:7168
	ds_read_b128 v[232:235], v1 offset:8448
	ds_read_b128 v[236:239], v48 offset:8192
	s_waitcnt lgkmcnt(11)
	v_mfma_f32_16x16x32_bf16 v[8:11], v[192:195], v[40:43], v[8:11]
	ds_read_b128 v[192:195], v48 offset:9216
	s_waitcnt lgkmcnt(11)
	v_mfma_f32_16x16x32_bf16 v[8:11], v[196:199], v[36:39], v[8:11]
	ds_read_b128 v[196:199], v1 offset:8512
	s_waitcnt lgkmcnt(11)
	v_mfma_f32_16x16x32_bf16 v[2:5], v[200:203], v[40:43], v[4:7]
	ds_read_b128 v[200:203], v48 offset:10240
	s_waitcnt lgkmcnt(11)
	v_mfma_f32_16x16x32_bf16 v[2:5], v[204:207], v[36:39], v[2:5]
	ds_read_b128 v[204:207], v48 offset:11264
	s_waitcnt lgkmcnt(11)
	s_nop 2
	v_pk_mul_f32 v[10:11], v[10:11], v[210:211]
	v_pk_mul_f32 v[8:9], v[8:9], v[208:209]
	ds_read_b128 v[208:211], v1 offset:8576
	s_waitcnt lgkmcnt(11)
	v_mfma_f32_16x16x32_bf16 v[12:15], v[212:215], v[40:43], v[12:15]
	ds_read_b128 v[212:215], v48 offset:12288
	s_waitcnt lgkmcnt(11)
	v_mfma_f32_16x16x32_bf16 v[12:15], v[216:219], v[36:39], v[12:15]
	ds_read_b128 v[216:219], v48 offset:13312
	s_waitcnt lgkmcnt(11)
	s_nop 2
	v_pk_mul_f32 v[6:7], v[4:5], v[222:223]
	v_pk_mul_f32 v[4:5], v[2:3], v[220:221]
	ds_read_b128 v[220:223], v1 offset:8640
	s_waitcnt lgkmcnt(11)
	v_mfma_f32_16x16x32_bf16 v[16:19], v[224:227], v[40:43], v[16:19]
	ds_read_b128 v[224:227], v48 offset:14336
	s_waitcnt lgkmcnt(11)
	v_mfma_f32_16x16x32_bf16 v[16:19], v[228:231], v[36:39], v[16:19]
	ds_read_b128 v[228:231], v48 offset:15360
	s_waitcnt lgkmcnt(11)
	s_nop 2
	v_pk_mul_f32 v[14:15], v[14:15], v[234:235]
	v_pk_mul_f32 v[12:13], v[12:13], v[232:233]
	ds_read_b128 v[232:235], v1 offset:8704
	s_waitcnt lgkmcnt(11)
	v_mfma_f32_16x16x32_bf16 v[20:23], v[236:239], v[40:43], v[20:23]
	ds_read_b128 v[236:239], v1 offset:8768
	s_waitcnt lgkmcnt(11)
	v_mfma_f32_16x16x32_bf16 v[20:23], v[192:195], v[36:39], v[20:23]
	s_waitcnt lgkmcnt(10)
	s_nop 2
	v_pk_mul_f32 v[18:19], v[18:19], v[198:199]
	v_pk_mul_f32 v[16:17], v[16:17], v[196:197]
	s_waitcnt lgkmcnt(9)
	v_mfma_f32_16x16x32_bf16 v[24:27], v[200:203], v[40:43], v[24:27]
	s_waitcnt lgkmcnt(8)
	v_mfma_f32_16x16x32_bf16 v[24:27], v[204:207], v[36:39], v[24:27]
	s_waitcnt lgkmcnt(7)
	s_nop 2
	v_pk_mul_f32 v[22:23], v[22:23], v[210:211]
	v_pk_mul_f32 v[20:21], v[20:21], v[208:209]
	s_waitcnt lgkmcnt(6)
	v_mfma_f32_16x16x32_bf16 v[28:31], v[212:215], v[40:43], v[28:31]
	s_waitcnt lgkmcnt(5)
	v_mfma_f32_16x16x32_bf16 v[28:31], v[216:219], v[36:39], v[28:31]
	s_waitcnt lgkmcnt(4)
	s_nop 2
	v_pk_mul_f32 v[26:27], v[26:27], v[222:223]
	v_pk_mul_f32 v[24:25], v[24:25], v[220:221]
	s_waitcnt lgkmcnt(3)
	v_mfma_f32_16x16x32_bf16 v[32:35], v[224:227], v[40:43], v[32:35]
	s_waitcnt lgkmcnt(2)
	v_mfma_f32_16x16x32_bf16 v[32:35], v[228:231], v[36:39], v[32:35]
	s_waitcnt lgkmcnt(1)
	s_nop 2
	v_pk_mul_f32 v[30:31], v[30:31], v[234:235]
	v_pk_mul_f32 v[28:29], v[28:29], v[232:233]
	s_waitcnt lgkmcnt(0)
	s_nop 7
	v_pk_mul_f32 v[34:35], v[34:35], v[238:239]
	v_pk_mul_f32 v[32:33], v[32:33], v[236:237]

;     ...
;         const bool has_next = S.next(ui + 1, nxt);
;         const char* nA = has_next ? (const char*)gA + (size_t)nxt.pm * tstep : cA; const char* nB = has_next ? (const char*)gBt + (size_t)nxt.pn * tstep : cB;
;     ...
; #pragma unroll
;         for (int a = 0; a < 2; ++a)
; #pragma unroll
;             for (int b = 0; b < 2; ++b)
; #pragma unroll
;                 for (int m = 0; m < 4; ++m)
; #pragma unroll
;                     for (int n = 0; n < 2; ++n) acc[a][b][m][n] = (f32x4){0.f, 0.f, 0.f, 0.f};
;         cur = nxt; cA = nA; cB = nB; ++ui;
.LBB0_758:
	s_ashr_i32 s65, s64, 31
	v_cmp_lt_i64_e32 vcc, s[14:15], v[140:141]
	s_lshl_b64 s[14:15], s[64:65], 19
	s_add_u32 s66, s24, s14
	s_addc_u32 s67, s25, s15
	s_and_b64 s[14:15], vcc, exec
	s_cselect_b32 s18, s67, s11
	s_cselect_b32 s19, s66, s10
	s_ashr_i32 s63, s62, 31
	s_lshl_b64 s[14:15], s[62:63], 19
	s_add_u32 s68, s60, s14
	s_addc_u32 s69, s61, s15
	s_and_b64 s[14:15], vcc, exec
	s_cselect_b32 s22, s69, s13
	s_cselect_b32 s23, s68, s12
	s_add_u32 s10, s10, 0x40080
	s_addc_u32 s11, s11, 0
	s_add_u32 s28, s12, 0x100
	v_mov_b32_e32 v2, 0
	s_addc_u32 s29, s13, 0
	s_mov_b32 s30, -2
	v_mov_b32_e32 v3, v2
	v_mov_b32_e32 v4, v2
	v_mov_b32_e32 v5, v2
	v_mov_b32_e32 v6, v2
	v_mov_b32_e32 v7, v2
	v_mov_b32_e32 v8, v2
	v_mov_b32_e32 v9, v2
	v_mov_b32_e32 v18, v2
	v_mov_b32_e32 v19, v2
	v_mov_b32_e32 v20, v2
	v_mov_b32_e32 v21, v2
	v_mov_b32_e32 v22, v2
	v_mov_b32_e32 v23, v2
	v_mov_b32_e32 v24, v2
	v_mov_b32_e32 v25, v2
	v_mov_b32_e32 v34, v2
	v_mov_b32_e32 v35, v2
	v_mov_b32_e32 v36, v2
	v_mov_b32_e32 v37, v2
	v_mov_b32_e32 v38, v2
	v_mov_b32_e32 v39, v2
	v_mov_b32_e32 v40, v2
	v_mov_b32_e32 v41, v2
	v_mov_b32_e32 v50, v2
	v_mov_b32_e32 v51, v2
	v_mov_b32_e32 v52, v2
	v_mov_b32_e32 v53, v2
	v_mov_b32_e32 v54, v2
	v_mov_b32_e32 v55, v2
	v_mov_b32_e32 v56, v2
	v_mov_b32_e32 v57, v2
	v_mov_b32_e32 v10, v2
	v_mov_b32_e32 v11, v2
	v_mov_b32_e32 v12, v2
	v_mov_b32_e32 v13, v2
	v_mov_b32_e32 v14, v2
	v_mov_b32_e32 v15, v2
	v_mov_b32_e32 v16, v2
	v_mov_b32_e32 v17, v2
	v_mov_b32_e32 v26, v2
	v_mov_b32_e32 v27, v2
	v_mov_b32_e32 v28, v2
	v_mov_b32_e32 v29, v2
	v_mov_b32_e32 v30, v2
	v_mov_b32_e32 v31, v2
	v_mov_b32_e32 v32, v2
	v_mov_b32_e32 v33, v2
	v_mov_b32_e32 v42, v2
	v_mov_b32_e32 v43, v2
	v_mov_b32_e32 v44, v2
	v_mov_b32_e32 v45, v2
	v_mov_b32_e32 v46, v2
	v_mov_b32_e32 v47, v2
	v_mov_b32_e32 v48, v2
	v_mov_b32_e32 v49, v2
	v_mov_b32_e32 v58, v2
	v_mov_b32_e32 v59, v2
	v_mov_b32_e32 v60, v2
	v_mov_b32_e32 v61, v2
	v_mov_b32_e32 v62, v2
	v_mov_b32_e32 v63, v2
	v_mov_b32_e32 v64, v2
	v_mov_b32_e32 v65, v2
	v_mov_b32_e32 v66, v2
	v_mov_b32_e32 v67, v2
	v_mov_b32_e32 v68, v2
	v_mov_b32_e32 v69, v2
	v_mov_b32_e32 v70, v2
	v_mov_b32_e32 v71, v2
	v_mov_b32_e32 v72, v2
	v_mov_b32_e32 v73, v2
	v_mov_b32_e32 v82, v2
	v_mov_b32_e32 v83, v2
	v_mov_b32_e32 v84, v2
	v_mov_b32_e32 v85, v2
	v_mov_b32_e32 v86, v2
	v_mov_b32_e32 v87, v2
	v_mov_b32_e32 v88, v2
	v_mov_b32_e32 v89, v2
	v_mov_b32_e32 v98, v2
	v_mov_b32_e32 v99, v2
	v_mov_b32_e32 v100, v2
	v_mov_b32_e32 v101, v2
	v_mov_b32_e32 v102, v2
	v_mov_b32_e32 v103, v2
	v_mov_b32_e32 v104, v2
	v_mov_b32_e32 v105, v2
	v_mov_b32_e32 v114, v2
	v_mov_b32_e32 v115, v2
	v_mov_b32_e32 v116, v2
	v_mov_b32_e32 v117, v2
	v_mov_b32_e32 v118, v2
	v_mov_b32_e32 v119, v2
	v_mov_b32_e32 v120, v2
	v_mov_b32_e32 v121, v2
	v_mov_b32_e32 v74, v2
	v_mov_b32_e32 v75, v2
	v_mov_b32_e32 v76, v2
	v_mov_b32_e32 v77, v2
	v_mov_b32_e32 v78, v2
	v_mov_b32_e32 v79, v2
	v_mov_b32_e32 v80, v2
	v_mov_b32_e32 v81, v2
	v_mov_b32_e32 v90, v2
	v_mov_b32_e32 v91, v2
	v_mov_b32_e32 v92, v2
	v_mov_b32_e32 v93, v2
	v_mov_b32_e32 v94, v2
	v_mov_b32_e32 v95, v2
	v_mov_b32_e32 v96, v2
	v_mov_b32_e32 v97, v2
	v_mov_b32_e32 v106, v2
	v_mov_b32_e32 v107, v2
	v_mov_b32_e32 v108, v2
	v_mov_b32_e32 v109, v2
	v_mov_b32_e32 v110, v2
	v_mov_b32_e32 v111, v2
	v_mov_b32_e32 v112, v2
	v_mov_b32_e32 v113, v2
	v_mov_b32_e32 v122, v2
	v_mov_b32_e32 v123, v2
	v_mov_b32_e32 v124, v2
	v_mov_b32_e32 v125, v2
	v_mov_b32_e32 v126, v2
	v_mov_b32_e32 v127, v2
	v_mov_b32_e32 v128, v2
	v_mov_b32_e32 v129, v2

;     ...
;         const bool has_next = S.next(ui + 1, nxt);
;         const char* nA = has_next ? (const char*)gA + (size_t)nxt.pm * tstep : cA; const char* nB = has_next ? (const char*)gBt + (size_t)nxt.pn * tstep : cB;
;     ...
; #pragma unroll
;         for (int a = 0; a < 2; ++a)
; #pragma unroll
;             for (int b = 0; b < 2; ++b)
; #pragma unroll
;                 for (int m = 0; m < 4; ++m)
; #pragma unroll
;                     for (int n = 0; n < 2; ++n) acc[a][b][m][n] = (f32x4){0.f, 0.f, 0.f, 0.f};
;         cur = nxt; cA = nA; cB = nB; ++ui;
.LBB0_903:
	s_ashr_i32 s15, s14, 31
	v_cmp_lt_i64_e32 vcc, s[40:41], v[144:145]
	s_lshl_b64 s[40:41], s[14:15], 19
	s_add_u32 s40, s24, s40
	s_addc_u32 s41, s25, s41
	s_and_b64 s[46:47], vcc, exec
	s_cselect_b32 s15, s41, s55
	s_cselect_b32 s31, s40, s54
	s_ashr_i32 s13, s12, 31
	s_lshl_b64 s[46:47], s[12:13], 19
	s_add_u32 s46, s5, s46
	s_addc_u32 s47, s7, s47
	s_and_b64 s[58:59], vcc, exec
	s_cselect_b32 s13, s47, s57
	s_cselect_b32 s36, s46, s56
	s_add_u32 s54, s54, 0x40080
	s_addc_u32 s55, s55, 0
	s_add_u32 s60, s56, 0x100
	v_mov_b32_e32 v2, 0
	s_addc_u32 s61, s57, 0
	s_mov_b32 s62, -2
	v_mov_b32_e32 v3, v2
	v_mov_b32_e32 v4, v2
	v_mov_b32_e32 v5, v2
	v_mov_b32_e32 v6, v2
	v_mov_b32_e32 v7, v2
	v_mov_b32_e32 v8, v2
	v_mov_b32_e32 v9, v2
	v_mov_b32_e32 v10, v2
	v_mov_b32_e32 v11, v2
	v_mov_b32_e32 v12, v2
	v_mov_b32_e32 v13, v2
	v_mov_b32_e32 v14, v2
	v_mov_b32_e32 v15, v2
	v_mov_b32_e32 v16, v2
	v_mov_b32_e32 v17, v2
	v_mov_b32_e32 v26, v2
	v_mov_b32_e32 v27, v2
	v_mov_b32_e32 v28, v2
	v_mov_b32_e32 v29, v2
	v_mov_b32_e32 v30, v2
	v_mov_b32_e32 v31, v2
	v_mov_b32_e32 v32, v2
	v_mov_b32_e32 v33, v2
	v_mov_b32_e32 v42, v2
	v_mov_b32_e32 v43, v2
	v_mov_b32_e32 v44, v2
	v_mov_b32_e32 v45, v2
	v_mov_b32_e32 v46, v2
	v_mov_b32_e32 v47, v2
	v_mov_b32_e32 v48, v2
	v_mov_b32_e32 v49, v2
	v_mov_b32_e32 v18, v2
	v_mov_b32_e32 v19, v2
	v_mov_b32_e32 v20, v2
	v_mov_b32_e32 v21, v2
	v_mov_b32_e32 v22, v2
	v_mov_b32_e32 v23, v2
	v_mov_b32_e32 v24, v2
	v_mov_b32_e32 v25, v2
	v_mov_b32_e32 v34, v2
	v_mov_b32_e32 v35, v2
	v_mov_b32_e32 v36, v2
	v_mov_b32_e32 v37, v2
	v_mov_b32_e32 v38, v2
	v_mov_b32_e32 v39, v2
	v_mov_b32_e32 v40, v2
	v_mov_b32_e32 v41, v2
	v_mov_b32_e32 v50, v2
	v_mov_b32_e32 v51, v2
	v_mov_b32_e32 v52, v2
	v_mov_b32_e32 v53, v2
	v_mov_b32_e32 v54, v2
	v_mov_b32_e32 v55, v2
	v_mov_b32_e32 v56, v2
	v_mov_b32_e32 v57, v2
	v_mov_b32_e32 v58, v2
	v_mov_b32_e32 v59, v2
	v_mov_b32_e32 v60, v2
	v_mov_b32_e32 v61, v2
	v_mov_b32_e32 v62, v2
	v_mov_b32_e32 v63, v2
	v_mov_b32_e32 v64, v2
	v_mov_b32_e32 v65, v2
	v_mov_b32_e32 v66, v2
	v_mov_b32_e32 v67, v2
	v_mov_b32_e32 v68, v2
	v_mov_b32_e32 v69, v2
	v_mov_b32_e32 v70, v2
	v_mov_b32_e32 v71, v2
	v_mov_b32_e32 v72, v2
	v_mov_b32_e32 v73, v2
	v_mov_b32_e32 v74, v2
	v_mov_b32_e32 v75, v2
	v_mov_b32_e32 v76, v2
	v_mov_b32_e32 v77, v2
	v_mov_b32_e32 v78, v2
	v_mov_b32_e32 v79, v2
	v_mov_b32_e32 v80, v2
	v_mov_b32_e32 v81, v2
	v_mov_b32_e32 v90, v2
	v_mov_b32_e32 v91, v2
	v_mov_b32_e32 v92, v2
	v_mov_b32_e32 v93, v2
	v_mov_b32_e32 v94, v2
	v_mov_b32_e32 v95, v2
	v_mov_b32_e32 v96, v2
	v_mov_b32_e32 v97, v2
	v_mov_b32_e32 v106, v2
	v_mov_b32_e32 v107, v2
	v_mov_b32_e32 v108, v2
	v_mov_b32_e32 v109, v2
	v_mov_b32_e32 v110, v2
	v_mov_b32_e32 v111, v2
	v_mov_b32_e32 v112, v2
	v_mov_b32_e32 v113, v2
	v_mov_b32_e32 v82, v2
	v_mov_b32_e32 v83, v2
	v_mov_b32_e32 v84, v2
	v_mov_b32_e32 v85, v2
	v_mov_b32_e32 v86, v2
	v_mov_b32_e32 v87, v2
	v_mov_b32_e32 v88, v2
	v_mov_b32_e32 v89, v2
	v_mov_b32_e32 v98, v2
	v_mov_b32_e32 v99, v2
	v_mov_b32_e32 v100, v2
	v_mov_b32_e32 v101, v2
	v_mov_b32_e32 v102, v2
	v_mov_b32_e32 v103, v2
	v_mov_b32_e32 v104, v2
	v_mov_b32_e32 v105, v2
	v_mov_b32_e32 v114, v2
	v_mov_b32_e32 v115, v2
	v_mov_b32_e32 v116, v2
	v_mov_b32_e32 v117, v2
	v_mov_b32_e32 v118, v2
	v_mov_b32_e32 v119, v2
	v_mov_b32_e32 v120, v2
	v_mov_b32_e32 v121, v2
	v_mov_b32_e32 v122, v2
	v_mov_b32_e32 v123, v2
	v_mov_b32_e32 v124, v2
	v_mov_b32_e32 v125, v2
	v_mov_b32_e32 v126, v2
	v_mov_b32_e32 v127, v2
	v_mov_b32_e32 v128, v2
	v_mov_b32_e32 v129, v2

; __device__ __forceinline__ void lru_scan_phase(const Params& p, int slot, const bf16_t* upre, bf16_t* hf, bf16_t* hb, char* smem, const bf16_t* gateA, bf16_t* gate_out) {
;     ...
;     const float gbr = gb[(d * 2 + 0) * DRNN + ch], gbi = gb[(d * 2 + 1) * DRNN + ch];
;     const float sp8 = 8.0f * log1pf(expf(-lam[d * DRNN + ch]));
;     float hcar = 0.f;
;     u32x4 pre[2][4];
;     auto chunk_info = [&](int i, int& seqbase, int& L, int& t0) {
;         const int c = d ? (i < 4 ? 3 - i : 71 - i) : i;
;         if (c < 4) { seqbase = T_LAT + b * 256; L = 256; t0 = c * 64; }
;         else { seqbase = b * 4096; L = 4096; t0 = (c - 4) * 64; }
;     };
;     auto load_pre = [&](int i) {
;         int seqbase, L, t0; chunk_info(i, seqbase, L, t0);
; #pragma unroll
;         for (int k = 0; k < 2; ++k) {
;             const int tk = (tid + k * NTHREADS) >> 4;
; #pragma unroll
;             for (int j = 0; j < 4; ++j) {
;                 const int tt = t0 + tk + j - 2;
;                 u32x4 v = {0u, 0u, 0u, 0u};
;                 if (tt >= 0 && tt < L) v = *reinterpret_cast<const u32x4*>(upre + (size_t)(seqbase + tt) * DRNN + chn);
;                 pre[k][j] = v;
;             }
;         }
;     };
;     load_pre(0);
.LBB0_945:
	s_or_b64 exec, exec, s[10:11]
	s_waitcnt vmcnt(0)
	v_mul_f32_e32 v1, 0xbfb8aa3b, v109
	v_rndne_f32_e32 v2, v1
	s_mov_b32 s0, 0xbfb8aa3b
	v_sub_f32_e32 v3, v1, v2
	v_fma_f32 v1, v109, s0, -v1
	v_fmac_f32_e32 v1, 0xb2a5705f, v109
	v_add_f32_e32 v1, v3, v1
	v_cvt_i32_f32_e32 v2, v2
	v_exp_f32_e32 v1, v1
	s_mov_b32 s0, 0x42ce8ed0
	v_cmp_nlt_f32_e32 vcc, s0, v109
	s_mov_b32 s0, 0xc2b17218
	v_ldexp_f32 v1, v1, v2
	v_cndmask_b32_e32 v1, 0, v1, vcc
	v_cmp_ngt_f32_e32 vcc, s0, v109
	s_mov_b32 s0, 0x3f2aaaab
	s_and_b64 s[4:5], s[8:9], exec
	v_cndmask_b32_e32 v1, v190, v1, vcc
	v_add_f32_e32 v109, 1.0, v1
	v_add_f32_e32 v2, -1.0, v109
	v_sub_f32_e32 v3, v2, v109
	v_add_f32_e32 v3, 1.0, v3
	v_sub_f32_e32 v2, v1, v2
	v_add_f32_e32 v111, v2, v3
	v_frexp_mant_f32_e32 v118, v109
	v_cvt_f64_f32_e32 v[2:3], v109
	v_frexp_exp_i32_f64_e32 v2, v[2:3]
	v_cmp_gt_f32_e32 vcc, s0, v118
	s_mov_b32 s0, 0x3f317218
	s_cselect_b32 s1, s52, s56
	v_subbrev_co_u32_e32 v2, vcc, 0, v2, vcc
	v_sub_u32_e32 v3, 0, v2
	v_ldexp_f32 v109, v109, v3
	v_ldexp_f32 v3, v111, v3
	v_add_f32_e32 v111, -1.0, v109
	v_add_f32_e32 v120, 1.0, v109
	v_add_f32_e32 v118, 1.0, v111
	v_add_f32_e32 v121, -1.0, v120
	v_sub_f32_e32 v118, v109, v118
	v_sub_f32_e32 v109, v109, v121
	v_add_f32_e32 v118, v3, v118
	v_add_f32_e32 v3, v3, v109
	v_add_f32_e32 v109, v120, v3
	v_rcp_f32_e32 v121, v109
	v_add_f32_e32 v119, v111, v118
	v_sub_f32_e32 v111, v111, v119
	v_add_f32_e32 v111, v118, v111
	v_sub_f32_e32 v118, v120, v109
	v_add_f32_e32 v3, v3, v118
	v_mul_f32_e32 v118, v119, v121
	v_mul_f32_e32 v120, v109, v118
	v_fma_f32 v122, v118, v109, -v120
	v_fmac_f32_e32 v122, v118, v3
	v_add_f32_e32 v123, v120, v122
	v_sub_f32_e32 v124, v119, v123
	v_sub_f32_e32 v119, v119, v124
	v_sub_f32_e32 v120, v123, v120
	v_sub_f32_e32 v119, v119, v123
	v_add_f32_e32 v111, v111, v119
	v_sub_f32_e32 v119, v120, v122
	v_add_f32_e32 v111, v119, v111
	v_add_f32_e32 v119, v124, v111
	v_mul_f32_e32 v120, v121, v119
	v_mul_f32_e32 v122, v109, v120
	v_fma_f32 v109, v120, v109, -v122
	v_fmac_f32_e32 v109, v120, v3
	v_sub_f32_e32 v3, v124, v119
	v_add_f32_e32 v3, v111, v3
	v_add_f32_e32 v111, v122, v109
	v_sub_f32_e32 v123, v119, v111
	v_sub_f32_e32 v119, v119, v123
	v_sub_f32_e32 v122, v111, v122
	v_sub_f32_e32 v111, v119, v111
	v_add_f32_e32 v3, v3, v111
	v_sub_f32_e32 v109, v122, v109
	v_cvt_f32_i32_e32 v2, v2
	v_add_f32_e32 v3, v109, v3
	v_add_f32_e32 v109, v118, v120
	v_add_f32_e32 v3, v123, v3
	v_sub_f32_e32 v111, v109, v118
	v_mul_f32_e32 v3, v121, v3
	v_sub_f32_e32 v111, v120, v111
	v_add_f32_e32 v3, v111, v3
	v_mul_f32_e32 v120, 0x3f317218, v2
	v_add_f32_e32 v111, v109, v3
	v_fma_f32 v121, v2, s0, -v120
	v_mul_f32_e32 v118, v111, v111
	v_fmac_f32_e32 v121, 0xb102e308, v2
	v_sub_f32_e32 v2, v111, v109
	v_fmamk_f32 v119, v118, 0x3e9b6dac, v179
	v_sub_f32_e32 v2, v3, v2
	v_add_f32_e32 v3, v120, v121
	v_fmaak_f32 v119, v118, v119, 0x3f2aaada
	v_sub_f32_e32 v109, v3, v120
	v_ldexp_f32 v120, v111, 1
	v_mul_f32_e32 v111, v111, v118
	v_mul_f32_e32 v111, v111, v119
	v_add_f32_e32 v118, v120, v111
	v_sub_f32_e32 v119, v118, v120
	v_ldexp_f32 v2, v2, 1
	v_sub_f32_e32 v111, v111, v119
	v_add_f32_e32 v2, v2, v111
	v_add_f32_e32 v111, v118, v2
	v_sub_f32_e32 v118, v111, v118
	v_sub_f32_e32 v2, v2, v118
	v_add_f32_e32 v118, v3, v111
	v_sub_f32_e32 v119, v118, v3
	v_sub_f32_e32 v120, v118, v119
	v_sub_f32_e32 v109, v121, v109
	v_sub_f32_e32 v3, v3, v120
	v_sub_f32_e32 v111, v111, v119
	v_add_f32_e32 v3, v111, v3
	v_add_f32_e32 v111, v109, v2
	v_sub_f32_e32 v119, v111, v109
	v_sub_f32_e32 v120, v111, v119
	v_sub_f32_e32 v109, v109, v120
	v_sub_f32_e32 v2, v2, v119
	v_add_f32_e32 v3, v111, v3
	v_add_f32_e32 v2, v2, v109
	v_add_f32_e32 v109, v118, v3
	v_sub_f32_e32 v111, v109, v118
	v_sub_f32_e32 v3, v3, v111
	v_add_f32_e32 v2, v2, v3
	s_mov_b32 s0, 0x7f800000
	v_add_f32_e32 v2, v109, v2
	v_cmp_neq_f32_e32 vcc, s0, v1
	s_mov_b32 s0, 0x33800000
	v_ashrrev_i32_e32 v109, 31, v108
	v_cndmask_b32_e32 v2, v190, v2, vcc
	v_cmp_lt_f32_e64 vcc, |v1|, s0
	s_cselect_b32 s0, s53, s57
	v_mov_b32_e32 v3, s0
	v_cndmask_b32_e32 v1, v2, v1, vcc
	v_mov_b32_e32 v2, s1
	v_lshl_add_u64 v[118:119], v[108:109], 1, v[2:3]
	v_ashrrev_i32_e32 v2, 3, v114
	v_lshlrev_b32_e32 v108, 2, v193
	v_mul_f32_e32 v197, 0xc1000000, v1
	v_lshl_add_u32 v1, v193, 12, 0
	v_bitop3_b32 v125, v108, v2, 3 bitop3:0x36
	v_bitop3_b32 v126, v108, v2, 2 bitop3:0x36
	v_bitop3_b32 v127, v108, v2, 1 bitop3:0x36
	v_lshlrev_b32_e32 v128, 6, v193
	v_lshlrev_b32_e32 v129, 4, v2
	v_xor_b32_e32 v2, v2, v108
	v_cmp_lt_u32_e32 vcc, 1, v193
	v_readlane_b32 s0, v254, 27
	v_lshl_add_u32 v125, v125, 4, v1
	v_lshl_add_u32 v126, v126, 4, v1
	v_lshl_add_u32 v127, v127, 4, v1
	v_xad_u32 v128, v129, v128, v1
	v_lshl_add_u32 v1, v2, 4, v1
	v_cndmask_b32_e64 v2, 0, 1, vcc
	v_cmp_ge_u32_e32 vcc, s0, v193
	v_readlane_b32 s0, v252, 32
	v_mov_b32_e32 v111, v0
	v_cndmask_b32_e64 v108, 0, 1, vcc
	v_cndmask_b32_e64 v2, v108, v2, s[8:9]
	v_and_b32_e32 v2, 1, v2
	v_cmp_lt_u32_e32 vcc, s0, v193
	v_lshl_add_u64 v[120:121], s[48:49], 0, v[110:111]
	v_lshlrev_b32_e32 v3, 1, v112
	v_ashrrev_i32_e32 v110, 6, v112
	v_ashrrev_i32_e32 v114, 6, v115
	v_lshlrev_b32_e32 v123, 10, v112
	v_lshlrev_b32_e32 v112, 8, v112
	v_cmp_eq_u32_e64 s[44:45], 1, v2
	v_cndmask_b32_e64 v2, 0, 1, vcc
	v_cmp_gt_u32_e32 vcc, s0, v193
	v_and_b32_e32 v110, 0xffffffc, v110
	v_and_b32_e32 v114, 0xffffffc, v114
	v_bfe_u32 v115, v115, 4, 2
	v_and_b32_e32 v123, 0x3000, v123
	v_and_b32_e32 v112, 0x300, v112
	v_cndmask_b32_e64 v108, 0, 1, vcc
	v_and_or_b32 v122, v180, 64, v113
	v_bitop3_b32 v110, v110, v113, v193 bitop3:0x36
	v_bitop3_b32 v114, v114, v113, v115 bitop3:0x36
	v_xor_b32_e32 v115, v193, v113
	v_add3_u32 v112, 0, v123, v112
	v_bitop3_b32 v123, v193, v113, 4 bitop3:0x36
	v_bitop3_b32 v124, v193, v113, 8 bitop3:0x36
	v_bitop3_b32 v113, v193, v113, 12 bitop3:0x36
	v_cndmask_b32_e64 v2, v108, v2, s[8:9]
	v_and_b32_e32 v3, 14, v3
	v_lshl_add_u32 v109, v195, 8, 0
	v_lshlrev_b32_e32 v110, 4, v110
	v_lshl_add_u32 v111, v196, 8, 0
	v_lshlrev_b32_e32 v114, 4, v114
	v_lshlrev_b32_e32 v115, 4, v115
	v_lshlrev_b32_e32 v123, 4, v123
	v_lshlrev_b32_e32 v124, 4, v124
	v_lshlrev_b32_e32 v113, 4, v113
	v_lshlrev_b32_e32 v198, 2, v122
	v_and_b32_e32 v2, 1, v2
	s_mov_b32 s12, 0
	s_mov_b32 s5, -1
	v_or_b32_e32 v199, 64, v198
	v_or_b32_e32 v200, 0x80, v198
	v_or_b32_e32 v201, 0xc0, v198
	v_cmp_eq_u32_e64 s[46:47], 1, v2
	v_add_u32_e32 v202, v109, v110
	v_add_u32_e32 v203, v111, v114
	v_add_u32_e32 v204, v112, v115
	v_add_u32_e32 v205, v112, v123
	v_add_u32_e32 v207, v112, v124
	v_add_u32_e32 v208, v112, v113
	v_add_u32_e32 v209, v128, v3
	v_add_u32_e32 v210, v1, v3
	v_add_u32_e32 v211, v125, v3
	v_add_u32_e32 v212, v126, v3
	v_add_u32_e32 v213, v127, v3
	s_waitcnt vmcnt(0)
	s_branch .LBB0_947

; __device__ __forceinline__ float bflo(unsigned w) { return __uint_as_float(w << 16); }
; __device__ __forceinline__ float bfhi(unsigned w) { return __uint_as_float(w & 0xffff0000u); }
; __device__ __forceinline__ int ukey(int tk) { return ((tk >> 4) << 2) | (tk & 3); }
; __device__ __forceinline__ void lru_scan_phase(const Params& p, int slot, const bf16_t* upre, bf16_t* hf, bf16_t* hb, char* smem, const bf16_t* gateA, bf16_t* gate_out) {
;     ...
;         __syncthreads();
; #pragma unroll
;         for (int k = 0; k < 2; ++k) {
;             const int tk = (tid + k * NTHREADS) >> 4;
;             float a[8];
; #pragma unroll
;             for (int q = 0; q < 8; ++q) a[q] = cbv[q];
; #pragma unroll
;             for (int j = 0; j < 4; ++j) {
;                 const u32x4 xv = pre[k][j];
;                 a[0] += cw[j][0] * bflo(xv[0]); a[1] += cw[j][1] * bfhi(xv[0]); a[2] += cw[j][2] * bflo(xv[1]); a[3] += cw[j][3] * bfhi(xv[1]);
;                 a[4] += cw[j][4] * bflo(xv[2]); a[5] += cw[j][5] * bfhi(xv[2]); a[6] += cw[j][6] * bflo(xv[3]); a[7] += cw[j][7] * bfhi(xv[3]);
;             }
;             u32x4 o = {pack2(a[0], a[1]), pack2(a[2], a[3]), pack2(a[4], a[5]), pack2(a[6], a[7])};
;             *reinterpret_cast<u32x4*>(smem + tk * 256 + ((ch8 ^ ukey(tk)) * 16)) = o;
;         }
;         __syncthreads();
;         if (i + 1 < 68) load_pre(i + 1);
.LBB0_947:
	s_waitcnt vmcnt(16)
	v_lshlrev_b32_e32 v2, 16, v80
	v_and_b32_e32 v3, 0xffff0000, v80
	v_pk_fma_f32 v[2:3], v[16:17], v[2:3], v[8:9]
	v_lshlrev_b32_e32 v108, 16, v76
	v_and_b32_e32 v109, 0xffff0000, v76
	v_pk_fma_f32 v[2:3], v[20:21], v[108:109], v[2:3]
	v_lshlrev_b32_e32 v108, 16, v84
	v_and_b32_e32 v109, 0xffff0000, v84
	v_pk_fma_f32 v[2:3], v[28:29], v[108:109], v[2:3]
	v_lshlrev_b32_e32 v108, 16, v88
	v_and_b32_e32 v109, 0xffff0000, v88
	v_pk_fma_f32 v[2:3], v[36:37], v[108:109], v[2:3]
	v_lshlrev_b32_e32 v110, 16, v77
	v_cvt_pk_bf16_f32 v108, v2, v3
	v_lshlrev_b32_e32 v2, 16, v81
	v_and_b32_e32 v3, 0xffff0000, v81
	v_pk_fma_f32 v[2:3], v[18:19], v[2:3], v[10:11]
	v_and_b32_e32 v111, 0xffff0000, v77
	v_pk_fma_f32 v[2:3], v[22:23], v[110:111], v[2:3]
	v_lshlrev_b32_e32 v110, 16, v85
	v_and_b32_e32 v111, 0xffff0000, v85
	v_pk_fma_f32 v[2:3], v[30:31], v[110:111], v[2:3]
	v_lshlrev_b32_e32 v110, 16, v89
	v_and_b32_e32 v111, 0xffff0000, v89
	v_pk_fma_f32 v[2:3], v[38:39], v[110:111], v[2:3]
	v_lshlrev_b32_e32 v110, 16, v78
	v_cvt_pk_bf16_f32 v109, v2, v3
	v_lshlrev_b32_e32 v2, 16, v82
	v_and_b32_e32 v3, 0xffff0000, v82
	v_pk_fma_f32 v[2:3], v[12:13], v[2:3], v[4:5]
	v_and_b32_e32 v111, 0xffff0000, v78
	v_pk_fma_f32 v[2:3], v[24:25], v[110:111], v[2:3]
	v_lshlrev_b32_e32 v110, 16, v86
	v_and_b32_e32 v111, 0xffff0000, v86
	v_pk_fma_f32 v[2:3], v[32:33], v[110:111], v[2:3]
	v_lshlrev_b32_e32 v110, 16, v90
	v_and_b32_e32 v111, 0xffff0000, v90
	v_pk_fma_f32 v[2:3], v[40:41], v[110:111], v[2:3]
	v_lshlrev_b32_e32 v112, 16, v79
	v_cvt_pk_bf16_f32 v110, v2, v3
	v_lshlrev_b32_e32 v2, 16, v83
	v_and_b32_e32 v3, 0xffff0000, v83
	v_pk_fma_f32 v[2:3], v[14:15], v[2:3], v[6:7]
	v_and_b32_e32 v113, 0xffff0000, v79
	v_pk_fma_f32 v[2:3], v[26:27], v[112:113], v[2:3]
	v_lshlrev_b32_e32 v112, 16, v87
	v_and_b32_e32 v113, 0xffff0000, v87
	v_pk_fma_f32 v[2:3], v[34:35], v[112:113], v[2:3]
	v_lshlrev_b32_e32 v112, 16, v91
	v_and_b32_e32 v113, 0xffff0000, v91
	v_pk_fma_f32 v[2:3], v[42:43], v[112:113], v[2:3]
	s_nop 0
	v_cvt_pk_bf16_f32 v111, v2, v3
	v_lshlrev_b32_e32 v2, 16, v92
	v_and_b32_e32 v3, 0xffff0000, v92
	s_barrier
	ds_write_b128 v202, v[108:111]
	v_pk_fma_f32 v[2:3], v[16:17], v[2:3], v[8:9]
	v_lshlrev_b32_e32 v108, 16, v96
	v_and_b32_e32 v109, 0xffff0000, v96
	v_pk_fma_f32 v[2:3], v[20:21], v[108:109], v[2:3]
	v_lshlrev_b32_e32 v108, 16, v100
	v_and_b32_e32 v109, 0xffff0000, v100
	v_pk_fma_f32 v[2:3], v[28:29], v[108:109], v[2:3]
	v_lshlrev_b32_e32 v108, 16, v104
	v_and_b32_e32 v109, 0xffff0000, v104
	v_pk_fma_f32 v[2:3], v[36:37], v[108:109], v[2:3]
	v_lshlrev_b32_e32 v110, 16, v97
	v_cvt_pk_bf16_f32 v108, v2, v3
	v_lshlrev_b32_e32 v2, 16, v93
	v_and_b32_e32 v3, 0xffff0000, v93
	v_pk_fma_f32 v[2:3], v[18:19], v[2:3], v[10:11]
	v_and_b32_e32 v111, 0xffff0000, v97
	v_pk_fma_f32 v[2:3], v[22:23], v[110:111], v[2:3]
	v_lshlrev_b32_e32 v110, 16, v101
	v_and_b32_e32 v111, 0xffff0000, v101
	v_pk_fma_f32 v[2:3], v[30:31], v[110:111], v[2:3]
	v_lshlrev_b32_e32 v110, 16, v105
	v_and_b32_e32 v111, 0xffff0000, v105
	v_pk_fma_f32 v[2:3], v[38:39], v[110:111], v[2:3]
	v_lshlrev_b32_e32 v110, 16, v98
	v_cvt_pk_bf16_f32 v109, v2, v3
	v_lshlrev_b32_e32 v2, 16, v94
	v_and_b32_e32 v3, 0xffff0000, v94
	v_pk_fma_f32 v[2:3], v[12:13], v[2:3], v[4:5]
	v_and_b32_e32 v111, 0xffff0000, v98
	v_pk_fma_f32 v[2:3], v[24:25], v[110:111], v[2:3]
	v_lshlrev_b32_e32 v110, 16, v102
	v_and_b32_e32 v111, 0xffff0000, v102
	v_pk_fma_f32 v[2:3], v[32:33], v[110:111], v[2:3]
	v_lshlrev_b32_e32 v110, 16, v106
	v_and_b32_e32 v111, 0xffff0000, v106
	v_pk_fma_f32 v[2:3], v[40:41], v[110:111], v[2:3]
	v_lshlrev_b32_e32 v112, 16, v99
	v_cvt_pk_bf16_f32 v110, v2, v3
	v_lshlrev_b32_e32 v2, 16, v95
	v_and_b32_e32 v3, 0xffff0000, v95
	v_pk_fma_f32 v[2:3], v[14:15], v[2:3], v[6:7]
	v_and_b32_e32 v113, 0xffff0000, v99
	v_pk_fma_f32 v[2:3], v[26:27], v[112:113], v[2:3]
	v_lshlrev_b32_e32 v112, 16, v103
	v_and_b32_e32 v113, 0xffff0000, v103
	v_pk_fma_f32 v[2:3], v[34:35], v[112:113], v[2:3]
	v_lshlrev_b32_e32 v112, 16, v107
	v_and_b32_e32 v113, 0xffff0000, v107
	v_pk_fma_f32 v[2:3], v[42:43], v[112:113], v[2:3]
	s_add_i32 s13, s12, 1
	v_cvt_pk_bf16_f32 v111, v2, v3
	s_cmpk_eq_i32 s12, 0x43
	ds_write_b128 v203, v[108:111]
	s_waitcnt lgkmcnt(0)
	s_barrier
	s_cbranch_scc1 .LBB0_965
	s_cmp_lt_u32 s12, 3
	s_cselect_b32 s0, 3, 0x47
	s_add_i32 s0, s0, s5
	s_and_b64 s[10:11], s[8:9], exec
	s_cselect_b32 s0, s13, s0
	s_lshl_b32 s1, s0, 6
	s_add_i32 s10, s1, 0xffffff00
	s_cmp_lt_i32 s0, 4
	v_readlane_b32 s0, v252, 27
	v_readlane_b32 s4, v252, 31
	s_cselect_b32 s14, s1, s10
	s_cselect_b32 s4, s0, s4
	s_movk_i32 s0, 0x1000
	v_add_u32_e32 v88, s14, v195
	s_cselect_b32 s7, 0x100, s0
	v_add_u32_e32 v1, -2, v88
	v_mov_b32_e32 v78, v0
	v_mov_b32_e32 v79, v0
	v_cmp_lt_i32_e32 vcc, 1, v88
	v_cmp_gt_i32_e64 s[48:49], s7, v1
	v_mov_b32_e32 v76, v0
	v_mov_b32_e32 v77, v0
	v_mov_b64_e32 v[82:83], v[78:79]
	s_and_b64 s[16:17], vcc, s[48:49]
	v_mov_b64_e32 v[80:81], v[76:77]
	s_and_saveexec_b64 s[10:11], s[16:17]
	s_cbranch_execz .LBB0_950
	v_add_u32_e32 v1, s4, v1
	v_mad_i64_i32 v[2:3], s[16:17], v1, s73, v[120:121]
	global_load_dwordx4 v[80:83], v[2:3], off

; #define PG8_STAGE(bufoff, gbase) do { _Pragma("unroll") for (int _i = 0; _i < 2; ++_i) \
;         __builtin_amdgcn_global_load_lds((const unsigned*)((const char*)(gbase) + voff[_i]), (LAS unsigned*)(lds + (bufoff) + ldsw + _i * 8192), 16, 0, 0); } while (0)
; #define PG8_LDA(dst, b, h) do { _Pragma("unroll") for (int m = 0; m < 4; ++m) _Pragma("unroll") for (int k = 0; k < 2; ++k) dst[m][k] = *(const LAS bf16x8*)(lds + PG8_SA(b, h) + aoff + m * 2048 + k * 1024); } while (0)
; #define PG8_LDB(dst, b, h) do { _Pragma("unroll") for (int n = 0; n < 2; ++n) _Pragma("unroll") for (int k = 0; k < 2; ++k) dst[n][k] = *(const LAS bf16x8*)(lds + PG8_SB(b, h) + boff + n * 2048 + k * 1024); } while (0)
; #define PG8_WAIT_L(n) asm volatile("s_waitcnt lgkmcnt(" #n ")" ::: "memory")
; #define PG8_BAR __builtin_amdgcn_s_barrier()
; #define PG8_SCHED __builtin_amdgcn_sched_barrier(0)
;     ...
;         for (int t = 0; t < nt; t += 2) {
;             const bool last = (t == nt - 2);
;             const char* a1 = cA + (size_t)(t + 1) * kstep;
;             const char* a2 = last ? nA : cA + (size_t)(t + 2) * kstep; const char* b2 = last ? nB : cB + (size_t)(t + 2) * kstep;
;             const char* a3 = a2 + kstep; const char* b3 = b2 + kstep;
;             PG8_LDB(B0, 0, 0); PG8_SCHED; PG8_LDA(At, 0, 0); PG8_STAGE(PG8_SA(1, 1), a1 + hstep);
;             PG8_WAIT_L(8); PG8_BAR; PG8_WAIT_L(0); PG8_MMA(0, 0, At, B0); PG8_BAR; PG8_SCHED;
;             PG8_LDB(B1, 0, 1); PG8_STAGE(PG8_SB(0, 0), b2);
;             PG8_BAR; PG8_WAIT_L(0); PG8_MMA(0, 1, At, B1); PG8_BAR;
;     ...
; #pragma unroll
;         for (int a = 0; a < 2; ++a)
; #pragma unroll
;             for (int b = 0; b < 2; ++b)
; #pragma unroll
;                 for (int m = 0; m < 4; ++m)
; #pragma unroll
;                     for (int n = 0; n < 2; ++n) acc[a][b][m][n] = (f32x4){0.f, 0.f, 0.f, 0.f};
;         cur = nxt; cA = nA; cB = nB; ++ui;
.LBB0_1244:
	s_add_u32 s40, s40, 0x80
	s_addc_u32 s41, s41, 0
	s_add_u32 s58, s58, 0x100
	v_mov_b32_e32 v2, 0
	s_addc_u32 s59, s59, 0
	s_mov_b32 s46, 0
	v_mov_b32_e32 v3, v2
	v_mov_b32_e32 v4, v2
	v_mov_b32_e32 v5, v2
	v_mov_b32_e32 v18, v2
	v_mov_b32_e32 v19, v2
	v_mov_b32_e32 v20, v2
	v_mov_b32_e32 v21, v2
	v_mov_b32_e32 v6, v2
	v_mov_b32_e32 v7, v2
	v_mov_b32_e32 v8, v2
	v_mov_b32_e32 v9, v2
	v_mov_b32_e32 v26, v2
	v_mov_b32_e32 v27, v2
	v_mov_b32_e32 v28, v2
	v_mov_b32_e32 v29, v2
	v_mov_b32_e32 v10, v2
	v_mov_b32_e32 v11, v2
	v_mov_b32_e32 v12, v2
	v_mov_b32_e32 v13, v2
	v_mov_b32_e32 v34, v2
	v_mov_b32_e32 v35, v2
	v_mov_b32_e32 v36, v2
	v_mov_b32_e32 v37, v2
	v_mov_b32_e32 v14, v2
	v_mov_b32_e32 v15, v2
	v_mov_b32_e32 v16, v2
	v_mov_b32_e32 v17, v2
	v_mov_b32_e32 v42, v2
	v_mov_b32_e32 v43, v2
	v_mov_b32_e32 v44, v2
	v_mov_b32_e32 v45, v2
	v_mov_b32_e32 v54, v2
	v_mov_b32_e32 v55, v2
	v_mov_b32_e32 v56, v2
	v_mov_b32_e32 v57, v2
	v_mov_b32_e32 v86, v2
	v_mov_b32_e32 v87, v2
	v_mov_b32_e32 v88, v2
	v_mov_b32_e32 v89, v2
	v_mov_b32_e32 v62, v2
	v_mov_b32_e32 v63, v2
	v_mov_b32_e32 v64, v2
	v_mov_b32_e32 v65, v2
	v_mov_b32_e32 v102, v2
	v_mov_b32_e32 v103, v2
	v_mov_b32_e32 v104, v2
	v_mov_b32_e32 v105, v2
	v_mov_b32_e32 v70, v2
	v_mov_b32_e32 v71, v2
	v_mov_b32_e32 v72, v2
	v_mov_b32_e32 v73, v2
	v_mov_b32_e32 v106, v2
	v_mov_b32_e32 v107, v2
	v_mov_b32_e32 v108, v2
	v_mov_b32_e32 v109, v2
	v_mov_b32_e32 v78, v2
	v_mov_b32_e32 v79, v2
	v_mov_b32_e32 v80, v2
	v_mov_b32_e32 v81, v2
	v_mov_b32_e32 v110, v2
	v_mov_b32_e32 v111, v2
	v_mov_b32_e32 v112, v2
	v_mov_b32_e32 v113, v2
	v_mov_b32_e32 v22, v2
	v_mov_b32_e32 v23, v2
	v_mov_b32_e32 v24, v2
	v_mov_b32_e32 v25, v2
	v_mov_b32_e32 v50, v2
	v_mov_b32_e32 v51, v2
	v_mov_b32_e32 v52, v2
	v_mov_b32_e32 v53, v2
	v_mov_b32_e32 v30, v2
	v_mov_b32_e32 v31, v2
	v_mov_b32_e32 v32, v2
	v_mov_b32_e32 v33, v2
	v_mov_b32_e32 v58, v2
	v_mov_b32_e32 v59, v2
	v_mov_b32_e32 v60, v2
	v_mov_b32_e32 v61, v2
	v_mov_b32_e32 v38, v2
	v_mov_b32_e32 v39, v2
	v_mov_b32_e32 v40, v2
	v_mov_b32_e32 v41, v2
	v_mov_b32_e32 v66, v2
	v_mov_b32_e32 v67, v2
	v_mov_b32_e32 v68, v2
	v_mov_b32_e32 v69, v2
	v_mov_b32_e32 v46, v2
	v_mov_b32_e32 v47, v2
	v_mov_b32_e32 v48, v2
	v_mov_b32_e32 v49, v2
	v_mov_b32_e32 v74, v2
	v_mov_b32_e32 v75, v2
	v_mov_b32_e32 v76, v2
	v_mov_b32_e32 v77, v2
	v_mov_b32_e32 v82, v2
	v_mov_b32_e32 v83, v2
	v_mov_b32_e32 v84, v2
	v_mov_b32_e32 v85, v2
	v_mov_b32_e32 v114, v2
	v_mov_b32_e32 v115, v2
	v_mov_b32_e32 v116, v2
	v_mov_b32_e32 v117, v2
	v_mov_b32_e32 v90, v2
	v_mov_b32_e32 v91, v2
	v_mov_b32_e32 v92, v2
	v_mov_b32_e32 v93, v2
	v_mov_b32_e32 v118, v2
	v_mov_b32_e32 v119, v2
	v_mov_b32_e32 v120, v2
	v_mov_b32_e32 v121, v2
	v_mov_b32_e32 v94, v2
	v_mov_b32_e32 v95, v2
	v_mov_b32_e32 v96, v2
	v_mov_b32_e32 v97, v2
	v_mov_b32_e32 v122, v2
	v_mov_b32_e32 v123, v2
	v_mov_b32_e32 v124, v2
	v_mov_b32_e32 v125, v2
	v_mov_b32_e32 v98, v2
	v_mov_b32_e32 v99, v2
	v_mov_b32_e32 v100, v2
	v_mov_b32_e32 v101, v2
	v_mov_b32_e32 v126, v2
	v_mov_b32_e32 v127, v2
	v_mov_b32_e32 v128, v2
	v_mov_b32_e32 v129, v2
.LBB0_1245:
	s_add_i32 s67, s46, 2
	s_add_u32 s0, s40, 0x80
	s_addc_u32 s1, s41, 0
	s_add_i32 s68, 0, 0x10000
	v_add_u32_e32 v169, s68, v166
	ds_read_b128 v[130:133], v169
	ds_read_b128 v[158:161], v169 offset:1024
	ds_read_b128 v[162:165], v169 offset:2048
	ds_read_b128 v[170:173], v169 offset:3072
	s_cmp_eq_u32 s30, s46
	s_cselect_b32 s46, s12, s0
	s_cselect_b32 s47, s13, s1
	s_cselect_b32 s49, s15, s59
	s_cselect_b32 s48, s14, s58
	v_lshl_add_u64 v[174:175], s[40:41], 0, v[154:155]
	s_add_i32 m0, s23, 0xc000
	ds_read_b128 v[194:197], v168
	ds_read_b128 v[198:201], v168 offset:1024
	ds_read_b128 v[202:205], v168 offset:2048
	ds_read_b128 v[206:209], v168 offset:3072
	ds_read_b128 v[210:213], v168 offset:4096
	ds_read_b128 v[214:217], v168 offset:5120
	ds_read_b128 v[218:221], v168 offset:6144
	ds_read_b128 v[222:225], v168 offset:7168
	global_load_lds_dwordx4 v[174:175], off
	v_lshl_add_u64 v[174:175], s[40:41], 0, v[156:157]
	s_add_i32 m0, s23, 0xe000
	s_nop 0
	global_load_lds_dwordx4 v[174:175], off
	s_waitcnt lgkmcnt(8)
	s_barrier
	s_waitcnt lgkmcnt(0)
	s_setprio 1
	s_waitcnt lgkmcnt(0)
	v_mfma_f32_16x16x32_bf16 v[126:129], v[130:133], v[194:197], v[126:129]
	v_mfma_f32_16x16x32_bf16 v[98:101], v[162:165], v[194:197], v[98:101]
	v_mfma_f32_16x16x32_bf16 v[122:125], v[130:133], v[202:205], v[122:125]
	v_mfma_f32_16x16x32_bf16 v[94:97], v[162:165], v[202:205], v[94:97]
	v_mfma_f32_16x16x32_bf16 v[118:121], v[130:133], v[210:213], v[118:121]
	v_mfma_f32_16x16x32_bf16 v[90:93], v[162:165], v[210:213], v[90:93]
	v_mfma_f32_16x16x32_bf16 v[114:117], v[130:133], v[218:221], v[114:117]
	v_mfma_f32_16x16x32_bf16 v[82:85], v[162:165], v[218:221], v[82:85]
	v_mfma_f32_16x16x32_bf16 v[126:129], v[158:161], v[198:201], v[126:129]
	v_mfma_f32_16x16x32_bf16 v[98:101], v[170:173], v[198:201], v[98:101]
	v_mfma_f32_16x16x32_bf16 v[122:125], v[158:161], v[206:209], v[122:125]
	v_mfma_f32_16x16x32_bf16 v[94:97], v[170:173], v[206:209], v[94:97]
	v_mfma_f32_16x16x32_bf16 v[118:121], v[158:161], v[214:217], v[118:121]
	v_mfma_f32_16x16x32_bf16 v[90:93], v[170:173], v[214:217], v[90:93]
	v_mfma_f32_16x16x32_bf16 v[114:117], v[158:161], v[222:225], v[114:117]
	v_mfma_f32_16x16x32_bf16 v[82:85], v[170:173], v[222:225], v[82:85]
	s_setprio 0
	s_barrier
	s_add_i32 s69, 0, 0x14000
	s_add_i32 s0, s68, s18
	v_add_u32_e32 v169, s69, v166
	v_lshl_add_u64 v[174:175], s[48:49], 0, v[152:153]
	s_mov_b32 m0, s0
	ds_read_b128 v[226:229], v169
	ds_read_b128 v[230:233], v169 offset:1024
	ds_read_b128 v[234:237], v169 offset:2048
	ds_read_b128 v[238:241], v169 offset:3072
	global_load_lds_dwordx4 v[174:175], off
	v_lshl_add_u64 v[192:193], s[48:49], 0, v[150:151]
	s_add_i32 m0, s0, 0x2000
	s_nop 0
	global_load_lds_dwordx4 v[192:193], off
	s_barrier
; #define PG8_STAGE(bufoff, gbase) do { _Pragma("unroll") for (int _i = 0; _i < 2; ++_i) \
;         __builtin_amdgcn_global_load_lds((const unsigned*)((const char*)(gbase) + voff[_i]), (LAS unsigned*)(lds + (bufoff) + ldsw + _i * 8192), 16, 0, 0); } while (0)
; #define PG8_LDA(dst, b, h) do { _Pragma("unroll") for (int m = 0; m < 4; ++m) _Pragma("unroll") for (int k = 0; k < 2; ++k) dst[m][k] = *(const LAS bf16x8*)(lds + PG8_SA(b, h) + aoff + m * 2048 + k * 1024); } while (0)
; #define PG8_LDB(dst, b, h) do { _Pragma("unroll") for (int n = 0; n < 2; ++n) _Pragma("unroll") for (int k = 0; k < 2; ++k) dst[n][k] = *(const LAS bf16x8*)(lds + PG8_SB(b, h) + boff + n * 2048 + k * 1024); } while (0)
; #define PG8_WAIT_V(n) asm volatile("s_waitcnt vmcnt(" #n ")" ::: "memory")
; #define PG8_WAIT_L(n) asm volatile("s_waitcnt lgkmcnt(" #n ")" ::: "memory")
; #define PG8_BAR __builtin_amdgcn_s_barrier()
; #define PG8_SCHED __builtin_amdgcn_sched_barrier(0)
;     ...
;             PG8_BAR; PG8_WAIT_L(0); PG8_MMA(0, 1, At, B1); PG8_BAR;
;             PG8_LDA(At, 0, 1); PG8_STAGE(PG8_SA(0, 0), a2);
;             PG8_BAR; PG8_WAIT_L(0); PG8_MMA(1, 0, At, B0); PG8_BAR; PG8_SCHED;
;             PG8_STAGE(PG8_SB(0, 1), b2 + hstep);
;             PG8_WAIT_V(6); PG8_BAR; PG8_MMA(1, 1, At, B1); PG8_BAR;
;             PG8_LDB(B0, 1, 0); PG8_SCHED; PG8_LDA(At, 1, 0); PG8_STAGE(PG8_SA(0, 1), a2 + hstep);
;             PG8_WAIT_L(8); PG8_BAR; PG8_WAIT_L(0); PG8_MMA(0, 0, At, B0); PG8_BAR; PG8_SCHED;
;             PG8_LDB(B1, 1, 1); PG8_STAGE(PG8_SB(1, 0), b3);
;             PG8_BAR; PG8_WAIT_L(0); PG8_MMA(0, 1, At, B1); PG8_BAR;
;             PG8_LDA(At, 1, 1); PG8_STAGE(PG8_SA(1, 0), a3);
;             PG8_BAR; PG8_WAIT_L(0); PG8_MMA(1, 0, At, B0); PG8_BAR; PG8_SCHED;
	s_waitcnt lgkmcnt(0)
	s_setprio 1
	s_waitcnt lgkmcnt(0)
	v_mfma_f32_16x16x32_bf16 v[74:77], v[226:229], v[194:197], v[74:77]
	v_mfma_f32_16x16x32_bf16 v[46:49], v[234:237], v[194:197], v[46:49]
	v_mfma_f32_16x16x32_bf16 v[66:69], v[226:229], v[202:205], v[66:69]
	v_mfma_f32_16x16x32_bf16 v[38:41], v[234:237], v[202:205], v[38:41]
	v_mfma_f32_16x16x32_bf16 v[58:61], v[226:229], v[210:213], v[58:61]
	v_mfma_f32_16x16x32_bf16 v[30:33], v[234:237], v[210:213], v[30:33]
	v_mfma_f32_16x16x32_bf16 v[50:53], v[226:229], v[218:221], v[50:53]
	v_mfma_f32_16x16x32_bf16 v[22:25], v[234:237], v[218:221], v[22:25]
	v_mfma_f32_16x16x32_bf16 v[74:77], v[230:233], v[198:201], v[74:77]
	v_mfma_f32_16x16x32_bf16 v[46:49], v[238:241], v[198:201], v[46:49]
	v_mfma_f32_16x16x32_bf16 v[66:69], v[230:233], v[206:209], v[66:69]
	v_mfma_f32_16x16x32_bf16 v[38:41], v[238:241], v[206:209], v[38:41]
	v_mfma_f32_16x16x32_bf16 v[58:61], v[230:233], v[214:217], v[58:61]
	v_mfma_f32_16x16x32_bf16 v[30:33], v[238:241], v[214:217], v[30:33]
	v_mfma_f32_16x16x32_bf16 v[50:53], v[230:233], v[222:225], v[50:53]
	v_mfma_f32_16x16x32_bf16 v[22:25], v[238:241], v[222:225], v[22:25]
	s_setprio 0
	s_mov_b32 m0, s23
	v_lshl_add_u64 v[242:243], s[46:47], 0, v[152:153]
	s_barrier
	ds_read_b128 v[194:197], v168 offset:16384
	ds_read_b128 v[198:201], v168 offset:17408
	ds_read_b128 v[202:205], v168 offset:18432
	ds_read_b128 v[206:209], v168 offset:19456
	ds_read_b128 v[210:213], v168 offset:20480
	ds_read_b128 v[214:217], v168 offset:21504
	ds_read_b128 v[218:221], v168 offset:22528
	ds_read_b128 v[222:225], v168 offset:23552
	global_load_lds_dwordx4 v[242:243], off
	v_lshl_add_u64 v[244:245], s[46:47], 0, v[150:151]
	s_mov_b32 m0, s36
	s_nop 0
	global_load_lds_dwordx4 v[244:245], off
	s_barrier
	s_waitcnt lgkmcnt(0)
	s_setprio 1
	s_waitcnt lgkmcnt(0)
	v_mfma_f32_16x16x32_bf16 v[110:113], v[130:133], v[194:197], v[110:113]
	v_mfma_f32_16x16x32_bf16 v[78:81], v[162:165], v[194:197], v[78:81]
	v_mfma_f32_16x16x32_bf16 v[106:109], v[130:133], v[202:205], v[106:109]
	v_mfma_f32_16x16x32_bf16 v[70:73], v[162:165], v[202:205], v[70:73]
	v_mfma_f32_16x16x32_bf16 v[102:105], v[130:133], v[210:213], v[102:105]
	v_mfma_f32_16x16x32_bf16 v[62:65], v[162:165], v[210:213], v[62:65]
	v_mfma_f32_16x16x32_bf16 v[86:89], v[130:133], v[218:221], v[86:89]
	v_mfma_f32_16x16x32_bf16 v[54:57], v[162:165], v[218:221], v[54:57]
	v_mfma_f32_16x16x32_bf16 v[110:113], v[158:161], v[198:201], v[110:113]
	v_mfma_f32_16x16x32_bf16 v[78:81], v[170:173], v[198:201], v[78:81]
	v_mfma_f32_16x16x32_bf16 v[106:109], v[158:161], v[206:209], v[106:109]
	v_mfma_f32_16x16x32_bf16 v[70:73], v[170:173], v[206:209], v[70:73]
	v_mfma_f32_16x16x32_bf16 v[102:105], v[158:161], v[214:217], v[102:105]
	v_mfma_f32_16x16x32_bf16 v[62:65], v[170:173], v[214:217], v[62:65]
	v_mfma_f32_16x16x32_bf16 v[86:89], v[158:161], v[222:225], v[86:89]
	v_mfma_f32_16x16x32_bf16 v[54:57], v[170:173], v[222:225], v[54:57]
	s_setprio 0
	s_barrier
	s_add_u32 s0, s48, s20
	s_addc_u32 s1, s49, 0
	s_add_i32 s48, s69, s18
	v_lshl_add_u64 v[246:247], s[0:1], 0, v[152:153]
	s_mov_b32 m0, s48
	v_lshl_add_u64 v[248:249], s[0:1], 0, v[150:151]
	global_load_lds_dwordx4 v[246:247], off
	s_add_i32 m0, s48, 0x2000
	s_nop 0
	global_load_lds_dwordx4 v[248:249], off
	s_waitcnt vmcnt(6)
	s_barrier
	s_setprio 1
	v_mfma_f32_16x16x32_bf16 v[42:45], v[226:229], v[194:197], v[42:45]
	v_mfma_f32_16x16x32_bf16 v[14:17], v[234:237], v[194:197], v[14:17]
	v_mfma_f32_16x16x32_bf16 v[34:37], v[226:229], v[202:205], v[34:37]
	v_mfma_f32_16x16x32_bf16 v[10:13], v[234:237], v[202:205], v[10:13]
	v_mfma_f32_16x16x32_bf16 v[26:29], v[226:229], v[210:213], v[26:29]
	v_mfma_f32_16x16x32_bf16 v[6:9], v[234:237], v[210:213], v[6:9]
	v_mfma_f32_16x16x32_bf16 v[18:21], v[226:229], v[218:221], v[18:21]
	v_mfma_f32_16x16x32_bf16 v[2:5], v[234:237], v[218:221], v[2:5]
	v_mfma_f32_16x16x32_bf16 v[42:45], v[230:233], v[198:201], v[42:45]
	v_mfma_f32_16x16x32_bf16 v[14:17], v[238:241], v[198:201], v[14:17]
	v_mfma_f32_16x16x32_bf16 v[34:37], v[230:233], v[206:209], v[34:37]
	v_mfma_f32_16x16x32_bf16 v[10:13], v[238:241], v[206:209], v[10:13]
	v_mfma_f32_16x16x32_bf16 v[26:29], v[230:233], v[214:217], v[26:29]
	v_mfma_f32_16x16x32_bf16 v[6:9], v[238:241], v[214:217], v[6:9]
	v_mfma_f32_16x16x32_bf16 v[18:21], v[230:233], v[222:225], v[18:21]
	v_mfma_f32_16x16x32_bf16 v[2:5], v[238:241], v[222:225], v[2:5]
	s_setprio 0
	s_add_i32 s48, 0, 0x18000
	v_add_u32_e32 v169, s48, v166
	s_barrier
	ds_read_b128 v[130:133], v169
	ds_read_b128 v[158:161], v169 offset:1024
	ds_read_b128 v[162:165], v169 offset:2048
	ds_read_b128 v[170:173], v169 offset:3072
	s_add_u32 s0, s46, s20
	s_addc_u32 s1, s47, 0
	s_mov_b32 m0, s60
	v_lshl_add_u64 v[226:227], s[0:1], 0, v[152:153]
	ds_read_b128 v[194:197], v168 offset:32768
	ds_read_b128 v[198:201], v168 offset:33792
	ds_read_b128 v[202:205], v168 offset:34816
	ds_read_b128 v[206:209], v168 offset:35840
	ds_read_b128 v[210:213], v168 offset:36864
	ds_read_b128 v[214:217], v168 offset:37888
	ds_read_b128 v[218:221], v168 offset:38912
	ds_read_b128 v[222:225], v168 offset:39936
	global_load_lds_dwordx4 v[226:227], off
	v_lshl_add_u64 v[226:227], s[0:1], 0, v[150:151]
	s_mov_b32 m0, s61
	s_nop 0
	global_load_lds_dwordx4 v[226:227], off
	s_waitcnt lgkmcnt(8)
	s_barrier
; #define PG8_STAGE(bufoff, gbase) do { _Pragma("unroll") for (int _i = 0; _i < 2; ++_i) \
;         __builtin_amdgcn_global_load_lds((const unsigned*)((const char*)(gbase) + voff[_i]), (LAS unsigned*)(lds + (bufoff) + ldsw + _i * 8192), 16, 0, 0); } while (0)
; #define PG8_LDA(dst, b, h) do { _Pragma("unroll") for (int m = 0; m < 4; ++m) _Pragma("unroll") for (int k = 0; k < 2; ++k) dst[m][k] = *(const LAS bf16x8*)(lds + PG8_SA(b, h) + aoff + m * 2048 + k * 1024); } while (0)
; #define PG8_LDB(dst, b, h) do { _Pragma("unroll") for (int n = 0; n < 2; ++n) _Pragma("unroll") for (int k = 0; k < 2; ++k) dst[n][k] = *(const LAS bf16x8*)(lds + PG8_SB(b, h) + boff + n * 2048 + k * 1024); } while (0)
; #define PG8_WAIT_V(n) asm volatile("s_waitcnt vmcnt(" #n ")" ::: "memory")
; #define PG8_WAIT_L(n) asm volatile("s_waitcnt lgkmcnt(" #n ")" ::: "memory")
; #define PG8_BAR __builtin_amdgcn_s_barrier()
; #define PG8_SCHED __builtin_amdgcn_sched_barrier(0)
;     ...
;             PG8_WAIT_L(8); PG8_BAR; PG8_WAIT_L(0); PG8_MMA(0, 0, At, B0); PG8_BAR; PG8_SCHED;
;             PG8_LDB(B1, 1, 1); PG8_STAGE(PG8_SB(1, 0), b3);
;             PG8_BAR; PG8_WAIT_L(0); PG8_MMA(0, 1, At, B1); PG8_BAR;
;             PG8_LDA(At, 1, 1); PG8_STAGE(PG8_SA(1, 0), a3);
;             PG8_BAR; PG8_WAIT_L(0); PG8_MMA(1, 0, At, B0); PG8_BAR; PG8_SCHED;
;             PG8_STAGE(PG8_SB(1, 1), b3 + hstep);
;             PG8_WAIT_V(6); PG8_BAR; PG8_MMA(1, 1, At, B1); PG8_BAR;
	s_waitcnt lgkmcnt(0)
	s_setprio 1
	s_waitcnt lgkmcnt(0)
	v_mfma_f32_16x16x32_bf16 v[126:129], v[130:133], v[194:197], v[126:129]
	v_mfma_f32_16x16x32_bf16 v[98:101], v[162:165], v[194:197], v[98:101]
	v_mfma_f32_16x16x32_bf16 v[122:125], v[130:133], v[202:205], v[122:125]
	v_mfma_f32_16x16x32_bf16 v[94:97], v[162:165], v[202:205], v[94:97]
	v_mfma_f32_16x16x32_bf16 v[118:121], v[130:133], v[210:213], v[118:121]
	v_mfma_f32_16x16x32_bf16 v[90:93], v[162:165], v[210:213], v[90:93]
	v_mfma_f32_16x16x32_bf16 v[114:117], v[130:133], v[218:221], v[114:117]
	v_mfma_f32_16x16x32_bf16 v[82:85], v[162:165], v[218:221], v[82:85]
	v_mfma_f32_16x16x32_bf16 v[126:129], v[158:161], v[198:201], v[126:129]
	v_mfma_f32_16x16x32_bf16 v[98:101], v[170:173], v[198:201], v[98:101]
	v_mfma_f32_16x16x32_bf16 v[122:125], v[158:161], v[206:209], v[122:125]
	v_mfma_f32_16x16x32_bf16 v[94:97], v[170:173], v[206:209], v[94:97]
	v_mfma_f32_16x16x32_bf16 v[118:121], v[158:161], v[214:217], v[118:121]
	v_mfma_f32_16x16x32_bf16 v[90:93], v[170:173], v[214:217], v[90:93]
	v_mfma_f32_16x16x32_bf16 v[114:117], v[158:161], v[222:225], v[114:117]
	v_mfma_f32_16x16x32_bf16 v[82:85], v[170:173], v[222:225], v[82:85]
	s_setprio 0
	s_barrier
	s_add_i32 s0, 0, 0x1c000
	s_add_i32 s1, s48, s18
	v_add_u32_e32 v169, s0, v166
	v_lshl_add_u64 v[174:175], v[174:175], 0, s[88:89]
	s_mov_b32 m0, s1
	ds_read_b128 v[226:229], v169
	ds_read_b128 v[230:233], v169 offset:1024
	ds_read_b128 v[234:237], v169 offset:2048
	ds_read_b128 v[238:241], v169 offset:3072
	global_load_lds_dwordx4 v[174:175], off
	v_lshl_add_u64 v[174:175], v[192:193], 0, s[88:89]
	s_add_i32 m0, s1, 0x2000
	s_nop 0
	global_load_lds_dwordx4 v[174:175], off
	s_barrier
	s_waitcnt lgkmcnt(0)
	s_setprio 1
	s_waitcnt lgkmcnt(0)
	v_mfma_f32_16x16x32_bf16 v[74:77], v[226:229], v[194:197], v[74:77]
	v_mfma_f32_16x16x32_bf16 v[46:49], v[234:237], v[194:197], v[46:49]
	v_mfma_f32_16x16x32_bf16 v[66:69], v[226:229], v[202:205], v[66:69]
	v_mfma_f32_16x16x32_bf16 v[38:41], v[234:237], v[202:205], v[38:41]
	v_mfma_f32_16x16x32_bf16 v[58:61], v[226:229], v[210:213], v[58:61]
	v_mfma_f32_16x16x32_bf16 v[30:33], v[234:237], v[210:213], v[30:33]
	v_mfma_f32_16x16x32_bf16 v[50:53], v[226:229], v[218:221], v[50:53]
	v_mfma_f32_16x16x32_bf16 v[22:25], v[234:237], v[218:221], v[22:25]
	v_mfma_f32_16x16x32_bf16 v[74:77], v[230:233], v[198:201], v[74:77]
	v_mfma_f32_16x16x32_bf16 v[46:49], v[238:241], v[198:201], v[46:49]
	v_mfma_f32_16x16x32_bf16 v[66:69], v[230:233], v[206:209], v[66:69]
	v_mfma_f32_16x16x32_bf16 v[38:41], v[238:241], v[206:209], v[38:41]
	v_mfma_f32_16x16x32_bf16 v[58:61], v[230:233], v[214:217], v[58:61]
	v_mfma_f32_16x16x32_bf16 v[30:33], v[238:241], v[214:217], v[30:33]
	v_mfma_f32_16x16x32_bf16 v[50:53], v[230:233], v[222:225], v[50:53]
	v_mfma_f32_16x16x32_bf16 v[22:25], v[238:241], v[222:225], v[22:25]
	s_setprio 0
	s_mov_b32 m0, s28
	v_lshl_add_u64 v[174:175], v[242:243], 0, s[88:89]
	s_barrier
	ds_read_b128 v[194:197], v168 offset:49152
	ds_read_b128 v[198:201], v168 offset:50176
	ds_read_b128 v[202:205], v168 offset:51200
	ds_read_b128 v[206:209], v168 offset:52224
	ds_read_b128 v[210:213], v168 offset:53248
	ds_read_b128 v[214:217], v168 offset:54272
	ds_read_b128 v[218:221], v168 offset:55296
	ds_read_b128 v[222:225], v168 offset:56320
	global_load_lds_dwordx4 v[174:175], off
	v_lshl_add_u64 v[174:175], v[244:245], 0, s[88:89]
	s_mov_b32 m0, s29
	s_nop 0
	global_load_lds_dwordx4 v[174:175], off
	s_barrier
	s_waitcnt lgkmcnt(0)
	s_setprio 1
	s_waitcnt lgkmcnt(0)
	v_mfma_f32_16x16x32_bf16 v[110:113], v[130:133], v[194:197], v[110:113]
	v_mfma_f32_16x16x32_bf16 v[78:81], v[162:165], v[194:197], v[78:81]
	v_mfma_f32_16x16x32_bf16 v[106:109], v[130:133], v[202:205], v[106:109]
	v_mfma_f32_16x16x32_bf16 v[70:73], v[162:165], v[202:205], v[70:73]
	v_mfma_f32_16x16x32_bf16 v[102:105], v[130:133], v[210:213], v[102:105]
	v_mfma_f32_16x16x32_bf16 v[62:65], v[162:165], v[210:213], v[62:65]
	v_mfma_f32_16x16x32_bf16 v[86:89], v[130:133], v[218:221], v[86:89]
	v_mfma_f32_16x16x32_bf16 v[54:57], v[162:165], v[218:221], v[54:57]
	v_mfma_f32_16x16x32_bf16 v[110:113], v[158:161], v[198:201], v[110:113]
	v_mfma_f32_16x16x32_bf16 v[78:81], v[170:173], v[198:201], v[78:81]
	v_mfma_f32_16x16x32_bf16 v[106:109], v[158:161], v[206:209], v[106:109]
	v_mfma_f32_16x16x32_bf16 v[70:73], v[170:173], v[206:209], v[70:73]
	v_mfma_f32_16x16x32_bf16 v[102:105], v[158:161], v[214:217], v[102:105]
	v_mfma_f32_16x16x32_bf16 v[62:65], v[170:173], v[214:217], v[62:65]
	v_mfma_f32_16x16x32_bf16 v[86:89], v[158:161], v[222:225], v[86:89]
	v_mfma_f32_16x16x32_bf16 v[54:57], v[170:173], v[222:225], v[54:57]
	s_setprio 0
	s_barrier
	s_add_i32 s0, s0, s18
	v_lshl_add_u64 v[130:131], v[246:247], 0, s[88:89]
	s_mov_b32 m0, s0
	s_nop 0
	global_load_lds_dwordx4 v[130:131], off
	v_lshl_add_u64 v[130:131], v[248:249], 0, s[88:89]
	s_add_i32 m0, s0, 0x2000
	s_nop 0
	global_load_lds_dwordx4 v[130:131], off
	s_waitcnt vmcnt(6)
	s_barrier
	s_setprio 1
	v_mfma_f32_16x16x32_bf16 v[42:45], v[226:229], v[194:197], v[42:45]
	v_mfma_f32_16x16x32_bf16 v[14:17], v[234:237], v[194:197], v[14:17]
	v_mfma_f32_16x16x32_bf16 v[34:37], v[226:229], v[202:205], v[34:37]
	v_mfma_f32_16x16x32_bf16 v[10:13], v[234:237], v[202:205], v[10:13]
	v_mfma_f32_16x16x32_bf16 v[26:29], v[226:229], v[210:213], v[26:29]
	v_mfma_f32_16x16x32_bf16 v[6:9], v[234:237], v[210:213], v[6:9]
	v_mfma_f32_16x16x32_bf16 v[18:21], v[226:229], v[218:221], v[18:21]
	v_mfma_f32_16x16x32_bf16 v[2:5], v[234:237], v[218:221], v[2:5]
	v_mfma_f32_16x16x32_bf16 v[42:45], v[230:233], v[198:201], v[42:45]
	v_mfma_f32_16x16x32_bf16 v[14:17], v[238:241], v[198:201], v[14:17]
	v_mfma_f32_16x16x32_bf16 v[34:37], v[230:233], v[206:209], v[34:37]
	v_mfma_f32_16x16x32_bf16 v[10:13], v[238:241], v[206:209], v[10:13]
	v_mfma_f32_16x16x32_bf16 v[26:29], v[230:233], v[214:217], v[26:29]
	v_mfma_f32_16x16x32_bf16 v[6:9], v[238:241], v[214:217], v[6:9]
	v_mfma_f32_16x16x32_bf16 v[18:21], v[230:233], v[222:225], v[18:21]
	v_mfma_f32_16x16x32_bf16 v[2:5], v[238:241], v[222:225], v[2:5]
	s_setprio 0
	s_add_u32 s40, s40, 0x100
	s_addc_u32 s41, s41, 0
	s_add_u32 s58, s58, 0x100
	s_addc_u32 s59, s59, 0
	s_cmp_ge_u32 s67, s7
	s_mov_b32 s46, s67
	s_barrier
;     __device__ __forceinline__ void operator()(Acc& acc, int pm, int pn, int wr, int wc, int fr, int fq) const {
;         const int brow = pm * 256;
;         const bool lat = brow < T_LAT;
;         const float* xin = lat ? xin_lat : xin_ctx;
;         float* xout = lat ? xout_lat : xout_ctx;
;         const int rsub = lat ? 0 : T_LAT;
;         const int mi = lat ? (brow >> 12) : 8;
;         const int c0 = pn * 256 + wc * 32 + fq * 4;
;         const float* gp = modv_l + (size_t)mi * 6144 + gate_i * 1024 + c0;
; #pragma unroll
;         for (int bj = 0; bj < 2; ++bj)
; #pragma unroll
;             for (int n = 0; n < 2; ++n) {
;                 const f32x4 gv = *reinterpret_cast<const f32x4*>(gp + bj * 128 + n * 16);
; #pragma unroll
;                 for (int ai = 0; ai < 2; ++ai)
; #pragma unroll
;                     for (int m = 0; m < 4; ++m) {
;                         const size_t o = (size_t)(brow + ai * 128 + wr * 64 + m * 16 + fr - rsub) * DM + c0 + bj * 128 + n * 16;
;                         const f32x4 xi = *reinterpret_cast<const f32x4*>(xin + o);
;                         const f32x4 a = acc[ai][bj][m][n];
;                         f32x4 r = {xi[0] + gv[0] * a[0], xi[1] + gv[1] * a[1], xi[2] + gv[2] * a[2], xi[3] + gv[3] * a[3]};
;                         *reinterpret_cast<f32x4*>(xout + o) = r;
;                     }
	s_cbranch_scc0 .LBB0_1245
	s_lshl_b32 s48, s65, 8
	v_readlane_b32 s0, v255, 26
	v_readlane_b32 s40, v255, 24
	v_readlane_b32 s68, v254, 6
	s_cmpk_lt_i32 s65, 0x80
	v_readlane_b32 s1, v255, 27
	v_readlane_b32 s41, v255, 25
	v_readlane_b32 s70, v254, 8
	v_readlane_b32 s71, v254, 9
	v_readlane_b32 s72, v254, 10
	v_readlane_b32 s73, v254, 11
	s_cselect_b32 s47, s41, s1
	s_cselect_b32 s46, s40, s0
	s_cselect_b32 s49, 0, 0xffff8000
	s_cselect_b32 s41, s71, s73
	s_cselect_b32 s40, s70, s72
	s_min_i32 s0, s65, 0x80
	s_ashr_i32 s0, s0, 4
	s_mul_hi_i32 s1, s0, 0x6000
	s_mulk_i32 s0, 0x6000
	s_add_u32 s0, s50, s0
	s_addc_u32 s1, s51, s1
	s_add_i32 s49, s49, s48
	s_add_u32 s0, s0, 0x2000
	s_addc_u32 s1, s1, 0
	v_lshl_or_b32 v162, s66, 8, v167
	v_add_u32_e32 v164, s49, v1
	v_ashrrev_i32_e32 v163, 31, v162
	v_lshl_add_u64 v[174:175], v[162:163], 2, s[0:1]
	global_load_dwordx4 v[130:133], v[174:175], off
	global_load_dwordx4 v[158:161], v[174:175], off offset:64
	global_load_dwordx4 v[170:173], v[174:175], off offset:512
	global_load_dwordx4 v[192:195], v[174:175], off offset:576
	v_lshl_add_u32 v165, v164, 10, v162
	v_lshlrev_b32_e32 v165, 2, v165
	v_add_u32_e32 v169, 0x10000, v165
	v_add_u32_e32 v248, 0x20000, v165
	v_add_u32_e32 v162, 0x30000, v165
	v_add_u32_e32 v163, 0x80000, v165
	v_add_u32_e32 v164, 0x90000, v165
	v_add_u32_e32 v174, 0xa0000, v165
	v_add_u32_e32 v175, 0xb0000, v165
	global_load_dwordx4 v[196:199], v165, s[46:47]
	global_load_dwordx4 v[200:203], v165, s[46:47] offset:64
	global_load_dwordx4 v[204:207], v169, s[46:47]
	global_load_dwordx4 v[208:211], v169, s[46:47] offset:64
	global_load_dwordx4 v[212:215], v248, s[46:47]
	global_load_dwordx4 v[216:219], v248, s[46:47] offset:64
	global_load_dwordx4 v[220:223], v162, s[46:47]
	global_load_dwordx4 v[224:227], v162, s[46:47] offset:64
	global_load_dwordx4 v[228:231], v163, s[46:47]
	global_load_dwordx4 v[232:235], v163, s[46:47] offset:64
	global_load_dwordx4 v[236:239], v164, s[46:47]
	global_load_dwordx4 v[240:243], v164, s[46:47] offset:64
	global_load_dwordx4 v[244:247], v174, s[46:47]
	v_readlane_b32 s74, v254, 12
	v_readlane_b32 s75, v254, 13
	v_readlane_b32 s74, v255, 22
	s_and_b64 vcc, exec, s[44:45]
	s_mov_b32 s66, s62
	s_mov_b32 s65, s64
	s_mov_b64 s[58:59], s[14:15]
	s_mov_b32 s94, 0x87ff
	v_readlane_b32 s75, v255, 23
	v_readlane_b32 s69, v254, 7
	s_waitcnt vmcnt(12)
	v_pk_fma_f32 v[126:127], v[126:127], v[130:131], v[196:197]
	v_pk_fma_f32 v[128:129], v[128:129], v[132:133], v[198:199]
	global_store_dwordx4 v165, v[126:129], s[40:41] sc1
	global_load_dwordx4 v[196:199], v174, s[46:47] offset:64
	s_waitcnt vmcnt(13)
	v_pk_fma_f32 v[98:99], v[98:99], v[158:159], v[200:201]
	v_pk_fma_f32 v[100:101], v[100:101], v[160:161], v[202:203]
	global_store_dwordx4 v165, v[98:101], s[40:41] offset:64 sc1
	global_load_dwordx4 v[200:203], v175, s[46:47]
	s_waitcnt vmcnt(14)
	v_pk_fma_f32 v[122:123], v[122:123], v[130:131], v[204:205]
	v_pk_fma_f32 v[124:125], v[124:125], v[132:133], v[206:207]
	global_store_dwordx4 v169, v[122:125], s[40:41] sc1
	global_load_dwordx4 v[204:207], v175, s[46:47] offset:64
	s_waitcnt vmcnt(15)
	v_pk_fma_f32 v[94:95], v[94:95], v[158:159], v[208:209]
	v_pk_fma_f32 v[96:97], v[96:97], v[160:161], v[210:211]
	global_store_dwordx4 v169, v[94:97], s[40:41] offset:64 sc1
	global_load_dwordx4 v[208:211], v165, s[46:47] offset:512
	s_waitcnt vmcnt(16)
	v_pk_fma_f32 v[118:119], v[118:119], v[130:131], v[212:213]
	v_pk_fma_f32 v[120:121], v[120:121], v[132:133], v[214:215]
	global_store_dwordx4 v248, v[118:121], s[40:41] sc1
	global_load_dwordx4 v[212:215], v165, s[46:47] offset:576
	s_waitcnt vmcnt(17)
	v_pk_fma_f32 v[90:91], v[90:91], v[158:159], v[216:217]
	v_pk_fma_f32 v[92:93], v[92:93], v[160:161], v[218:219]
	global_store_dwordx4 v248, v[90:93], s[40:41] offset:64 sc1
	global_load_dwordx4 v[216:219], v169, s[46:47] offset:512
	s_waitcnt vmcnt(18)
	v_pk_fma_f32 v[114:115], v[114:115], v[130:131], v[220:221]
	v_pk_fma_f32 v[116:117], v[116:117], v[132:133], v[222:223]
	global_store_dwordx4 v162, v[114:117], s[40:41] sc1
	global_load_dwordx4 v[220:223], v169, s[46:47] offset:576
	s_waitcnt vmcnt(19)
	v_pk_fma_f32 v[82:83], v[82:83], v[158:159], v[224:225]
	v_pk_fma_f32 v[84:85], v[84:85], v[160:161], v[226:227]
	global_store_dwordx4 v162, v[82:85], s[40:41] offset:64 sc1
	global_load_dwordx4 v[224:227], v248, s[46:47] offset:512
	s_waitcnt vmcnt(20)
	v_pk_fma_f32 v[110:111], v[110:111], v[130:131], v[228:229]
	v_pk_fma_f32 v[112:113], v[112:113], v[132:133], v[230:231]
	global_store_dwordx4 v163, v[110:113], s[40:41] sc1
	global_load_dwordx4 v[228:231], v248, s[46:47] offset:576
	s_waitcnt vmcnt(21)
	v_pk_fma_f32 v[78:79], v[78:79], v[158:159], v[232:233]
	v_pk_fma_f32 v[80:81], v[80:81], v[160:161], v[234:235]
	global_store_dwordx4 v163, v[78:81], s[40:41] offset:64 sc1
	global_load_dwordx4 v[232:235], v162, s[46:47] offset:512
	s_waitcnt vmcnt(22)
; #define PG8_WAIT_V(n) asm volatile("s_waitcnt vmcnt(" #n ")" ::: "memory")
; #define PG8_BAR __builtin_amdgcn_s_barrier()
;     ...
;         E(acc, cur.pm + pm0, cur.pn, wr, wc, fr, fq);
;         if (!has_next) break;
; #pragma unroll
;         for (int a = 0; a < 2; ++a)
; #pragma unroll
;             for (int b = 0; b < 2; ++b)
; #pragma unroll
;                 for (int m = 0; m < 4; ++m)
; #pragma unroll
;                     for (int n = 0; n < 2; ++n) acc[a][b][m][n] = (f32x4){0.f, 0.f, 0.f, 0.f};
;         cur = nxt; cA = nA; cB = nB; ++ui;
;     }
;     PG8_WAIT_V(0);
;     if (wr == 0) PG8_BAR;
;     PG8_BAR;
;     __device__ __forceinline__ void operator()(Acc& acc, int pm, int pn, int wr, int wc, int fr, int fq) const {
;     ...
; #pragma unroll
;         for (int bj = 0; bj < 2; ++bj)
; #pragma unroll
;             for (int n = 0; n < 2; ++n) {
;                 const f32x4 gv = *reinterpret_cast<const f32x4*>(gp + bj * 128 + n * 16);
; #pragma unroll
;                 for (int ai = 0; ai < 2; ++ai)
; #pragma unroll
;                     for (int m = 0; m < 4; ++m) {
;                         const size_t o = (size_t)(brow + ai * 128 + wr * 64 + m * 16 + fr - rsub) * DM + c0 + bj * 128 + n * 16;
;                         const f32x4 xi = *reinterpret_cast<const f32x4*>(xin + o);
;                         const f32x4 a = acc[ai][bj][m][n];
;                         f32x4 r = {xi[0] + gv[0] * a[0], xi[1] + gv[1] * a[1], xi[2] + gv[2] * a[2], xi[3] + gv[3] * a[3]};
;                         *reinterpret_cast<f32x4*>(xout + o) = r;
;                     }
	v_pk_fma_f32 v[106:107], v[106:107], v[130:131], v[236:237]
	v_pk_fma_f32 v[108:109], v[108:109], v[132:133], v[238:239]
	global_store_dwordx4 v164, v[106:109], s[40:41] sc1
	global_load_dwordx4 v[236:239], v162, s[46:47] offset:576
	s_waitcnt vmcnt(23)
	v_pk_fma_f32 v[70:71], v[70:71], v[158:159], v[240:241]
	v_pk_fma_f32 v[72:73], v[72:73], v[160:161], v[242:243]
	global_store_dwordx4 v164, v[70:73], s[40:41] offset:64 sc1
	global_load_dwordx4 v[240:243], v163, s[46:47] offset:512
	s_waitcnt vmcnt(24)
	v_pk_fma_f32 v[102:103], v[102:103], v[130:131], v[244:245]
	v_pk_fma_f32 v[104:105], v[104:105], v[132:133], v[246:247]
	global_store_dwordx4 v174, v[102:105], s[40:41] sc1
	global_load_dwordx4 v[244:247], v163, s[46:47] offset:576
	s_waitcnt vmcnt(24)
	v_pk_fma_f32 v[62:63], v[62:63], v[158:159], v[196:197]
	v_pk_fma_f32 v[64:65], v[64:65], v[160:161], v[198:199]
	global_store_dwordx4 v174, v[62:65], s[40:41] offset:64 sc1
	global_load_dwordx4 v[196:199], v164, s[46:47] offset:512
	s_waitcnt vmcnt(24)
	v_pk_fma_f32 v[86:87], v[86:87], v[130:131], v[200:201]
	v_pk_fma_f32 v[88:89], v[88:89], v[132:133], v[202:203]
	global_store_dwordx4 v175, v[86:89], s[40:41] sc1
	global_load_dwordx4 v[200:203], v164, s[46:47] offset:576
	s_waitcnt vmcnt(24)
	v_pk_fma_f32 v[54:55], v[54:55], v[158:159], v[204:205]
	v_pk_fma_f32 v[56:57], v[56:57], v[160:161], v[206:207]
	global_store_dwordx4 v175, v[54:57], s[40:41] offset:64 sc1
	global_load_dwordx4 v[204:207], v174, s[46:47] offset:512
	s_waitcnt vmcnt(24)
	v_pk_fma_f32 v[74:75], v[74:75], v[170:171], v[208:209]
	v_pk_fma_f32 v[76:77], v[76:77], v[172:173], v[210:211]
	global_store_dwordx4 v165, v[74:77], s[40:41] offset:512 sc1
	global_load_dwordx4 v[208:211], v174, s[46:47] offset:576
	s_waitcnt vmcnt(24)
	v_pk_fma_f32 v[46:47], v[46:47], v[192:193], v[212:213]
	v_pk_fma_f32 v[48:49], v[48:49], v[194:195], v[214:215]
	global_store_dwordx4 v165, v[46:49], s[40:41] offset:576 sc1
	global_load_dwordx4 v[212:215], v175, s[46:47] offset:512
	s_waitcnt vmcnt(24)
	v_pk_fma_f32 v[66:67], v[66:67], v[170:171], v[216:217]
	v_pk_fma_f32 v[68:69], v[68:69], v[172:173], v[218:219]
	global_store_dwordx4 v169, v[66:69], s[40:41] offset:512 sc1
	global_load_dwordx4 v[216:219], v175, s[46:47] offset:576
	s_waitcnt vmcnt(24)
	v_pk_fma_f32 v[38:39], v[38:39], v[192:193], v[220:221]
	v_pk_fma_f32 v[40:41], v[40:41], v[194:195], v[222:223]
	global_store_dwordx4 v169, v[38:41], s[40:41] offset:576 sc1
	s_waitcnt vmcnt(23)
	v_pk_fma_f32 v[58:59], v[58:59], v[170:171], v[224:225]
	v_pk_fma_f32 v[60:61], v[60:61], v[172:173], v[226:227]
	global_store_dwordx4 v248, v[58:61], s[40:41] offset:512 sc1
	s_waitcnt vmcnt(22)
	v_pk_fma_f32 v[30:31], v[30:31], v[192:193], v[228:229]
	v_pk_fma_f32 v[32:33], v[32:33], v[194:195], v[230:231]
	global_store_dwordx4 v248, v[30:33], s[40:41] offset:576 sc1
	s_waitcnt vmcnt(21)
	v_pk_fma_f32 v[50:51], v[50:51], v[170:171], v[232:233]
	v_pk_fma_f32 v[52:53], v[52:53], v[172:173], v[234:235]
	global_store_dwordx4 v162, v[50:53], s[40:41] offset:512 sc1
	s_waitcnt vmcnt(20)
	v_pk_fma_f32 v[22:23], v[22:23], v[192:193], v[236:237]
	v_pk_fma_f32 v[24:25], v[24:25], v[194:195], v[238:239]
	global_store_dwordx4 v162, v[22:25], s[40:41] offset:576 sc1
	s_waitcnt vmcnt(19)
	v_pk_fma_f32 v[42:43], v[42:43], v[170:171], v[240:241]
	v_pk_fma_f32 v[44:45], v[44:45], v[172:173], v[242:243]
	global_store_dwordx4 v163, v[42:45], s[40:41] offset:512 sc1
	s_waitcnt vmcnt(18)
	v_pk_fma_f32 v[14:15], v[14:15], v[192:193], v[244:245]
	v_pk_fma_f32 v[16:17], v[16:17], v[194:195], v[246:247]
	global_store_dwordx4 v163, v[14:17], s[40:41] offset:576 sc1
	s_waitcnt vmcnt(17)
	v_pk_fma_f32 v[34:35], v[34:35], v[170:171], v[196:197]
	v_pk_fma_f32 v[36:37], v[36:37], v[172:173], v[198:199]
	global_store_dwordx4 v164, v[34:37], s[40:41] offset:512 sc1
	s_waitcnt vmcnt(16)
	v_pk_fma_f32 v[10:11], v[10:11], v[192:193], v[200:201]
	v_pk_fma_f32 v[12:13], v[12:13], v[194:195], v[202:203]
	global_store_dwordx4 v164, v[10:13], s[40:41] offset:576 sc1
	s_waitcnt vmcnt(15)
	v_pk_fma_f32 v[26:27], v[26:27], v[170:171], v[204:205]
	v_pk_fma_f32 v[28:29], v[28:29], v[172:173], v[206:207]
	global_store_dwordx4 v174, v[26:29], s[40:41] offset:512 sc1
	s_waitcnt vmcnt(14)
	v_pk_fma_f32 v[6:7], v[6:7], v[192:193], v[208:209]
	v_pk_fma_f32 v[8:9], v[8:9], v[194:195], v[210:211]
	global_store_dwordx4 v174, v[6:9], s[40:41] offset:576 sc1
	s_waitcnt vmcnt(13)
	v_pk_fma_f32 v[18:19], v[18:19], v[170:171], v[212:213]
	v_pk_fma_f32 v[20:21], v[20:21], v[172:173], v[214:215]
	global_store_dwordx4 v175, v[18:21], s[40:41] offset:512 sc1
	s_waitcnt vmcnt(12)
	v_pk_fma_f32 v[2:3], v[2:3], v[192:193], v[216:217]
	v_pk_fma_f32 v[4:5], v[4:5], v[194:195], v[218:219]
	global_store_dwordx4 v175, v[2:5], s[40:41] offset:576 sc1
	s_mov_b64 s[40:41], s[12:13]
	s_mov_b64 s[0:1], 0x2000
	s_cbranch_vccz .LBB0_1238
	s_waitcnt vmcnt(0)
	s_cmpk_gt_u32 s4, 0xff
	s_cbranch_scc1 .LBB0_1249
	s_barrier

; __device__ __forceinline__ int otid() { int t = threadIdx.x; asm volatile("" : "+v"(t)); return t; }
;     const int tid_ = otid(); const int lane = tid_ & 63, w = tid_ >> 6;
;     if (bidx < 0) { bidx = blockIdx.x; nblk = gridDim.x; }
;     const int gw = bidx * 8 + w, nw = nblk * 8;
;     for (int r = rbeg + gw; r < nrows; r += nw) {
;         const float* xp = (r < T_LAT) ? xlat + (size_t)r * DM : xctx + (size_t)(r - T_LAT) * DM;
;         const int m = (r < T_LAT) ? (r >> 12) : 8;
;         const float* mv = p.modv + ((size_t)layer * 9 + m) * 6144 + shift_i * 1024;
;         f32x4 v[4];
;         float ss = 0.f;
; #pragma unroll
;         for (int i = 0; i < 4; ++i) {
;             v[i] = *reinterpret_cast<const f32x4*>(xp + (i * 64 + lane) * 4);
;             ss += v[i][0] * v[i][0] + v[i][1] * v[i][1] + v[i][2] * v[i][2] + v[i][3] * v[i][3];
;         }
; #pragma unroll
;         for (int o = 32; o >= 1; o >>= 1) ss += __shfl_xor(ss, o);
;         const float rstd = rsqrtf(ss * (1.0f / 1024.0f) + EPSV);
;         bf16_t* hp = p.hbuf + (size_t)r * DM;
; #pragma unroll
;         for (int i = 0; i < 4; ++i) {
;             const int col = (i * 64 + lane) * 4;
;             f32x4 gg = *reinterpret_cast<const f32x4*>(g + col);
.LBB0_1401:
	v_mov_b32_e32 v2, v176
	v_readlane_b32 s0, v253, 42
	v_ashrrev_i32_e32 v1, 6, v2
	s_nop 0
	v_add_u32_e32 v22, s0, v1
	s_mov_b32 s0, 0x8000
	v_cmp_gt_i32_e32 vcc, s0, v22
	s_and_saveexec_b64 s[10:11], vcc
	v_readlane_b32 s12, v254, 16
	v_readlane_b32 s13, v254, 17
	s_mov_b32 s4, s12
	v_readlane_b32 s12, v254, 6
	v_readlane_b32 s14, v254, 8
	v_readlane_b32 s15, v254, 9
	v_readlane_b32 s16, v254, 10
	v_readlane_b32 s17, v254, 11
	v_readlane_b32 s14, v254, 18
	v_readlane_b32 s16, v254, 22
	v_readlane_b32 s18, v254, 12
	v_readlane_b32 s19, v254, 13
	v_readlane_b32 s15, v254, 19
	v_readlane_b32 s17, v254, 23
	s_movk_i32 s7, 0x7fff
	s_movk_i32 s22, 0x6000
	s_mov_b64 s[28:29], 0x3000
	s_mov_b64 s[30:31], 0x4000
	v_readlane_b32 s13, v254, 7
	s_cbranch_execz .LBB0_1404
	v_readlane_b32 s12, v255, 28
	v_lshlrev_b32_e32 v1, 2, v2
	v_cmp_lt_i32_e32 vcc, v183, v182
	s_lshl_b32 s20, s12, 10
	v_readlane_b32 s60, v254, 42
	v_and_b32_e32 v4, 0xfc, v1
	v_cndmask_b32_e32 v1, v180, v183, vcc
	v_cmp_lt_i32_e32 vcc, v184, v182
	s_lshl_b64 s[0:1], s[20:21], 2
	v_readlane_b32 s62, v254, 44
	v_cndmask_b32_e32 v3, v180, v184, vcc
	v_cmp_lt_i32_e32 vcc, v185, v182
	v_readlane_b32 s63, v254, 45
	s_add_u32 s0, s62, s0
	v_lshlrev_b32_e32 v39, 2, v3
	v_cndmask_b32_e32 v3, v180, v185, vcc
	v_cmp_lt_i32_e32 vcc, v186, v182
	s_addc_u32 s1, s63, s1
	v_lshlrev_b32_e32 v6, 2, v4
	v_mov_b32_e32 v7, v0
	v_lshlrev_b32_e32 v44, 2, v3
	v_cndmask_b32_e32 v3, v180, v186, vcc
	v_cmp_lt_i32_e32 vcc, v187, v182
	v_ashrrev_i32_e32 v23, 31, v22
	v_lshl_add_u64 v[24:25], s[0:1], 0, v[6:7]
	v_lshlrev_b32_e32 v45, 2, v3
	v_cndmask_b32_e32 v3, v180, v187, vcc
	v_cmp_lt_i32_e32 vcc, v188, v182
	v_lshlrev_b64 v[12:13], 12, v[22:23]
	v_and_b32_e32 v5, 63, v2
	v_readlane_b32 s0, v254, 14
	v_lshlrev_b32_e32 v46, 2, v3
	v_cndmask_b32_e32 v3, v180, v188, vcc
	v_lshl_or_b32 v12, v5, 4, v12
	v_readlane_b32 s1, v254, 15
	v_lshlrev_b32_e32 v47, 2, v3
	v_lshlrev_b64 v[2:3], 11, v[22:23]
	v_lshl_add_u64 v[26:27], s[0:1], 0, v[12:13]
	v_readlane_b32 s0, v254, 20
	v_readlane_b32 s13, v255, 29
	v_readlane_b32 s58, v255, 22
	v_or_b32_e32 v6, 0x100, v4
	v_or_b32_e32 v8, 0x200, v4
	v_or_b32_e32 v10, 0x300, v4
	v_lshl_or_b32 v2, v5, 3, v2
	v_readlane_b32 s1, v254, 21
	v_readlane_b32 s59, v255, 23
	s_mul_i32 s20, s12, 9
	v_lshlrev_b32_e32 v1, 2, v1
	v_lshl_add_u64 v[28:29], s[0:1], 0, v[2:3]
	s_mov_b64 s[12:13], 0
	v_lshlrev_b32_e32 v30, 2, v4
	v_lshlrev_b32_e32 v32, 2, v6
	v_lshlrev_b32_e32 v34, 2, v8
	v_lshlrev_b32_e32 v36, 2, v10
	v_readlane_b32 s61, v254, 43
	v_readlane_b32 s64, v254, 46
	v_readlane_b32 s65, v254, 47
	v_readlane_b32 s66, v254, 48
	v_readlane_b32 s67, v254, 49
	v_readlane_b32 s68, v254, 50
	v_readlane_b32 s69, v254, 51
	v_readlane_b32 s70, v254, 52
	v_readlane_b32 s71, v254, 53
	v_readlane_b32 s72, v254, 54
	v_readlane_b32 s73, v254, 55
	v_readlane_b32 s74, v254, 56
	v_readlane_b32 s75, v254, 57
	global_load_dwordx4 v[200:203], v[24:25], off
	global_load_dwordx4 v[204:207], v[24:25], off offset:1024
	global_load_dwordx4 v[208:211], v[24:25], off offset:2048
	global_load_dwordx4 v[212:215], v[24:25], off offset:3072
;     ...
;     for (int r = rbeg + gw; r < nrows; r += nw) {
;         const float* xp = (r < T_LAT) ? xlat + (size_t)r * DM : xctx + (size_t)(r - T_LAT) * DM;
;         const int m = (r < T_LAT) ? (r >> 12) : 8;
;         const float* mv = p.modv + ((size_t)layer * 9 + m) * 6144 + shift_i * 1024;
;         f32x4 v[4];
;         float ss = 0.f;
; #pragma unroll
;         for (int i = 0; i < 4; ++i) {
;             v[i] = *reinterpret_cast<const f32x4*>(xp + (i * 64 + lane) * 4);
;             ss += v[i][0] * v[i][0] + v[i][1] * v[i][1] + v[i][2] * v[i][2] + v[i][3] * v[i][3];
;         }
; #pragma unroll
;         for (int o = 32; o >= 1; o >>= 1) ss += __shfl_xor(ss, o);
;         const float rstd = rsqrtf(ss * (1.0f / 1024.0f) + EPSV);
;         bf16_t* hp = p.hbuf + (size_t)r * DM;
; #pragma unroll
;         for (int i = 0; i < 4; ++i) {
;             const int col = (i * 64 + lane) * 4;
;             f32x4 gg = *reinterpret_cast<const f32x4*>(g + col);
;             f32x4 sh = *reinterpret_cast<const f32x4*>(mv + col);
;             f32x4 sc = *reinterpret_cast<const f32x4*>(mv + 1024 + col);
;             float o0 = v[i][0] * rstd * gg[0] * (1.f + sc[0]) + sh[0];
;             float o1 = v[i][1] * rstd * gg[1] * (1.f + sc[1]) + sh[1];
;             float o2 = v[i][2] * rstd * gg[2] * (1.f + sc[2]) + sh[2];
;             float o3 = v[i][3] * rstd * gg[3] * (1.f + sc[3]) + sh[3];
;             u32x2 o = {pack2(o0, o1), pack2(o2, o3)};
;             *reinterpret_cast<u32x2*>(hp + col) = o;
;         }
.LBB0_1403:
	global_load_dwordx4 v[14:17], v[26:27], off offset:-2048
	global_load_dwordx4 v[10:13], v[26:27], off offset:-1024
	global_load_dwordx4 v[6:9], v[26:27], off
	global_load_dwordx4 v[2:5], v[26:27], off offset:1024
	v_ashrrev_i32_e32 v192, 12, v22
	v_ashrrev_i32_e32 v193, 31, v192
	v_lshl_add_u64 v[192:193], v[192:193], 0, s[20:21]
	v_mov_b64_e32 v[194:195], s[18:19]
	v_mad_u64_u32 v[18:19], s[0:1], v192, s22, v[194:195]
	v_mad_i32_i24 v19, v193, s22, v19
	v_mov_b32_e32 v31, v0
	v_mov_b32_e32 v33, v0
	v_mov_b32_e32 v35, v0
	v_mov_b32_e32 v37, v0
	v_add_u32_e32 v22, s4, v22
	v_lshl_add_u64 v[42:43], v[18:19], 0, s[30:31]
	v_lshl_add_u64 v[40:41], v[18:19], 0, s[28:29]
	v_lshl_add_u64 v[192:193], v[40:41], 0, v[30:31]
	v_lshl_add_u64 v[194:195], v[42:43], 0, v[30:31]
	global_load_dwordx4 v[216:219], v[192:193], off
	global_load_dwordx4 v[220:223], v[194:195], off
	v_lshl_add_u64 v[192:193], v[40:41], 0, v[32:33]
	v_lshl_add_u64 v[194:195], v[42:43], 0, v[32:33]
	global_load_dwordx4 v[224:227], v[192:193], off
	global_load_dwordx4 v[228:231], v[194:195], off
	v_lshl_add_u64 v[192:193], v[40:41], 0, v[34:35]
	v_lshl_add_u64 v[194:195], v[42:43], 0, v[34:35]
	global_load_dwordx4 v[232:235], v[192:193], off
	global_load_dwordx4 v[236:239], v[194:195], off
	v_lshl_add_u64 v[192:193], v[40:41], 0, v[36:37]
	v_lshl_add_u64 v[194:195], v[42:43], 0, v[36:37]
	global_load_dwordx4 v[240:243], v[192:193], off
	global_load_dwordx4 v[244:247], v[194:195], off
	v_lshl_add_u64 v[26:27], v[26:27], 0, s[14:15]
	s_waitcnt vmcnt(8)
	v_mov_b32_e32 v194, v15
	v_mov_b32_e32 v195, v11
	v_mov_b32_e32 v192, v14
	v_mov_b32_e32 v193, v10
	v_pk_mul_f32 v[194:195], v[194:195], v[194:195]
	s_nop 0
	v_pk_fma_f32 v[192:193], v[192:193], v[192:193], v[194:195]
	v_mov_b32_e32 v194, v16
	v_mov_b32_e32 v195, v12
	v_pk_fma_f32 v[192:193], v[194:195], v[194:195], v[192:193]
	v_mov_b32_e32 v194, v17
	v_mov_b32_e32 v195, v13
	v_pk_fma_f32 v[20:21], v[194:195], v[194:195], v[192:193]
	v_add_f32_e32 v20, v20, v21
	v_mov_b32_e32 v42, v7
	v_mov_b32_e32 v43, v3
	v_mov_b32_e32 v40, v6
	v_mov_b32_e32 v41, v2
	v_pk_mul_f32 v[42:43], v[42:43], v[42:43]
	s_nop 0
	v_pk_fma_f32 v[40:41], v[40:41], v[40:41], v[42:43]
	v_mov_b32_e32 v42, v8
	v_mov_b32_e32 v43, v4
	v_pk_fma_f32 v[40:41], v[42:43], v[42:43], v[40:41]
	v_mov_b32_e32 v42, v9
	v_mov_b32_e32 v43, v5
	v_pk_fma_f32 v[40:41], v[42:43], v[42:43], v[40:41]
	v_add_f32_e32 v20, v20, v40
	v_add_f32_e32 v20, v20, v41
	ds_bpermute_b32 v21, v1, v20
	s_waitcnt lgkmcnt(0)
	v_add_f32_e32 v20, v20, v21
	ds_bpermute_b32 v21, v39, v20
	s_waitcnt lgkmcnt(0)
	v_add_f32_e32 v20, v20, v21
	ds_bpermute_b32 v21, v44, v20
	s_waitcnt lgkmcnt(0)
	v_add_f32_e32 v20, v20, v21
	ds_bpermute_b32 v21, v45, v20
	s_waitcnt lgkmcnt(0)
	v_add_f32_e32 v20, v20, v21
	ds_bpermute_b32 v21, v46, v20
	s_waitcnt lgkmcnt(0)
	v_add_f32_e32 v20, v20, v21
	ds_bpermute_b32 v21, v47, v20
	s_waitcnt lgkmcnt(0)
	v_add_f32_e32 v20, v20, v21
	v_fmamk_f32 v20, v20, 0x3a800000, v177
	v_cmp_gt_f32_e32 vcc, s93, v20
	v_mul_f32_e32 v21, 0x4b800000, v20
	s_nop 0
	v_cndmask_b32_e32 v20, v20, v21, vcc
	v_rsq_f32_e32 v20, v20
	s_nop 0
	v_mul_f32_e32 v21, 0x45800000, v20
	v_cndmask_b32_e32 v38, v20, v21, vcc
	v_pk_mul_f32 v[14:15], v[14:15], v[38:39] op_sel_hi:[1,0]
	v_pk_mul_f32 v[16:17], v[16:17], v[38:39] op_sel_hi:[1,0]
	v_pk_mul_f32 v[10:11], v[10:11], v[38:39] op_sel_hi:[1,0]
	v_pk_mul_f32 v[12:13], v[12:13], v[38:39] op_sel_hi:[1,0]
	v_pk_mul_f32 v[6:7], v[6:7], v[38:39] op_sel_hi:[1,0]
	v_pk_mul_f32 v[8:9], v[8:9], v[38:39] op_sel_hi:[1,0]
	v_pk_mul_f32 v[2:3], v[2:3], v[38:39] op_sel_hi:[1,0]
	v_pk_mul_f32 v[4:5], v[4:5], v[38:39] op_sel_hi:[1,0]
	v_cmp_lt_i32_e32 vcc, s7, v22
	s_or_b64 s[12:13], vcc, s[12:13]
	s_waitcnt vmcnt(0)
	v_pk_mul_f32 v[14:15], v[200:201], v[14:15]
	v_pk_add_f32 v[18:19], v[220:221], 1.0 op_sel_hi:[1,0]
	v_pk_mul_f32 v[16:17], v[202:203], v[16:17]
	v_pk_fma_f32 v[14:15], v[18:19], v[14:15], v[216:217]
	v_pk_add_f32 v[18:19], v[222:223], 1.0 op_sel_hi:[1,0]
	v_cvt_pk_bf16_f32 v14, v14, v15
	v_pk_fma_f32 v[16:17], v[18:19], v[16:17], v[218:219]
	s_nop 0
	v_cvt_pk_bf16_f32 v15, v16, v17
	global_store_dwordx2 v[28:29], v[14:15], off offset:-1024
	v_pk_mul_f32 v[10:11], v[204:205], v[10:11]
	v_pk_add_f32 v[18:19], v[228:229], 1.0 op_sel_hi:[1,0]
	v_pk_mul_f32 v[12:13], v[206:207], v[12:13]
	v_pk_fma_f32 v[10:11], v[18:19], v[10:11], v[224:225]
	v_pk_add_f32 v[18:19], v[230:231], 1.0 op_sel_hi:[1,0]
	v_cvt_pk_bf16_f32 v10, v10, v11
	v_pk_fma_f32 v[12:13], v[18:19], v[12:13], v[226:227]
	s_nop 0
	v_cvt_pk_bf16_f32 v11, v12, v13
	global_store_dwordx2 v[28:29], v[10:11], off offset:-512
	v_pk_mul_f32 v[6:7], v[208:209], v[6:7]
	v_pk_add_f32 v[18:19], v[236:237], 1.0 op_sel_hi:[1,0]
	v_pk_mul_f32 v[8:9], v[210:211], v[8:9]
	v_pk_fma_f32 v[6:7], v[18:19], v[6:7], v[232:233]
	v_pk_add_f32 v[18:19], v[238:239], 1.0 op_sel_hi:[1,0]
	v_cvt_pk_bf16_f32 v6, v6, v7
	v_pk_fma_f32 v[8:9], v[18:19], v[8:9], v[234:235]
	s_nop 0
	v_cvt_pk_bf16_f32 v7, v8, v9
	global_store_dwordx2 v[28:29], v[6:7], off
	v_pk_mul_f32 v[2:3], v[212:213], v[2:3]
	v_pk_add_f32 v[18:19], v[244:245], 1.0 op_sel_hi:[1,0]
	v_pk_mul_f32 v[4:5], v[214:215], v[4:5]
	v_pk_fma_f32 v[2:3], v[18:19], v[2:3], v[240:241]
	v_pk_add_f32 v[18:19], v[246:247], 1.0 op_sel_hi:[1,0]
	v_cvt_pk_bf16_f32 v2, v2, v3
	v_pk_fma_f32 v[4:5], v[18:19], v[4:5], v[242:243]
	s_nop 0
	v_cvt_pk_bf16_f32 v3, v4, v5
	global_store_dwordx2 v[28:29], v[2:3], off offset:512
	v_lshl_add_u64 v[28:29], v[28:29], 0, s[16:17]
	s_andn2_b64 exec, exec, s[12:13]
	s_cbranch_execnz .LBB0_1403

; #define PG8_STAGE(bufoff, gbase) do { _Pragma("unroll") for (int _i = 0; _i < 2; ++_i) \
;         __builtin_amdgcn_global_load_lds((const unsigned*)((const char*)(gbase) + voff[_i]), (LAS unsigned*)(lds + (bufoff) + ldsw + _i * 8192), 16, 0, 0); } while (0)
; #define PG8_WAIT_V(n) asm volatile("s_waitcnt vmcnt(" #n ")" ::: "memory")
; #define PG8_BAR __builtin_amdgcn_s_barrier()
;     ...
;     f32x4 acc[2][2][4][2];
; #pragma unroll
;     for (int a = 0; a < 2; ++a)
; #pragma unroll
;         for (int b = 0; b < 2; ++b)
; #pragma unroll
;             for (int m = 0; m < 4; ++m)
; #pragma unroll
;                 for (int n = 0; n < 2; ++n) acc[a][b][m][n] = (f32x4){0.f, 0.f, 0.f, 0.f};
;     bf16x8 At[4][2], B0[2][2], B1[2][2];
;     const char* cA = (const char*)gA + (size_t)cur.pm * tstep; const char* cB = (const char*)gBt + (size_t)cur.pn * tstep;
;     PG8_STAGE(PG8_SB(0, 0), cB); PG8_STAGE(PG8_SA(0, 0), cA); PG8_STAGE(PG8_SB(0, 1), cB + hstep); PG8_STAGE(PG8_SA(0, 1), cA + hstep);
;     if (wr == 1) PG8_BAR;
;     PG8_WAIT_V(4); PG8_BAR;
;     PG8_STAGE(PG8_SB(1, 0), cB + kstep); PG8_STAGE(PG8_SA(1, 0), cA + kstep); PG8_STAGE(PG8_SB(1, 1), cB + hstep + kstep);
;     PG8_WAIT_V(6); PG8_BAR;
.LBB0_1407:
	v_mov_b32_e32 v131, v0
	v_mov_b32_e32 v133, v0
	v_lshl_add_u64 v[10:11], s[10:11], 0, v[130:131]
	v_lshl_add_u64 v[18:19], s[14:15], 0, v[130:131]
	v_lshl_add_u64 v[20:21], s[14:15], 0, v[132:133]
	s_mov_b64 s[14:15], 0x80
	v_lshl_add_u64 v[12:13], s[10:11], 0, v[132:133]
	v_and_b32_e32 v9, 15, v7
	s_add_i32 m0, s17, 0x18000
	v_lshl_add_u64 v[10:11], v[10:11], 0, s[14:15]
	v_lshl_add_u64 v[14:15], s[12:13], 0, v[130:131]
	v_lshl_or_b32 v1, s28, 6, v9
	s_lshl_b32 s0, s28, 13
	s_waitcnt vmcnt(4)
	s_barrier
	global_load_lds_dwordx4 v[10:11], off
	v_lshl_add_u64 v[10:11], v[12:13], 0, s[14:15]
	s_add_i32 m0, s17, 0x1a000
	s_add_i32 s28, s17, 0x8000
	v_lshl_add_u64 v[16:17], s[12:13], 0, v[132:133]
	global_load_lds_dwordx4 v[10:11], off
	v_lshl_add_u64 v[10:11], v[14:15], 0, s[14:15]
	s_mov_b32 m0, s28
	s_add_i32 s29, s17, 0xa000
	global_load_lds_dwordx4 v[10:11], off
	v_lshl_add_u64 v[10:11], v[16:17], 0, s[14:15]
	s_mov_b32 m0, s29
	v_bfe_u32 v154, v7, 4, 2
	global_load_lds_dwordx4 v[10:11], off
	s_add_i32 m0, s17, 0x1c000
	v_lshl_add_u64 v[10:11], v[18:19], 0, s[14:15]
	global_load_lds_dwordx4 v[10:11], off
	v_lshl_add_u64 v[10:11], v[20:21], 0, s[14:15]
	s_add_i32 m0, s17, 0x1e000
	v_lshlrev_b32_e32 v22, 4, v154
	global_load_lds_dwordx4 v[10:11], off
	v_lshlrev_b32_e32 v7, 2, v7
	v_lshl_or_b32 v9, v9, 6, v22
	v_and_b32_e32 v7, 32, v7
	v_bitop3_b32 v22, v9, s0, v7 bitop3:0xde
	s_lshl_b32 s0, s23, 5
	s_and_b32 s23, s0, 0x60
	s_lshl_b32 s0, s23, 7
	v_bitop3_b32 v155, v9, s0, v7 bitop3:0xde
	v_readlane_b32 s0, v254, 25
	v_readlane_b32 s31, v254, 24
	s_lshr_b32 s22, s5, 6
	s_mul_i32 s0, s0, s5
	s_mul_hi_u32 s1, s31, s5
	s_add_i32 s30, s22, -2
	s_add_i32 s1, s1, s0
	s_mul_i32 s0, s31, s5
	v_add_u32_e32 v2, v4, v2
	s_add_u32 s0, s52, s0
	v_add_lshl_u32 v2, v2, v3, 1
	v_mov_b32_e32 v3, v0
	s_addc_u32 s1, s53, s1
	v_lshl_add_u64 v[150:151], s[0:1], 0, v[2:3]
	v_add_u32_e32 v2, v8, v5
	s_waitcnt vmcnt(6)
	v_add_lshl_u32 v2, v2, v6, 1
	v_lshl_add_u64 v[152:153], s[0:1], 0, v[2:3]
	v_mov_b32_e32 v2, 0
	s_mov_b32 s5, 0
	v_add_u32_e32 v156, 0, v22
	v_mov_b32_e32 v3, v2
	v_mov_b32_e32 v4, v2
	v_mov_b32_e32 v5, v2
	v_mov_b32_e32 v18, v2
	v_mov_b32_e32 v19, v2
	v_mov_b32_e32 v20, v2
	v_mov_b32_e32 v21, v2
	v_mov_b32_e32 v6, v2
	v_mov_b32_e32 v7, v2
	v_mov_b32_e32 v8, v2
	v_mov_b32_e32 v9, v2
	v_mov_b32_e32 v26, v2
	v_mov_b32_e32 v27, v2
	v_mov_b32_e32 v28, v2
	v_mov_b32_e32 v29, v2
	v_mov_b32_e32 v10, v2
	v_mov_b32_e32 v11, v2
	v_mov_b32_e32 v12, v2
	v_mov_b32_e32 v13, v2
	v_mov_b32_e32 v34, v2
	v_mov_b32_e32 v35, v2
	v_mov_b32_e32 v36, v2
	v_mov_b32_e32 v37, v2
	v_mov_b32_e32 v14, v2
	v_mov_b32_e32 v15, v2
	v_mov_b32_e32 v16, v2
	v_mov_b32_e32 v17, v2
	v_mov_b32_e32 v42, v2
	v_mov_b32_e32 v43, v2
	v_mov_b32_e32 v44, v2
	v_mov_b32_e32 v45, v2
	v_mov_b32_e32 v54, v2
	v_mov_b32_e32 v55, v2
	v_mov_b32_e32 v56, v2
	v_mov_b32_e32 v57, v2
	v_mov_b32_e32 v86, v2
	v_mov_b32_e32 v87, v2
	v_mov_b32_e32 v88, v2
	v_mov_b32_e32 v89, v2
	v_mov_b32_e32 v62, v2
	v_mov_b32_e32 v63, v2
	v_mov_b32_e32 v64, v2
	v_mov_b32_e32 v65, v2
	v_mov_b32_e32 v102, v2
	v_mov_b32_e32 v103, v2
	v_mov_b32_e32 v104, v2
	v_mov_b32_e32 v105, v2
	v_mov_b32_e32 v70, v2
	v_mov_b32_e32 v71, v2
	v_mov_b32_e32 v72, v2
	v_mov_b32_e32 v73, v2
	v_mov_b32_e32 v106, v2
	v_mov_b32_e32 v107, v2
	v_mov_b32_e32 v108, v2
	v_mov_b32_e32 v109, v2
	v_mov_b32_e32 v78, v2
	v_mov_b32_e32 v79, v2
	v_mov_b32_e32 v80, v2
	v_mov_b32_e32 v81, v2
	v_mov_b32_e32 v110, v2
	v_mov_b32_e32 v111, v2
	v_mov_b32_e32 v112, v2
	v_mov_b32_e32 v113, v2
	v_mov_b32_e32 v22, v2
	v_mov_b32_e32 v23, v2
	v_mov_b32_e32 v24, v2
	v_mov_b32_e32 v25, v2
	v_mov_b32_e32 v50, v2
	v_mov_b32_e32 v51, v2
	v_mov_b32_e32 v52, v2
	v_mov_b32_e32 v53, v2
	v_mov_b32_e32 v30, v2
	v_mov_b32_e32 v31, v2
	v_mov_b32_e32 v32, v2
	v_mov_b32_e32 v33, v2
	v_mov_b32_e32 v58, v2
	v_mov_b32_e32 v59, v2
	v_mov_b32_e32 v60, v2
	v_mov_b32_e32 v61, v2
	v_mov_b32_e32 v38, v2
	v_mov_b32_e32 v39, v2
	v_mov_b32_e32 v40, v2
	v_mov_b32_e32 v41, v2
	v_mov_b32_e32 v66, v2
	v_mov_b32_e32 v67, v2
	v_mov_b32_e32 v68, v2
	v_mov_b32_e32 v69, v2
	v_mov_b32_e32 v46, v2
	v_mov_b32_e32 v47, v2
	v_mov_b32_e32 v48, v2
	v_mov_b32_e32 v49, v2
	v_mov_b32_e32 v74, v2
	v_mov_b32_e32 v75, v2
	v_mov_b32_e32 v76, v2
	v_mov_b32_e32 v77, v2
	v_mov_b32_e32 v82, v2
	v_mov_b32_e32 v83, v2
	v_mov_b32_e32 v84, v2
	v_mov_b32_e32 v85, v2
	v_mov_b32_e32 v114, v2
	v_mov_b32_e32 v115, v2
	v_mov_b32_e32 v116, v2
	v_mov_b32_e32 v117, v2
	v_mov_b32_e32 v90, v2
	v_mov_b32_e32 v91, v2
	v_mov_b32_e32 v92, v2
	v_mov_b32_e32 v93, v2
	v_mov_b32_e32 v118, v2
	v_mov_b32_e32 v119, v2
	v_mov_b32_e32 v120, v2
	v_mov_b32_e32 v121, v2
	v_mov_b32_e32 v94, v2
	v_mov_b32_e32 v95, v2
	v_mov_b32_e32 v96, v2
	v_mov_b32_e32 v97, v2
	v_mov_b32_e32 v122, v2
	v_mov_b32_e32 v123, v2
	v_mov_b32_e32 v124, v2
	v_mov_b32_e32 v125, v2
	v_mov_b32_e32 v98, v2
	v_mov_b32_e32 v99, v2
	v_mov_b32_e32 v100, v2
	v_mov_b32_e32 v101, v2
	v_mov_b32_e32 v126, v2
	v_mov_b32_e32 v127, v2
	v_mov_b32_e32 v128, v2
	v_mov_b32_e32 v129, v2
	s_barrier
; #define PG8_STAGE(bufoff, gbase) do { _Pragma("unroll") for (int _i = 0; _i < 2; ++_i) \
;         __builtin_amdgcn_global_load_lds((const unsigned*)((const char*)(gbase) + voff[_i]), (LAS unsigned*)(lds + (bufoff) + ldsw + _i * 8192), 16, 0, 0); } while (0)
; #define PG8_LDA(dst, b, h) do { _Pragma("unroll") for (int m = 0; m < 4; ++m) _Pragma("unroll") for (int k = 0; k < 2; ++k) dst[m][k] = *(const LAS bf16x8*)(lds + PG8_SA(b, h) + aoff + m * 2048 + k * 1024); } while (0)
; #define PG8_LDB(dst, b, h) do { _Pragma("unroll") for (int n = 0; n < 2; ++n) _Pragma("unroll") for (int k = 0; k < 2; ++k) dst[n][k] = *(const LAS bf16x8*)(lds + PG8_SB(b, h) + boff + n * 2048 + k * 1024); } while (0)
; #define PG8_WAIT_L(n) asm volatile("s_waitcnt lgkmcnt(" #n ")" ::: "memory")
; #define PG8_BAR __builtin_amdgcn_s_barrier()
; #define PG8_SCHED __builtin_amdgcn_sched_barrier(0)
;     ...
;         for (int t = 0; t < nt; t += 2) {
;             const bool last = (t == nt - 2);
;             const char* a1 = cA + (size_t)(t + 1) * kstep;
;             const char* a2 = last ? nA : cA + (size_t)(t + 2) * kstep; const char* b2 = last ? nB : cB + (size_t)(t + 2) * kstep;
;             const char* a3 = a2 + kstep; const char* b3 = b2 + kstep;
;             PG8_LDB(B0, 0, 0); PG8_SCHED; PG8_LDA(At, 0, 0); PG8_STAGE(PG8_SA(1, 1), a1 + hstep);
;             PG8_WAIT_L(8); PG8_BAR; PG8_WAIT_L(0); PG8_MMA(0, 0, At, B0); PG8_BAR; PG8_SCHED;
;             PG8_LDB(B1, 0, 1); PG8_STAGE(PG8_SB(0, 0), b2);
;             PG8_BAR; PG8_WAIT_L(0); PG8_MMA(0, 1, At, B1); PG8_BAR;
;             PG8_LDA(At, 0, 1); PG8_STAGE(PG8_SA(0, 0), a2);
;             PG8_BAR; PG8_WAIT_L(0); PG8_MMA(1, 0, At, B0); PG8_BAR; PG8_SCHED;
.LBB0_1408:
	s_add_i32 s31, s5, 2
	s_add_u32 s0, s14, 0x80
	s_addc_u32 s1, s15, 0
	s_cmp_lg_u32 s30, s5
	s_cselect_b32 s0, s0, 0
	s_cselect_b32 s1, s1, 0
	s_add_u32 s40, s12, s0
	s_addc_u32 s41, s13, s1
	s_add_i32 s5, 0, 0x10000
	v_add_u32_e32 v157, s5, v155
	ds_read_b128 v[158:161], v157
	ds_read_b128 v[162:165], v157 offset:1024
	ds_read_b128 v[166:169], v157 offset:2048
	ds_read_b128 v[170:173], v157 offset:3072
	s_add_u32 s44, s10, s0
	s_addc_u32 s45, s11, s1
	v_lshl_add_u64 v[174:175], v[150:151], 0, s[14:15]
	s_add_i32 m0, s17, 0xc000
	ds_read_b128 v[194:197], v156
	ds_read_b128 v[198:201], v156 offset:1024
	ds_read_b128 v[202:205], v156 offset:2048
	ds_read_b128 v[206:209], v156 offset:3072
	ds_read_b128 v[210:213], v156 offset:4096
	ds_read_b128 v[214:217], v156 offset:5120
	ds_read_b128 v[218:221], v156 offset:6144
	ds_read_b128 v[222:225], v156 offset:7168
	global_load_lds_dwordx4 v[174:175], off
	v_lshl_add_u64 v[174:175], v[152:153], 0, s[14:15]
	s_add_i32 m0, s17, 0xe000
	s_nop 0
	global_load_lds_dwordx4 v[174:175], off
	s_waitcnt lgkmcnt(8)
	s_barrier
	s_waitcnt lgkmcnt(0)
	s_setprio 1
	s_waitcnt lgkmcnt(0)
	v_mfma_f32_16x16x32_bf16 v[126:129], v[158:161], v[194:197], v[126:129]
	v_mfma_f32_16x16x32_bf16 v[98:101], v[166:169], v[194:197], v[98:101]
	v_mfma_f32_16x16x32_bf16 v[122:125], v[158:161], v[202:205], v[122:125]
	v_mfma_f32_16x16x32_bf16 v[94:97], v[166:169], v[202:205], v[94:97]
	v_mfma_f32_16x16x32_bf16 v[118:121], v[158:161], v[210:213], v[118:121]
	v_mfma_f32_16x16x32_bf16 v[90:93], v[166:169], v[210:213], v[90:93]
	v_mfma_f32_16x16x32_bf16 v[114:117], v[158:161], v[218:221], v[114:117]
	v_mfma_f32_16x16x32_bf16 v[82:85], v[166:169], v[218:221], v[82:85]
	v_mfma_f32_16x16x32_bf16 v[126:129], v[162:165], v[198:201], v[126:129]
	v_mfma_f32_16x16x32_bf16 v[98:101], v[170:173], v[198:201], v[98:101]
	v_mfma_f32_16x16x32_bf16 v[122:125], v[162:165], v[206:209], v[122:125]
	v_mfma_f32_16x16x32_bf16 v[94:97], v[170:173], v[206:209], v[94:97]
	v_mfma_f32_16x16x32_bf16 v[118:121], v[162:165], v[214:217], v[118:121]
	v_mfma_f32_16x16x32_bf16 v[90:93], v[170:173], v[214:217], v[90:93]
	v_mfma_f32_16x16x32_bf16 v[114:117], v[162:165], v[222:225], v[114:117]
	v_mfma_f32_16x16x32_bf16 v[82:85], v[170:173], v[222:225], v[82:85]
	s_setprio 0
	s_barrier
	s_add_i32 s36, 0, 0x14000
	s_add_i32 s0, s5, s16
	v_add_u32_e32 v157, s36, v155
	v_lshl_add_u64 v[174:175], s[44:45], 0, v[130:131]
	s_mov_b32 m0, s0
	ds_read_b128 v[226:229], v157
	ds_read_b128 v[230:233], v157 offset:1024
	ds_read_b128 v[234:237], v157 offset:2048
	ds_read_b128 v[238:241], v157 offset:3072
	global_load_lds_dwordx4 v[174:175], off
	v_lshl_add_u64 v[192:193], s[44:45], 0, v[132:133]
	s_add_i32 m0, s0, 0x2000
	s_nop 0
	global_load_lds_dwordx4 v[192:193], off
	s_barrier
	s_waitcnt lgkmcnt(0)
	s_setprio 1
	s_waitcnt lgkmcnt(0)
	v_mfma_f32_16x16x32_bf16 v[74:77], v[226:229], v[194:197], v[74:77]
	v_mfma_f32_16x16x32_bf16 v[46:49], v[234:237], v[194:197], v[46:49]
	v_mfma_f32_16x16x32_bf16 v[66:69], v[226:229], v[202:205], v[66:69]
	v_mfma_f32_16x16x32_bf16 v[38:41], v[234:237], v[202:205], v[38:41]
	v_mfma_f32_16x16x32_bf16 v[58:61], v[226:229], v[210:213], v[58:61]
	v_mfma_f32_16x16x32_bf16 v[30:33], v[234:237], v[210:213], v[30:33]
	v_mfma_f32_16x16x32_bf16 v[50:53], v[226:229], v[218:221], v[50:53]
	v_mfma_f32_16x16x32_bf16 v[22:25], v[234:237], v[218:221], v[22:25]
	v_mfma_f32_16x16x32_bf16 v[74:77], v[230:233], v[198:201], v[74:77]
	v_mfma_f32_16x16x32_bf16 v[46:49], v[238:241], v[198:201], v[46:49]
	v_mfma_f32_16x16x32_bf16 v[66:69], v[230:233], v[206:209], v[66:69]
	v_mfma_f32_16x16x32_bf16 v[38:41], v[238:241], v[206:209], v[38:41]
	v_mfma_f32_16x16x32_bf16 v[58:61], v[230:233], v[214:217], v[58:61]
	v_mfma_f32_16x16x32_bf16 v[30:33], v[238:241], v[214:217], v[30:33]
	v_mfma_f32_16x16x32_bf16 v[50:53], v[230:233], v[222:225], v[50:53]
	v_mfma_f32_16x16x32_bf16 v[22:25], v[238:241], v[222:225], v[22:25]
	s_setprio 0
	s_mov_b32 m0, s17
	v_lshl_add_u64 v[242:243], s[40:41], 0, v[130:131]
	s_barrier
	ds_read_b128 v[194:197], v156 offset:16384
	ds_read_b128 v[198:201], v156 offset:17408
	ds_read_b128 v[202:205], v156 offset:18432
	ds_read_b128 v[206:209], v156 offset:19456
	ds_read_b128 v[210:213], v156 offset:20480
	ds_read_b128 v[214:217], v156 offset:21504
	ds_read_b128 v[218:221], v156 offset:22528
	ds_read_b128 v[222:225], v156 offset:23552
	global_load_lds_dwordx4 v[242:243], off
	v_lshl_add_u64 v[244:245], s[40:41], 0, v[132:133]
	s_mov_b32 m0, s18
	s_nop 0
	global_load_lds_dwordx4 v[244:245], off
	s_barrier
	s_waitcnt lgkmcnt(0)
	s_setprio 1
	s_waitcnt lgkmcnt(0)
	v_mfma_f32_16x16x32_bf16 v[110:113], v[158:161], v[194:197], v[110:113]
	v_mfma_f32_16x16x32_bf16 v[78:81], v[166:169], v[194:197], v[78:81]
	v_mfma_f32_16x16x32_bf16 v[106:109], v[158:161], v[202:205], v[106:109]
	v_mfma_f32_16x16x32_bf16 v[70:73], v[166:169], v[202:205], v[70:73]
	v_mfma_f32_16x16x32_bf16 v[102:105], v[158:161], v[210:213], v[102:105]
	v_mfma_f32_16x16x32_bf16 v[62:65], v[166:169], v[210:213], v[62:65]
	v_mfma_f32_16x16x32_bf16 v[86:89], v[158:161], v[218:221], v[86:89]
	v_mfma_f32_16x16x32_bf16 v[54:57], v[166:169], v[218:221], v[54:57]
	v_mfma_f32_16x16x32_bf16 v[110:113], v[162:165], v[198:201], v[110:113]
	v_mfma_f32_16x16x32_bf16 v[78:81], v[170:173], v[198:201], v[78:81]
	v_mfma_f32_16x16x32_bf16 v[106:109], v[162:165], v[206:209], v[106:109]
	v_mfma_f32_16x16x32_bf16 v[70:73], v[170:173], v[206:209], v[70:73]
	v_mfma_f32_16x16x32_bf16 v[102:105], v[162:165], v[214:217], v[102:105]
	v_mfma_f32_16x16x32_bf16 v[62:65], v[170:173], v[214:217], v[62:65]
	v_mfma_f32_16x16x32_bf16 v[86:89], v[162:165], v[222:225], v[86:89]
	v_mfma_f32_16x16x32_bf16 v[54:57], v[170:173], v[222:225], v[54:57]
	s_setprio 0
	s_barrier
; #define PG8_STAGE(bufoff, gbase) do { _Pragma("unroll") for (int _i = 0; _i < 2; ++_i) \
;         __builtin_amdgcn_global_load_lds((const unsigned*)((const char*)(gbase) + voff[_i]), (LAS unsigned*)(lds + (bufoff) + ldsw + _i * 8192), 16, 0, 0); } while (0)
; #define PG8_LDA(dst, b, h) do { _Pragma("unroll") for (int m = 0; m < 4; ++m) _Pragma("unroll") for (int k = 0; k < 2; ++k) dst[m][k] = *(const LAS bf16x8*)(lds + PG8_SA(b, h) + aoff + m * 2048 + k * 1024); } while (0)
; #define PG8_LDB(dst, b, h) do { _Pragma("unroll") for (int n = 0; n < 2; ++n) _Pragma("unroll") for (int k = 0; k < 2; ++k) dst[n][k] = *(const LAS bf16x8*)(lds + PG8_SB(b, h) + boff + n * 2048 + k * 1024); } while (0)
; #define PG8_WAIT_V(n) asm volatile("s_waitcnt vmcnt(" #n ")" ::: "memory")
; #define PG8_WAIT_L(n) asm volatile("s_waitcnt lgkmcnt(" #n ")" ::: "memory")
; #define PG8_BAR __builtin_amdgcn_s_barrier()
; #define PG8_SCHED __builtin_amdgcn_sched_barrier(0)
;     ...
;             PG8_BAR; PG8_WAIT_L(0); PG8_MMA(0, 1, At, B1); PG8_BAR;
;             PG8_LDA(At, 0, 1); PG8_STAGE(PG8_SA(0, 0), a2);
;             PG8_BAR; PG8_WAIT_L(0); PG8_MMA(1, 0, At, B0); PG8_BAR; PG8_SCHED;
;             PG8_STAGE(PG8_SB(0, 1), b2 + hstep);
;             PG8_WAIT_V(6); PG8_BAR; PG8_MMA(1, 1, At, B1); PG8_BAR;
;             PG8_LDB(B0, 1, 0); PG8_SCHED; PG8_LDA(At, 1, 0); PG8_STAGE(PG8_SA(0, 1), a2 + hstep);
;             PG8_WAIT_L(8); PG8_BAR; PG8_WAIT_L(0); PG8_MMA(0, 0, At, B0); PG8_BAR; PG8_SCHED;
;             PG8_LDB(B1, 1, 1); PG8_STAGE(PG8_SB(1, 0), b3);
;             PG8_BAR; PG8_WAIT_L(0); PG8_MMA(0, 1, At, B1); PG8_BAR;
;             PG8_LDA(At, 1, 1); PG8_STAGE(PG8_SA(1, 0), a3);
;             PG8_BAR; PG8_WAIT_L(0); PG8_MMA(1, 0, At, B0); PG8_BAR; PG8_SCHED;
;             PG8_STAGE(PG8_SB(1, 1), b3 + hstep);
;             PG8_WAIT_V(6); PG8_BAR; PG8_MMA(1, 1, At, B1); PG8_BAR;
	s_add_u32 s0, s44, s7
	s_addc_u32 s1, s45, 0
	s_add_i32 s5, s36, s16
	v_lshl_add_u64 v[246:247], s[0:1], 0, v[130:131]
	s_mov_b32 m0, s5
	v_lshl_add_u64 v[248:249], s[0:1], 0, v[132:133]
	global_load_lds_dwordx4 v[246:247], off
	s_add_i32 m0, s5, 0x2000
	s_nop 0
	global_load_lds_dwordx4 v[248:249], off
	s_waitcnt vmcnt(6)
	s_barrier
	s_setprio 1
	v_mfma_f32_16x16x32_bf16 v[42:45], v[226:229], v[194:197], v[42:45]
	v_mfma_f32_16x16x32_bf16 v[14:17], v[234:237], v[194:197], v[14:17]
	v_mfma_f32_16x16x32_bf16 v[34:37], v[226:229], v[202:205], v[34:37]
	v_mfma_f32_16x16x32_bf16 v[10:13], v[234:237], v[202:205], v[10:13]
	v_mfma_f32_16x16x32_bf16 v[26:29], v[226:229], v[210:213], v[26:29]
	v_mfma_f32_16x16x32_bf16 v[6:9], v[234:237], v[210:213], v[6:9]
	v_mfma_f32_16x16x32_bf16 v[18:21], v[226:229], v[218:221], v[18:21]
	v_mfma_f32_16x16x32_bf16 v[2:5], v[234:237], v[218:221], v[2:5]
	v_mfma_f32_16x16x32_bf16 v[42:45], v[230:233], v[198:201], v[42:45]
	v_mfma_f32_16x16x32_bf16 v[14:17], v[238:241], v[198:201], v[14:17]
	v_mfma_f32_16x16x32_bf16 v[34:37], v[230:233], v[206:209], v[34:37]
	v_mfma_f32_16x16x32_bf16 v[10:13], v[238:241], v[206:209], v[10:13]
	v_mfma_f32_16x16x32_bf16 v[26:29], v[230:233], v[214:217], v[26:29]
	v_mfma_f32_16x16x32_bf16 v[6:9], v[238:241], v[214:217], v[6:9]
	v_mfma_f32_16x16x32_bf16 v[18:21], v[230:233], v[222:225], v[18:21]
	v_mfma_f32_16x16x32_bf16 v[2:5], v[238:241], v[222:225], v[2:5]
	s_setprio 0
	s_add_i32 s5, 0, 0x18000
	v_add_u32_e32 v157, s5, v155
	s_barrier
	ds_read_b128 v[158:161], v157
	ds_read_b128 v[162:165], v157 offset:1024
	ds_read_b128 v[166:169], v157 offset:2048
	ds_read_b128 v[170:173], v157 offset:3072
	s_add_u32 s0, s40, s7
	s_addc_u32 s1, s41, 0
	s_mov_b32 m0, s19
	v_lshl_add_u64 v[226:227], s[0:1], 0, v[130:131]
	ds_read_b128 v[194:197], v156 offset:32768
	ds_read_b128 v[198:201], v156 offset:33792
	ds_read_b128 v[202:205], v156 offset:34816
	ds_read_b128 v[206:209], v156 offset:35840
	ds_read_b128 v[210:213], v156 offset:36864
	ds_read_b128 v[214:217], v156 offset:37888
	ds_read_b128 v[218:221], v156 offset:38912
	ds_read_b128 v[222:225], v156 offset:39936
	global_load_lds_dwordx4 v[226:227], off
	v_lshl_add_u64 v[226:227], s[0:1], 0, v[132:133]
	s_mov_b32 m0, s20
	s_nop 0
	global_load_lds_dwordx4 v[226:227], off
	s_waitcnt lgkmcnt(8)
	s_barrier
	s_waitcnt lgkmcnt(0)
	s_setprio 1
	s_waitcnt lgkmcnt(0)
	v_mfma_f32_16x16x32_bf16 v[126:129], v[158:161], v[194:197], v[126:129]
	v_mfma_f32_16x16x32_bf16 v[98:101], v[166:169], v[194:197], v[98:101]
	v_mfma_f32_16x16x32_bf16 v[122:125], v[158:161], v[202:205], v[122:125]
	v_mfma_f32_16x16x32_bf16 v[94:97], v[166:169], v[202:205], v[94:97]
	v_mfma_f32_16x16x32_bf16 v[118:121], v[158:161], v[210:213], v[118:121]
	v_mfma_f32_16x16x32_bf16 v[90:93], v[166:169], v[210:213], v[90:93]
	v_mfma_f32_16x16x32_bf16 v[114:117], v[158:161], v[218:221], v[114:117]
	v_mfma_f32_16x16x32_bf16 v[82:85], v[166:169], v[218:221], v[82:85]
	v_mfma_f32_16x16x32_bf16 v[126:129], v[162:165], v[198:201], v[126:129]
	v_mfma_f32_16x16x32_bf16 v[98:101], v[170:173], v[198:201], v[98:101]
	v_mfma_f32_16x16x32_bf16 v[122:125], v[162:165], v[206:209], v[122:125]
	v_mfma_f32_16x16x32_bf16 v[94:97], v[170:173], v[206:209], v[94:97]
	v_mfma_f32_16x16x32_bf16 v[118:121], v[162:165], v[214:217], v[118:121]
	v_mfma_f32_16x16x32_bf16 v[90:93], v[170:173], v[214:217], v[90:93]
	v_mfma_f32_16x16x32_bf16 v[114:117], v[162:165], v[222:225], v[114:117]
	v_mfma_f32_16x16x32_bf16 v[82:85], v[170:173], v[222:225], v[82:85]
	s_setprio 0
	s_barrier
	s_add_i32 s0, 0, 0x1c000
	s_add_i32 s1, s5, s16
	v_add_u32_e32 v157, s0, v155
	v_lshl_add_u64 v[174:175], v[174:175], 0, s[88:89]
	s_mov_b32 m0, s1
	ds_read_b128 v[226:229], v157
	ds_read_b128 v[230:233], v157 offset:1024
	ds_read_b128 v[234:237], v157 offset:2048
	ds_read_b128 v[238:241], v157 offset:3072
	global_load_lds_dwordx4 v[174:175], off
	v_lshl_add_u64 v[174:175], v[192:193], 0, s[88:89]
	s_add_i32 m0, s1, 0x2000
	s_nop 0
	global_load_lds_dwordx4 v[174:175], off
	s_barrier
	s_waitcnt lgkmcnt(0)
	s_setprio 1
	s_waitcnt lgkmcnt(0)
	v_mfma_f32_16x16x32_bf16 v[74:77], v[226:229], v[194:197], v[74:77]
	v_mfma_f32_16x16x32_bf16 v[46:49], v[234:237], v[194:197], v[46:49]
	v_mfma_f32_16x16x32_bf16 v[66:69], v[226:229], v[202:205], v[66:69]
	v_mfma_f32_16x16x32_bf16 v[38:41], v[234:237], v[202:205], v[38:41]
	v_mfma_f32_16x16x32_bf16 v[58:61], v[226:229], v[210:213], v[58:61]
	v_mfma_f32_16x16x32_bf16 v[30:33], v[234:237], v[210:213], v[30:33]
	v_mfma_f32_16x16x32_bf16 v[50:53], v[226:229], v[218:221], v[50:53]
	v_mfma_f32_16x16x32_bf16 v[22:25], v[234:237], v[218:221], v[22:25]
	v_mfma_f32_16x16x32_bf16 v[74:77], v[230:233], v[198:201], v[74:77]
	v_mfma_f32_16x16x32_bf16 v[46:49], v[238:241], v[198:201], v[46:49]
	v_mfma_f32_16x16x32_bf16 v[66:69], v[230:233], v[206:209], v[66:69]
	v_mfma_f32_16x16x32_bf16 v[38:41], v[238:241], v[206:209], v[38:41]
	v_mfma_f32_16x16x32_bf16 v[58:61], v[230:233], v[214:217], v[58:61]
	v_mfma_f32_16x16x32_bf16 v[30:33], v[238:241], v[214:217], v[30:33]
	v_mfma_f32_16x16x32_bf16 v[50:53], v[230:233], v[222:225], v[50:53]
	v_mfma_f32_16x16x32_bf16 v[22:25], v[238:241], v[222:225], v[22:25]
	s_setprio 0
	s_mov_b32 m0, s28
	v_lshl_add_u64 v[174:175], v[242:243], 0, s[88:89]
	s_barrier
	ds_read_b128 v[194:197], v156 offset:49152
	ds_read_b128 v[198:201], v156 offset:50176
	ds_read_b128 v[202:205], v156 offset:51200
	ds_read_b128 v[206:209], v156 offset:52224
	ds_read_b128 v[210:213], v156 offset:53248
	ds_read_b128 v[214:217], v156 offset:54272
	ds_read_b128 v[218:221], v156 offset:55296
	ds_read_b128 v[222:225], v156 offset:56320
	global_load_lds_dwordx4 v[174:175], off
	v_lshl_add_u64 v[174:175], v[244:245], 0, s[88:89]
	s_mov_b32 m0, s29
	s_nop 0
	global_load_lds_dwordx4 v[174:175], off
	s_barrier
;     __device__ __forceinline__ void operator()(Acc& acc, int pm, int pn, int wr, int wc, int fr, int fq) const {
;         const int brow = pm * 256;
;         const bool lat = brow < T_LAT;
;         const float* xin = lat ? xin_lat : xin_ctx;
;         float* xout = lat ? xout_lat : xout_ctx;
;         const int rsub = lat ? 0 : T_LAT;
;         const int mi = lat ? (brow >> 12) : 8;
;         const int c0 = pn * 256 + wc * 32 + fq * 4;
;         const float* gp = modv_l + (size_t)mi * 6144 + gate_i * 1024 + c0;
; #pragma unroll
;         for (int bj = 0; bj < 2; ++bj)
; #pragma unroll
;             for (int n = 0; n < 2; ++n) {
;                 const f32x4 gv = *reinterpret_cast<const f32x4*>(gp + bj * 128 + n * 16);
; #pragma unroll
;                 for (int ai = 0; ai < 2; ++ai)
; #pragma unroll
;                     for (int m = 0; m < 4; ++m) {
;                         const size_t o = (size_t)(brow + ai * 128 + wr * 64 + m * 16 + fr - rsub) * DM + c0 + bj * 128 + n * 16;
;                         const f32x4 xi = *reinterpret_cast<const f32x4*>(xin + o);
;                         const f32x4 a = acc[ai][bj][m][n];
;                         f32x4 r = {xi[0] + gv[0] * a[0], xi[1] + gv[1] * a[1], xi[2] + gv[2] * a[2], xi[3] + gv[3] * a[3]};
;                         *reinterpret_cast<f32x4*>(xout + o) = r;
;                     }
;             }
	s_waitcnt lgkmcnt(0)
	s_setprio 1
	s_waitcnt lgkmcnt(0)
	v_mfma_f32_16x16x32_bf16 v[110:113], v[158:161], v[194:197], v[110:113]
	v_mfma_f32_16x16x32_bf16 v[78:81], v[166:169], v[194:197], v[78:81]
	v_mfma_f32_16x16x32_bf16 v[106:109], v[158:161], v[202:205], v[106:109]
	v_mfma_f32_16x16x32_bf16 v[70:73], v[166:169], v[202:205], v[70:73]
	v_mfma_f32_16x16x32_bf16 v[102:105], v[158:161], v[210:213], v[102:105]
	v_mfma_f32_16x16x32_bf16 v[62:65], v[166:169], v[210:213], v[62:65]
	v_mfma_f32_16x16x32_bf16 v[86:89], v[158:161], v[218:221], v[86:89]
	v_mfma_f32_16x16x32_bf16 v[54:57], v[166:169], v[218:221], v[54:57]
	v_mfma_f32_16x16x32_bf16 v[110:113], v[162:165], v[198:201], v[110:113]
	v_mfma_f32_16x16x32_bf16 v[78:81], v[170:173], v[198:201], v[78:81]
	v_mfma_f32_16x16x32_bf16 v[106:109], v[162:165], v[206:209], v[106:109]
	v_mfma_f32_16x16x32_bf16 v[70:73], v[170:173], v[206:209], v[70:73]
	v_mfma_f32_16x16x32_bf16 v[102:105], v[162:165], v[214:217], v[102:105]
	v_mfma_f32_16x16x32_bf16 v[62:65], v[170:173], v[214:217], v[62:65]
	v_mfma_f32_16x16x32_bf16 v[86:89], v[162:165], v[222:225], v[86:89]
	v_mfma_f32_16x16x32_bf16 v[54:57], v[170:173], v[222:225], v[54:57]
	s_setprio 0
	s_barrier
	s_add_i32 s0, s0, s16
	v_lshl_add_u64 v[158:159], v[246:247], 0, s[88:89]
	s_mov_b32 m0, s0
	s_nop 0
	global_load_lds_dwordx4 v[158:159], off
	v_lshl_add_u64 v[158:159], v[248:249], 0, s[88:89]
	s_add_i32 m0, s0, 0x2000
	s_nop 0
	global_load_lds_dwordx4 v[158:159], off
	s_waitcnt vmcnt(6)
	s_barrier
	s_setprio 1
	v_mfma_f32_16x16x32_bf16 v[42:45], v[226:229], v[194:197], v[42:45]
	v_mfma_f32_16x16x32_bf16 v[14:17], v[234:237], v[194:197], v[14:17]
	v_mfma_f32_16x16x32_bf16 v[34:37], v[226:229], v[202:205], v[34:37]
	v_mfma_f32_16x16x32_bf16 v[10:13], v[234:237], v[202:205], v[10:13]
	v_mfma_f32_16x16x32_bf16 v[26:29], v[226:229], v[210:213], v[26:29]
	v_mfma_f32_16x16x32_bf16 v[6:9], v[234:237], v[210:213], v[6:9]
	v_mfma_f32_16x16x32_bf16 v[18:21], v[226:229], v[218:221], v[18:21]
	v_mfma_f32_16x16x32_bf16 v[2:5], v[234:237], v[218:221], v[2:5]
	v_mfma_f32_16x16x32_bf16 v[42:45], v[230:233], v[198:201], v[42:45]
	v_mfma_f32_16x16x32_bf16 v[14:17], v[238:241], v[198:201], v[14:17]
	v_mfma_f32_16x16x32_bf16 v[34:37], v[230:233], v[206:209], v[34:37]
	v_mfma_f32_16x16x32_bf16 v[10:13], v[238:241], v[206:209], v[10:13]
	v_mfma_f32_16x16x32_bf16 v[26:29], v[230:233], v[214:217], v[26:29]
	v_mfma_f32_16x16x32_bf16 v[6:9], v[238:241], v[214:217], v[6:9]
	v_mfma_f32_16x16x32_bf16 v[18:21], v[230:233], v[222:225], v[18:21]
	v_mfma_f32_16x16x32_bf16 v[2:5], v[238:241], v[222:225], v[2:5]
	s_setprio 0
	s_add_u32 s14, s14, 0x100
	s_addc_u32 s15, s15, 0
	s_cmp_ge_u32 s31, s22
	s_mov_b32 s5, s31
	s_barrier
	s_cbranch_scc0 .LBB0_1408
	v_readlane_b32 s0, v253, 63
	v_readlane_b32 s10, v255, 26
	v_readlane_b32 s11, v255, 27
	v_readlane_b32 s12, v254, 6
	v_readlane_b32 s16, v254, 10
	v_readlane_b32 s17, v254, 11
	v_readlane_b32 s13, v254, 7
	v_readlane_b32 s14, v254, 8
	v_readlane_b32 s15, v254, 9
	v_readlane_b32 s18, v254, 12
	v_readlane_b32 s19, v254, 13
	v_mov_b32_e32 v161, v0
	v_lshl_or_b32 v157, v154, 2, s0
	v_or_b32_e32 v157, s23, v157
	v_lshlrev_b32_e32 v160, 2, v157
	v_readlane_b32 s0, v253, 61
	s_nop 1
	v_lshl_add_u64 v[158:159], s[50:51], 0, v[160:161]
	v_add_u32_e32 v162, s0, v1
	s_mov_b64 s[0:1], 0x32000
	v_lshl_add_u64 v[158:159], v[158:159], 0, s[0:1]
	global_load_dwordx4 v[192:195], v[158:159], off
	global_load_dwordx4 v[196:199], v[158:159], off offset:64
	global_load_dwordx4 v[200:203], v[158:159], off offset:512
	global_load_dwordx4 v[204:207], v[158:159], off offset:576
	v_add_u32_e32 v163, 0xffff8000, v162
	v_lshl_or_b32 v164, v163, 12, v160
	v_add_u32_e32 v165, 0x10000, v164
	v_add_u32_e32 v166, 0x20000, v164
	v_add_u32_e32 v167, 0x30000, v164
	v_add_u32_e32 v168, 0x80000, v164
	v_add_u32_e32 v169, 0x90000, v164
	v_add_u32_e32 v170, 0xa0000, v164
	v_add_u32_e32 v171, 0xb0000, v164
	global_load_dwordx4 v[208:211], v164, s[10:11]
	global_load_dwordx4 v[212:215], v164, s[10:11] offset:64
	global_load_dwordx4 v[216:219], v165, s[10:11]
	global_load_dwordx4 v[220:223], v165, s[10:11] offset:64
	global_load_dwordx4 v[224:227], v166, s[10:11]
	global_load_dwordx4 v[228:231], v166, s[10:11] offset:64
	global_load_dwordx4 v[232:235], v167, s[10:11]
	global_load_dwordx4 v[236:239], v167, s[10:11] offset:64
	global_load_dwordx4 v[240:243], v168, s[10:11]
	global_load_dwordx4 v[244:247], v168, s[10:11] offset:64
	s_cmpk_lt_u32 s4, 0x100
	s_waitcnt vmcnt(9)
	v_pk_fma_f32 v[126:127], v[126:127], v[192:193], v[208:209]
	v_pk_fma_f32 v[128:129], v[128:129], v[194:195], v[210:211]
	global_store_dwordx4 v164, v[126:129], s[16:17] sc1
	global_load_dwordx4 v[208:211], v169, s[10:11]
	s_waitcnt vmcnt(10)
	v_pk_fma_f32 v[98:99], v[98:99], v[196:197], v[212:213]
	v_pk_fma_f32 v[100:101], v[100:101], v[198:199], v[214:215]
	global_store_dwordx4 v164, v[98:101], s[16:17] offset:64 sc1
	global_load_dwordx4 v[212:215], v169, s[10:11] offset:64
	s_waitcnt vmcnt(11)
	v_pk_fma_f32 v[122:123], v[122:123], v[192:193], v[216:217]
	v_pk_fma_f32 v[124:125], v[124:125], v[194:195], v[218:219]
	global_store_dwordx4 v165, v[122:125], s[16:17] sc1
	global_load_dwordx4 v[216:219], v170, s[10:11]
	s_waitcnt vmcnt(12)
	v_pk_fma_f32 v[94:95], v[94:95], v[196:197], v[220:221]
	v_pk_fma_f32 v[96:97], v[96:97], v[198:199], v[222:223]
	global_store_dwordx4 v165, v[94:97], s[16:17] offset:64 sc1
	global_load_dwordx4 v[220:223], v170, s[10:11] offset:64
	s_waitcnt vmcnt(13)
;     __device__ __forceinline__ void operator()(Acc& acc, int pm, int pn, int wr, int wc, int fr, int fq) const {
;     ...
; #pragma unroll
;         for (int bj = 0; bj < 2; ++bj)
; #pragma unroll
;             for (int n = 0; n < 2; ++n) {
;                 const f32x4 gv = *reinterpret_cast<const f32x4*>(gp + bj * 128 + n * 16);
; #pragma unroll
;                 for (int ai = 0; ai < 2; ++ai)
; #pragma unroll
;                     for (int m = 0; m < 4; ++m) {
;                         const size_t o = (size_t)(brow + ai * 128 + wr * 64 + m * 16 + fr - rsub) * DM + c0 + bj * 128 + n * 16;
;                         const f32x4 xi = *reinterpret_cast<const f32x4*>(xin + o);
;                         const f32x4 a = acc[ai][bj][m][n];
;                         f32x4 r = {xi[0] + gv[0] * a[0], xi[1] + gv[1] * a[1], xi[2] + gv[2] * a[2], xi[3] + gv[3] * a[3]};
;                         *reinterpret_cast<f32x4*>(xout + o) = r;
;                     }
;             }
	v_pk_fma_f32 v[118:119], v[118:119], v[192:193], v[224:225]
	v_pk_fma_f32 v[120:121], v[120:121], v[194:195], v[226:227]
	global_store_dwordx4 v166, v[118:121], s[16:17] sc1
	global_load_dwordx4 v[224:227], v171, s[10:11]
	s_waitcnt vmcnt(14)
	v_pk_fma_f32 v[90:91], v[90:91], v[196:197], v[228:229]
	v_pk_fma_f32 v[92:93], v[92:93], v[198:199], v[230:231]
	global_store_dwordx4 v166, v[90:93], s[16:17] offset:64 sc1
	global_load_dwordx4 v[228:231], v171, s[10:11] offset:64
	s_waitcnt vmcnt(15)
	v_pk_fma_f32 v[114:115], v[114:115], v[192:193], v[232:233]
	v_pk_fma_f32 v[116:117], v[116:117], v[194:195], v[234:235]
	global_store_dwordx4 v167, v[114:117], s[16:17] sc1
	global_load_dwordx4 v[232:235], v164, s[10:11] offset:512
	s_waitcnt vmcnt(16)
	v_pk_fma_f32 v[82:83], v[82:83], v[196:197], v[236:237]
	v_pk_fma_f32 v[84:85], v[84:85], v[198:199], v[238:239]
	global_store_dwordx4 v167, v[82:85], s[16:17] offset:64 sc1
	global_load_dwordx4 v[236:239], v164, s[10:11] offset:576
	s_waitcnt vmcnt(17)
	v_pk_fma_f32 v[110:111], v[110:111], v[192:193], v[240:241]
	v_pk_fma_f32 v[112:113], v[112:113], v[194:195], v[242:243]
	global_store_dwordx4 v168, v[110:113], s[16:17] sc1
	global_load_dwordx4 v[240:243], v165, s[10:11] offset:512
	s_waitcnt vmcnt(18)
	v_pk_fma_f32 v[78:79], v[78:79], v[196:197], v[244:245]
	v_pk_fma_f32 v[80:81], v[80:81], v[198:199], v[246:247]
	global_store_dwordx4 v168, v[78:81], s[16:17] offset:64 sc1
	global_load_dwordx4 v[244:247], v165, s[10:11] offset:576
	s_waitcnt vmcnt(18)
	v_pk_fma_f32 v[106:107], v[106:107], v[192:193], v[208:209]
	v_pk_fma_f32 v[108:109], v[108:109], v[194:195], v[210:211]
	global_store_dwordx4 v169, v[106:109], s[16:17] sc1
	global_load_dwordx4 v[208:211], v166, s[10:11] offset:512
	s_waitcnt vmcnt(18)
	v_pk_fma_f32 v[70:71], v[70:71], v[196:197], v[212:213]
	v_pk_fma_f32 v[72:73], v[72:73], v[198:199], v[214:215]
	global_store_dwordx4 v169, v[70:73], s[16:17] offset:64 sc1
	global_load_dwordx4 v[212:215], v166, s[10:11] offset:576
	s_waitcnt vmcnt(18)
	v_pk_fma_f32 v[102:103], v[102:103], v[192:193], v[216:217]
	v_pk_fma_f32 v[104:105], v[104:105], v[194:195], v[218:219]
	global_store_dwordx4 v170, v[102:105], s[16:17] sc1
	global_load_dwordx4 v[216:219], v167, s[10:11] offset:512
	s_waitcnt vmcnt(18)
	v_pk_fma_f32 v[62:63], v[62:63], v[196:197], v[220:221]
	v_pk_fma_f32 v[64:65], v[64:65], v[198:199], v[222:223]
	global_store_dwordx4 v170, v[62:65], s[16:17] offset:64 sc1
	global_load_dwordx4 v[220:223], v167, s[10:11] offset:576
	s_waitcnt vmcnt(18)
	v_pk_fma_f32 v[86:87], v[86:87], v[192:193], v[224:225]
	v_pk_fma_f32 v[88:89], v[88:89], v[194:195], v[226:227]
	global_store_dwordx4 v171, v[86:89], s[16:17] sc1
	global_load_dwordx4 v[224:227], v168, s[10:11] offset:512
	s_waitcnt vmcnt(18)
	v_pk_fma_f32 v[54:55], v[54:55], v[196:197], v[228:229]
	v_pk_fma_f32 v[56:57], v[56:57], v[198:199], v[230:231]
	global_store_dwordx4 v171, v[54:57], s[16:17] offset:64 sc1
	global_load_dwordx4 v[228:231], v168, s[10:11] offset:576
	s_waitcnt vmcnt(18)
	v_pk_fma_f32 v[74:75], v[74:75], v[200:201], v[232:233]
	v_pk_fma_f32 v[76:77], v[76:77], v[202:203], v[234:235]
	global_store_dwordx4 v164, v[74:77], s[16:17] offset:512 sc1
	global_load_dwordx4 v[232:235], v169, s[10:11] offset:512
	s_waitcnt vmcnt(18)
	v_pk_fma_f32 v[46:47], v[46:47], v[204:205], v[236:237]
	v_pk_fma_f32 v[48:49], v[48:49], v[206:207], v[238:239]
	global_store_dwordx4 v164, v[46:49], s[16:17] offset:576 sc1
	global_load_dwordx4 v[236:239], v169, s[10:11] offset:576
	s_waitcnt vmcnt(18)
	v_pk_fma_f32 v[66:67], v[66:67], v[200:201], v[240:241]
	v_pk_fma_f32 v[68:69], v[68:69], v[202:203], v[242:243]
	global_store_dwordx4 v165, v[66:69], s[16:17] offset:512 sc1
	global_load_dwordx4 v[240:243], v170, s[10:11] offset:512
	s_waitcnt vmcnt(18)
	v_pk_fma_f32 v[38:39], v[38:39], v[204:205], v[244:245]
	v_pk_fma_f32 v[40:41], v[40:41], v[206:207], v[246:247]
	global_store_dwordx4 v165, v[38:41], s[16:17] offset:576 sc1
	global_load_dwordx4 v[244:247], v170, s[10:11] offset:576
	s_waitcnt vmcnt(18)
	v_pk_fma_f32 v[58:59], v[58:59], v[200:201], v[208:209]
	v_pk_fma_f32 v[60:61], v[60:61], v[202:203], v[210:211]
	global_store_dwordx4 v166, v[58:61], s[16:17] offset:512 sc1
	global_load_dwordx4 v[208:211], v171, s[10:11] offset:512
	s_waitcnt vmcnt(18)
	v_pk_fma_f32 v[30:31], v[30:31], v[204:205], v[212:213]
	v_pk_fma_f32 v[32:33], v[32:33], v[206:207], v[214:215]
	global_store_dwordx4 v166, v[30:33], s[16:17] offset:576 sc1
	global_load_dwordx4 v[212:215], v171, s[10:11] offset:576
	s_waitcnt vmcnt(18)
	v_pk_fma_f32 v[50:51], v[50:51], v[200:201], v[216:217]
	v_pk_fma_f32 v[52:53], v[52:53], v[202:203], v[218:219]
	global_store_dwordx4 v167, v[50:53], s[16:17] offset:512 sc1
	s_waitcnt vmcnt(17)
	v_pk_fma_f32 v[22:23], v[22:23], v[204:205], v[220:221]
	v_pk_fma_f32 v[24:25], v[24:25], v[206:207], v[222:223]
	global_store_dwordx4 v167, v[22:25], s[16:17] offset:576 sc1
	s_waitcnt vmcnt(16)
	v_pk_fma_f32 v[42:43], v[42:43], v[200:201], v[224:225]
	v_pk_fma_f32 v[44:45], v[44:45], v[202:203], v[226:227]
	global_store_dwordx4 v168, v[42:45], s[16:17] offset:512 sc1
	s_waitcnt vmcnt(15)
	v_pk_fma_f32 v[14:15], v[14:15], v[204:205], v[228:229]
	v_pk_fma_f32 v[16:17], v[16:17], v[206:207], v[230:231]
	global_store_dwordx4 v168, v[14:17], s[16:17] offset:576 sc1
	s_waitcnt vmcnt(14)
	v_pk_fma_f32 v[34:35], v[34:35], v[200:201], v[232:233]
	v_pk_fma_f32 v[36:37], v[36:37], v[202:203], v[234:235]
	global_store_dwordx4 v169, v[34:37], s[16:17] offset:512 sc1
	s_waitcnt vmcnt(13)
	v_pk_fma_f32 v[10:11], v[10:11], v[204:205], v[236:237]
	v_pk_fma_f32 v[12:13], v[12:13], v[206:207], v[238:239]
	global_store_dwordx4 v169, v[10:13], s[16:17] offset:576 sc1
	s_waitcnt vmcnt(12)
	v_pk_fma_f32 v[26:27], v[26:27], v[200:201], v[240:241]
	v_pk_fma_f32 v[28:29], v[28:29], v[202:203], v[242:243]
	global_store_dwordx4 v170, v[26:29], s[16:17] offset:512 sc1
	s_waitcnt vmcnt(11)
	v_pk_fma_f32 v[6:7], v[6:7], v[204:205], v[244:245]
	v_pk_fma_f32 v[8:9], v[8:9], v[206:207], v[246:247]
	global_store_dwordx4 v170, v[6:9], s[16:17] offset:576 sc1
	s_waitcnt vmcnt(10)
	v_pk_fma_f32 v[18:19], v[18:19], v[200:201], v[208:209]
	v_pk_fma_f32 v[20:21], v[20:21], v[202:203], v[210:211]
	global_store_dwordx4 v171, v[18:21], s[16:17] offset:512 sc1
	s_waitcnt vmcnt(9)
	v_pk_fma_f32 v[2:3], v[2:3], v[204:205], v[212:213]
	v_pk_fma_f32 v[4:5], v[4:5], v[206:207], v[214:215]
	global_store_dwordx4 v171, v[2:5], s[16:17] offset:576 sc1
	s_mov_b32 s0, 0xf80b0000
	s_mov_b32 s1, -1
	s_waitcnt vmcnt(0)
	s_cbranch_scc0 .LBB0_1411
	s_barrier

; #define PG8_STAGE(bufoff, gbase) do { _Pragma("unroll") for (int _i = 0; _i < 2; ++_i) \
;         __builtin_amdgcn_global_load_lds((const unsigned*)((const char*)(gbase) + voff[_i]), (LAS unsigned*)(lds + (bufoff) + ldsw + _i * 8192), 16, 0, 0); } while (0)
; #define PG8_LDA(dst, b, h) do { _Pragma("unroll") for (int m = 0; m < 4; ++m) _Pragma("unroll") for (int k = 0; k < 2; ++k) dst[m][k] = *(const LAS bf16x8*)(lds + PG8_SA(b, h) + aoff + m * 2048 + k * 1024); } while (0)
; #define PG8_LDB(dst, b, h) do { _Pragma("unroll") for (int n = 0; n < 2; ++n) _Pragma("unroll") for (int k = 0; k < 2; ++k) dst[n][k] = *(const LAS bf16x8*)(lds + PG8_SB(b, h) + boff + n * 2048 + k * 1024); } while (0)
; #define PG8_WAIT_L(n) asm volatile("s_waitcnt lgkmcnt(" #n ")" ::: "memory")
; #define PG8_BAR __builtin_amdgcn_s_barrier()
; #define PG8_SCHED __builtin_amdgcn_sched_barrier(0)
;     ...
;         const bool has_next = S.next(ui + 1, nxt);
;         const char* nA = has_next ? (const char*)gA + (size_t)nxt.pm * tstep : cA; const char* nB = has_next ? (const char*)gBt + (size_t)nxt.pn * tstep : cB;
;         for (int t = 0; t < nt; t += 2) {
;             const bool last = (t == nt - 2);
;             const char* a1 = cA + (size_t)(t + 1) * kstep;
;             const char* a2 = last ? nA : cA + (size_t)(t + 2) * kstep; const char* b2 = last ? nB : cB + (size_t)(t + 2) * kstep;
;             const char* a3 = a2 + kstep; const char* b3 = b2 + kstep;
;             PG8_LDB(B0, 0, 0); PG8_SCHED; PG8_LDA(At, 0, 0); PG8_STAGE(PG8_SA(1, 1), a1 + hstep);
;             PG8_WAIT_L(8); PG8_BAR; PG8_WAIT_L(0); PG8_MMA(0, 0, At, B0); PG8_BAR; PG8_SCHED;
;             PG8_LDB(B1, 0, 1); PG8_STAGE(PG8_SB(0, 0), b2);
;             PG8_BAR; PG8_WAIT_L(0); PG8_MMA(0, 1, At, B1); PG8_BAR;
;     ...
;         for (int a = 0; a < 2; ++a)
; #pragma unroll
;             for (int b = 0; b < 2; ++b)
; #pragma unroll
;                 for (int m = 0; m < 4; ++m)
; #pragma unroll
;                     for (int n = 0; n < 2; ++n) acc[a][b][m][n] = (f32x4){0.f, 0.f, 0.f, 0.f};
;         cur = nxt; cA = nA; cB = nB; ++ui;
.LBB0_1648:
	s_add_u32 s22, s52, 0x100
	v_mov_b32_e32 v2, 0
	s_addc_u32 s23, s53, 0
	s_mov_b32 s28, -2
	v_mov_b32_e32 v3, v2
	v_mov_b32_e32 v4, v2
	v_mov_b32_e32 v5, v2
	v_mov_b32_e32 v30, v2
	v_mov_b32_e32 v31, v2
	v_mov_b32_e32 v32, v2
	v_mov_b32_e32 v33, v2
	v_mov_b32_e32 v6, v2
	v_mov_b32_e32 v7, v2
	v_mov_b32_e32 v8, v2
	v_mov_b32_e32 v9, v2
	v_mov_b32_e32 v34, v2
	v_mov_b32_e32 v35, v2
	v_mov_b32_e32 v36, v2
	v_mov_b32_e32 v37, v2
	v_mov_b32_e32 v10, v2
	v_mov_b32_e32 v11, v2
	v_mov_b32_e32 v12, v2
	v_mov_b32_e32 v13, v2
	v_mov_b32_e32 v42, v2
	v_mov_b32_e32 v43, v2
	v_mov_b32_e32 v44, v2
	v_mov_b32_e32 v45, v2
	v_mov_b32_e32 v14, v2
	v_mov_b32_e32 v15, v2
	v_mov_b32_e32 v16, v2
	v_mov_b32_e32 v17, v2
	v_mov_b32_e32 v46, v2
	v_mov_b32_e32 v47, v2
	v_mov_b32_e32 v48, v2
	v_mov_b32_e32 v49, v2
	v_mov_b32_e32 v62, v2
	v_mov_b32_e32 v63, v2
	v_mov_b32_e32 v64, v2
	v_mov_b32_e32 v65, v2
	v_mov_b32_e32 v94, v2
	v_mov_b32_e32 v95, v2
	v_mov_b32_e32 v96, v2
	v_mov_b32_e32 v97, v2
	v_mov_b32_e32 v70, v2
	v_mov_b32_e32 v71, v2
	v_mov_b32_e32 v72, v2
	v_mov_b32_e32 v73, v2
	v_mov_b32_e32 v98, v2
	v_mov_b32_e32 v99, v2
	v_mov_b32_e32 v100, v2
	v_mov_b32_e32 v101, v2
	v_mov_b32_e32 v74, v2
	v_mov_b32_e32 v75, v2
	v_mov_b32_e32 v76, v2
	v_mov_b32_e32 v77, v2
	v_mov_b32_e32 v106, v2
	v_mov_b32_e32 v107, v2
	v_mov_b32_e32 v108, v2
	v_mov_b32_e32 v109, v2
	v_mov_b32_e32 v78, v2
	v_mov_b32_e32 v79, v2
	v_mov_b32_e32 v80, v2
	v_mov_b32_e32 v81, v2
	v_mov_b32_e32 v110, v2
	v_mov_b32_e32 v111, v2
	v_mov_b32_e32 v112, v2
	v_mov_b32_e32 v113, v2
	v_mov_b32_e32 v18, v2
	v_mov_b32_e32 v19, v2
	v_mov_b32_e32 v20, v2
	v_mov_b32_e32 v21, v2
	v_mov_b32_e32 v50, v2
	v_mov_b32_e32 v51, v2
	v_mov_b32_e32 v52, v2
	v_mov_b32_e32 v53, v2
	v_mov_b32_e32 v22, v2
	v_mov_b32_e32 v23, v2
	v_mov_b32_e32 v24, v2
	v_mov_b32_e32 v25, v2
	v_mov_b32_e32 v54, v2
	v_mov_b32_e32 v55, v2
	v_mov_b32_e32 v56, v2
	v_mov_b32_e32 v57, v2
	v_mov_b32_e32 v26, v2
	v_mov_b32_e32 v27, v2
	v_mov_b32_e32 v28, v2
	v_mov_b32_e32 v29, v2
	v_mov_b32_e32 v58, v2
	v_mov_b32_e32 v59, v2
	v_mov_b32_e32 v60, v2
	v_mov_b32_e32 v61, v2
	v_mov_b32_e32 v38, v2
	v_mov_b32_e32 v39, v2
	v_mov_b32_e32 v40, v2
	v_mov_b32_e32 v41, v2
	v_mov_b32_e32 v66, v2
	v_mov_b32_e32 v67, v2
	v_mov_b32_e32 v68, v2
	v_mov_b32_e32 v69, v2
	v_mov_b32_e32 v82, v2
	v_mov_b32_e32 v83, v2
	v_mov_b32_e32 v84, v2
	v_mov_b32_e32 v85, v2
	v_mov_b32_e32 v114, v2
	v_mov_b32_e32 v115, v2
	v_mov_b32_e32 v116, v2
	v_mov_b32_e32 v117, v2
	v_mov_b32_e32 v86, v2
	v_mov_b32_e32 v87, v2
	v_mov_b32_e32 v88, v2
	v_mov_b32_e32 v89, v2
	v_mov_b32_e32 v118, v2
	v_mov_b32_e32 v119, v2
	v_mov_b32_e32 v120, v2
	v_mov_b32_e32 v121, v2
	v_mov_b32_e32 v90, v2
	v_mov_b32_e32 v91, v2
	v_mov_b32_e32 v92, v2
	v_mov_b32_e32 v93, v2
	v_mov_b32_e32 v122, v2
	v_mov_b32_e32 v123, v2
	v_mov_b32_e32 v124, v2
	v_mov_b32_e32 v125, v2
	v_mov_b32_e32 v102, v2
	v_mov_b32_e32 v103, v2
	v_mov_b32_e32 v104, v2
	v_mov_b32_e32 v105, v2
	v_mov_b32_e32 v126, v2
	v_mov_b32_e32 v127, v2
	v_mov_b32_e32 v128, v2
	v_mov_b32_e32 v129, v2
.LBB0_1649:
	s_add_u32 s46, s14, 0x100
	s_addc_u32 s47, s15, 0
	s_add_i32 s0, 0, 0x10000
	v_add_u32_e32 v161, s0, v158
	ds_read_b128 v[154:157], v161
	ds_read_b128 v[162:165], v161 offset:1024
	ds_read_b128 v[166:169], v161 offset:2048
	ds_read_b128 v[170:173], v161 offset:3072
	s_cmp_eq_u32 s28, 40
	s_cselect_b32 s53, s11, s47
	s_cselect_b32 s52, s10, s46
	s_cselect_b32 s49, s13, s23
	s_cselect_b32 s48, s12, s22
	v_lshl_add_u64 v[174:175], s[14:15], 0, v[150:151]
	s_add_i32 m0, s56, 0xc000
	ds_read_b128 v[194:197], v160
	ds_read_b128 v[198:201], v160 offset:1024
	ds_read_b128 v[202:205], v160 offset:2048
	ds_read_b128 v[206:209], v160 offset:3072
	ds_read_b128 v[210:213], v160 offset:4096
	ds_read_b128 v[214:217], v160 offset:5120
	ds_read_b128 v[218:221], v160 offset:6144
	ds_read_b128 v[222:225], v160 offset:7168
	global_load_lds_dwordx4 v[174:175], off
	v_lshl_add_u64 v[174:175], s[14:15], 0, v[152:153]
	s_add_i32 m0, s56, 0xe000
	s_nop 0
	global_load_lds_dwordx4 v[174:175], off
	s_waitcnt lgkmcnt(8)
	s_barrier
	s_waitcnt lgkmcnt(0)
	s_setprio 1
	s_waitcnt lgkmcnt(0)
	v_mfma_f32_16x16x32_bf16 v[126:129], v[154:157], v[194:197], v[126:129]
	v_mfma_f32_16x16x32_bf16 v[102:105], v[166:169], v[194:197], v[102:105]
	v_mfma_f32_16x16x32_bf16 v[122:125], v[154:157], v[202:205], v[122:125]
	v_mfma_f32_16x16x32_bf16 v[90:93], v[166:169], v[202:205], v[90:93]
	v_mfma_f32_16x16x32_bf16 v[118:121], v[154:157], v[210:213], v[118:121]
	v_mfma_f32_16x16x32_bf16 v[86:89], v[166:169], v[210:213], v[86:89]
	v_mfma_f32_16x16x32_bf16 v[114:117], v[154:157], v[218:221], v[114:117]
	v_mfma_f32_16x16x32_bf16 v[82:85], v[166:169], v[218:221], v[82:85]
	v_mfma_f32_16x16x32_bf16 v[126:129], v[162:165], v[198:201], v[126:129]
	v_mfma_f32_16x16x32_bf16 v[102:105], v[170:173], v[198:201], v[102:105]
	v_mfma_f32_16x16x32_bf16 v[122:125], v[162:165], v[206:209], v[122:125]
	v_mfma_f32_16x16x32_bf16 v[90:93], v[170:173], v[206:209], v[90:93]
	v_mfma_f32_16x16x32_bf16 v[118:121], v[162:165], v[214:217], v[118:121]
	v_mfma_f32_16x16x32_bf16 v[86:89], v[170:173], v[214:217], v[86:89]
	v_mfma_f32_16x16x32_bf16 v[114:117], v[162:165], v[222:225], v[114:117]
	v_mfma_f32_16x16x32_bf16 v[82:85], v[170:173], v[222:225], v[82:85]
	s_setprio 0
	s_barrier
	s_add_i32 s14, 0, 0x14000
	s_add_i32 s0, s0, s36
	v_add_u32_e32 v161, s14, v158
	v_lshl_add_u64 v[174:175], s[48:49], 0, v[132:133]
	s_mov_b32 m0, s0
	ds_read_b128 v[226:229], v161
	ds_read_b128 v[230:233], v161 offset:1024
	ds_read_b128 v[234:237], v161 offset:2048
	ds_read_b128 v[238:241], v161 offset:3072
	global_load_lds_dwordx4 v[174:175], off
	v_lshl_add_u64 v[192:193], s[48:49], 0, v[130:131]
	s_add_i32 m0, s0, 0x2000
	s_nop 0
	global_load_lds_dwordx4 v[192:193], off
	s_barrier
; #define PG8_STAGE(bufoff, gbase) do { _Pragma("unroll") for (int _i = 0; _i < 2; ++_i) \
;         __builtin_amdgcn_global_load_lds((const unsigned*)((const char*)(gbase) + voff[_i]), (LAS unsigned*)(lds + (bufoff) + ldsw + _i * 8192), 16, 0, 0); } while (0)
; #define PG8_LDA(dst, b, h) do { _Pragma("unroll") for (int m = 0; m < 4; ++m) _Pragma("unroll") for (int k = 0; k < 2; ++k) dst[m][k] = *(const LAS bf16x8*)(lds + PG8_SA(b, h) + aoff + m * 2048 + k * 1024); } while (0)
; #define PG8_LDB(dst, b, h) do { _Pragma("unroll") for (int n = 0; n < 2; ++n) _Pragma("unroll") for (int k = 0; k < 2; ++k) dst[n][k] = *(const LAS bf16x8*)(lds + PG8_SB(b, h) + boff + n * 2048 + k * 1024); } while (0)
; #define PG8_WAIT_V(n) asm volatile("s_waitcnt vmcnt(" #n ")" ::: "memory")
; #define PG8_WAIT_L(n) asm volatile("s_waitcnt lgkmcnt(" #n ")" ::: "memory")
; #define PG8_BAR __builtin_amdgcn_s_barrier()
; #define PG8_SCHED __builtin_amdgcn_sched_barrier(0)
;     ...
;             PG8_LDA(At, 0, 1); PG8_STAGE(PG8_SA(0, 0), a2);
;             PG8_BAR; PG8_WAIT_L(0); PG8_MMA(1, 0, At, B0); PG8_BAR; PG8_SCHED;
;             PG8_STAGE(PG8_SB(0, 1), b2 + hstep);
;             PG8_WAIT_V(6); PG8_BAR; PG8_MMA(1, 1, At, B1); PG8_BAR;
;             PG8_LDB(B0, 1, 0); PG8_SCHED; PG8_LDA(At, 1, 0); PG8_STAGE(PG8_SA(0, 1), a2 + hstep);
;             PG8_WAIT_L(8); PG8_BAR; PG8_WAIT_L(0); PG8_MMA(0, 0, At, B0); PG8_BAR; PG8_SCHED;
	s_waitcnt lgkmcnt(0)
	s_setprio 1
	s_waitcnt lgkmcnt(0)
	v_mfma_f32_16x16x32_bf16 v[66:69], v[226:229], v[194:197], v[66:69]
	v_mfma_f32_16x16x32_bf16 v[38:41], v[234:237], v[194:197], v[38:41]
	v_mfma_f32_16x16x32_bf16 v[58:61], v[226:229], v[202:205], v[58:61]
	v_mfma_f32_16x16x32_bf16 v[26:29], v[234:237], v[202:205], v[26:29]
	v_mfma_f32_16x16x32_bf16 v[54:57], v[226:229], v[210:213], v[54:57]
	v_mfma_f32_16x16x32_bf16 v[22:25], v[234:237], v[210:213], v[22:25]
	v_mfma_f32_16x16x32_bf16 v[50:53], v[226:229], v[218:221], v[50:53]
	v_mfma_f32_16x16x32_bf16 v[18:21], v[234:237], v[218:221], v[18:21]
	v_mfma_f32_16x16x32_bf16 v[66:69], v[230:233], v[198:201], v[66:69]
	v_mfma_f32_16x16x32_bf16 v[38:41], v[238:241], v[198:201], v[38:41]
	v_mfma_f32_16x16x32_bf16 v[58:61], v[230:233], v[206:209], v[58:61]
	v_mfma_f32_16x16x32_bf16 v[26:29], v[238:241], v[206:209], v[26:29]
	v_mfma_f32_16x16x32_bf16 v[54:57], v[230:233], v[214:217], v[54:57]
	v_mfma_f32_16x16x32_bf16 v[22:25], v[238:241], v[214:217], v[22:25]
	v_mfma_f32_16x16x32_bf16 v[50:53], v[230:233], v[222:225], v[50:53]
	v_mfma_f32_16x16x32_bf16 v[18:21], v[238:241], v[222:225], v[18:21]
	s_setprio 0
	s_mov_b32 m0, s56
	v_lshl_add_u64 v[242:243], s[52:53], 0, v[132:133]
	s_barrier
	ds_read_b128 v[194:197], v160 offset:16384
	ds_read_b128 v[198:201], v160 offset:17408
	ds_read_b128 v[202:205], v160 offset:18432
	ds_read_b128 v[206:209], v160 offset:19456
	ds_read_b128 v[210:213], v160 offset:20480
	ds_read_b128 v[214:217], v160 offset:21504
	ds_read_b128 v[218:221], v160 offset:22528
	ds_read_b128 v[222:225], v160 offset:23552
	global_load_lds_dwordx4 v[242:243], off
	v_lshl_add_u64 v[244:245], s[52:53], 0, v[130:131]
	s_mov_b32 m0, s57
	s_nop 0
	global_load_lds_dwordx4 v[244:245], off
	s_barrier
	s_waitcnt lgkmcnt(0)
	s_setprio 1
	s_waitcnt lgkmcnt(0)
	v_mfma_f32_16x16x32_bf16 v[110:113], v[154:157], v[194:197], v[110:113]
	v_mfma_f32_16x16x32_bf16 v[78:81], v[166:169], v[194:197], v[78:81]
	v_mfma_f32_16x16x32_bf16 v[106:109], v[154:157], v[202:205], v[106:109]
	v_mfma_f32_16x16x32_bf16 v[74:77], v[166:169], v[202:205], v[74:77]
	v_mfma_f32_16x16x32_bf16 v[98:101], v[154:157], v[210:213], v[98:101]
	v_mfma_f32_16x16x32_bf16 v[70:73], v[166:169], v[210:213], v[70:73]
	v_mfma_f32_16x16x32_bf16 v[94:97], v[154:157], v[218:221], v[94:97]
	v_mfma_f32_16x16x32_bf16 v[62:65], v[166:169], v[218:221], v[62:65]
	v_mfma_f32_16x16x32_bf16 v[110:113], v[162:165], v[198:201], v[110:113]
	v_mfma_f32_16x16x32_bf16 v[78:81], v[170:173], v[198:201], v[78:81]
	v_mfma_f32_16x16x32_bf16 v[106:109], v[162:165], v[206:209], v[106:109]
	v_mfma_f32_16x16x32_bf16 v[74:77], v[170:173], v[206:209], v[74:77]
	v_mfma_f32_16x16x32_bf16 v[98:101], v[162:165], v[214:217], v[98:101]
	v_mfma_f32_16x16x32_bf16 v[70:73], v[170:173], v[214:217], v[70:73]
	v_mfma_f32_16x16x32_bf16 v[94:97], v[162:165], v[222:225], v[94:97]
	v_mfma_f32_16x16x32_bf16 v[62:65], v[170:173], v[222:225], v[62:65]
	s_setprio 0
	s_barrier
	s_add_u32 s0, s48, 0xb0000
	s_addc_u32 s1, s49, 0
	s_add_i32 s14, s14, s36
	v_lshl_add_u64 v[154:155], s[0:1], 0, v[132:133]
	s_mov_b32 m0, s14
	s_nop 0
	global_load_lds_dwordx4 v[154:155], off
	v_lshl_add_u64 v[154:155], s[0:1], 0, v[130:131]
	s_add_i32 m0, s14, 0x2000
	s_nop 0
	global_load_lds_dwordx4 v[154:155], off
	s_waitcnt vmcnt(6)
	s_barrier
	s_setprio 1
	v_mfma_f32_16x16x32_bf16 v[46:49], v[226:229], v[194:197], v[46:49]
	v_mfma_f32_16x16x32_bf16 v[14:17], v[234:237], v[194:197], v[14:17]
	v_mfma_f32_16x16x32_bf16 v[42:45], v[226:229], v[202:205], v[42:45]
	v_mfma_f32_16x16x32_bf16 v[10:13], v[234:237], v[202:205], v[10:13]
	v_mfma_f32_16x16x32_bf16 v[34:37], v[226:229], v[210:213], v[34:37]
	v_mfma_f32_16x16x32_bf16 v[6:9], v[234:237], v[210:213], v[6:9]
	v_mfma_f32_16x16x32_bf16 v[30:33], v[226:229], v[218:221], v[30:33]
	v_mfma_f32_16x16x32_bf16 v[2:5], v[234:237], v[218:221], v[2:5]
	v_mfma_f32_16x16x32_bf16 v[46:49], v[230:233], v[198:201], v[46:49]
	v_mfma_f32_16x16x32_bf16 v[14:17], v[238:241], v[198:201], v[14:17]
	v_mfma_f32_16x16x32_bf16 v[42:45], v[230:233], v[206:209], v[42:45]
	v_mfma_f32_16x16x32_bf16 v[10:13], v[238:241], v[206:209], v[10:13]
	v_mfma_f32_16x16x32_bf16 v[34:37], v[230:233], v[214:217], v[34:37]
	v_mfma_f32_16x16x32_bf16 v[6:9], v[238:241], v[214:217], v[6:9]
	v_mfma_f32_16x16x32_bf16 v[30:33], v[230:233], v[222:225], v[30:33]
	v_mfma_f32_16x16x32_bf16 v[2:5], v[238:241], v[222:225], v[2:5]
	s_setprio 0
	s_add_i32 s14, 0, 0x18000
	v_add_u32_e32 v161, s14, v158
	s_barrier
	ds_read_b128 v[154:157], v161
	ds_read_b128 v[162:165], v161 offset:1024
	ds_read_b128 v[166:169], v161 offset:2048
	ds_read_b128 v[170:173], v161 offset:3072
	s_add_u32 s0, s52, 0xb0000
	s_addc_u32 s1, s53, 0
	s_mov_b32 m0, s58
	v_lshl_add_u64 v[226:227], s[0:1], 0, v[132:133]
	ds_read_b128 v[194:197], v160 offset:32768
	ds_read_b128 v[198:201], v160 offset:33792
	ds_read_b128 v[202:205], v160 offset:34816
	ds_read_b128 v[206:209], v160 offset:35840
	ds_read_b128 v[210:213], v160 offset:36864
	ds_read_b128 v[214:217], v160 offset:37888
	ds_read_b128 v[218:221], v160 offset:38912
	ds_read_b128 v[222:225], v160 offset:39936
	global_load_lds_dwordx4 v[226:227], off
	v_lshl_add_u64 v[226:227], s[0:1], 0, v[130:131]
	s_mov_b32 m0, s59
	s_nop 0
	global_load_lds_dwordx4 v[226:227], off
	s_waitcnt lgkmcnt(8)
	s_barrier
; #define PG8_STAGE(bufoff, gbase) do { _Pragma("unroll") for (int _i = 0; _i < 2; ++_i) \
;         __builtin_amdgcn_global_load_lds((const unsigned*)((const char*)(gbase) + voff[_i]), (LAS unsigned*)(lds + (bufoff) + ldsw + _i * 8192), 16, 0, 0); } while (0)
; #define PG8_LDA(dst, b, h) do { _Pragma("unroll") for (int m = 0; m < 4; ++m) _Pragma("unroll") for (int k = 0; k < 2; ++k) dst[m][k] = *(const LAS bf16x8*)(lds + PG8_SA(b, h) + aoff + m * 2048 + k * 1024); } while (0)
; #define PG8_LDB(dst, b, h) do { _Pragma("unroll") for (int n = 0; n < 2; ++n) _Pragma("unroll") for (int k = 0; k < 2; ++k) dst[n][k] = *(const LAS bf16x8*)(lds + PG8_SB(b, h) + boff + n * 2048 + k * 1024); } while (0)
; #define PG8_WAIT_V(n) asm volatile("s_waitcnt vmcnt(" #n ")" ::: "memory")
; #define PG8_WAIT_L(n) asm volatile("s_waitcnt lgkmcnt(" #n ")" ::: "memory")
; #define PG8_BAR __builtin_amdgcn_s_barrier()
; #define PG8_SCHED __builtin_amdgcn_sched_barrier(0)
;     ...
;             PG8_WAIT_L(8); PG8_BAR; PG8_WAIT_L(0); PG8_MMA(0, 0, At, B0); PG8_BAR; PG8_SCHED;
;             PG8_LDB(B1, 1, 1); PG8_STAGE(PG8_SB(1, 0), b3);
;             PG8_BAR; PG8_WAIT_L(0); PG8_MMA(0, 1, At, B1); PG8_BAR;
;             PG8_LDA(At, 1, 1); PG8_STAGE(PG8_SA(1, 0), a3);
;             PG8_BAR; PG8_WAIT_L(0); PG8_MMA(1, 0, At, B0); PG8_BAR; PG8_SCHED;
;             PG8_STAGE(PG8_SB(1, 1), b3 + hstep);
;             PG8_WAIT_V(6); PG8_BAR; PG8_MMA(1, 1, At, B1); PG8_BAR;
	s_waitcnt lgkmcnt(0)
	s_setprio 1
	s_waitcnt lgkmcnt(0)
	v_mfma_f32_16x16x32_bf16 v[126:129], v[154:157], v[194:197], v[126:129]
	v_mfma_f32_16x16x32_bf16 v[102:105], v[166:169], v[194:197], v[102:105]
	v_mfma_f32_16x16x32_bf16 v[122:125], v[154:157], v[202:205], v[122:125]
	v_mfma_f32_16x16x32_bf16 v[90:93], v[166:169], v[202:205], v[90:93]
	v_mfma_f32_16x16x32_bf16 v[118:121], v[154:157], v[210:213], v[118:121]
	v_mfma_f32_16x16x32_bf16 v[86:89], v[166:169], v[210:213], v[86:89]
	v_mfma_f32_16x16x32_bf16 v[114:117], v[154:157], v[218:221], v[114:117]
	v_mfma_f32_16x16x32_bf16 v[82:85], v[166:169], v[218:221], v[82:85]
	v_mfma_f32_16x16x32_bf16 v[126:129], v[162:165], v[198:201], v[126:129]
	v_mfma_f32_16x16x32_bf16 v[102:105], v[170:173], v[198:201], v[102:105]
	v_mfma_f32_16x16x32_bf16 v[122:125], v[162:165], v[206:209], v[122:125]
	v_mfma_f32_16x16x32_bf16 v[90:93], v[170:173], v[206:209], v[90:93]
	v_mfma_f32_16x16x32_bf16 v[118:121], v[162:165], v[214:217], v[118:121]
	v_mfma_f32_16x16x32_bf16 v[86:89], v[170:173], v[214:217], v[86:89]
	v_mfma_f32_16x16x32_bf16 v[114:117], v[162:165], v[222:225], v[114:117]
	v_mfma_f32_16x16x32_bf16 v[82:85], v[170:173], v[222:225], v[82:85]
	s_setprio 0
	s_barrier
	s_add_i32 s15, 0, 0x1c000
	s_add_i32 s0, s14, s36
	v_add_u32_e32 v161, s15, v158
	v_lshl_add_u64 v[174:175], v[174:175], 0, s[88:89]
	s_mov_b32 m0, s0
	ds_read_b128 v[226:229], v161
	ds_read_b128 v[230:233], v161 offset:1024
	ds_read_b128 v[234:237], v161 offset:2048
	ds_read_b128 v[238:241], v161 offset:3072
	global_load_lds_dwordx4 v[174:175], off
	v_lshl_add_u64 v[174:175], v[192:193], 0, s[88:89]
	s_add_i32 m0, s0, 0x2000
	s_nop 0
	global_load_lds_dwordx4 v[174:175], off
	s_barrier
	s_waitcnt lgkmcnt(0)
	s_setprio 1
	s_waitcnt lgkmcnt(0)
	v_mfma_f32_16x16x32_bf16 v[66:69], v[226:229], v[194:197], v[66:69]
	v_mfma_f32_16x16x32_bf16 v[38:41], v[234:237], v[194:197], v[38:41]
	v_mfma_f32_16x16x32_bf16 v[58:61], v[226:229], v[202:205], v[58:61]
	v_mfma_f32_16x16x32_bf16 v[26:29], v[234:237], v[202:205], v[26:29]
	v_mfma_f32_16x16x32_bf16 v[54:57], v[226:229], v[210:213], v[54:57]
	v_mfma_f32_16x16x32_bf16 v[22:25], v[234:237], v[210:213], v[22:25]
	v_mfma_f32_16x16x32_bf16 v[50:53], v[226:229], v[218:221], v[50:53]
	v_mfma_f32_16x16x32_bf16 v[18:21], v[234:237], v[218:221], v[18:21]
	v_mfma_f32_16x16x32_bf16 v[66:69], v[230:233], v[198:201], v[66:69]
	v_mfma_f32_16x16x32_bf16 v[38:41], v[238:241], v[198:201], v[38:41]
	v_mfma_f32_16x16x32_bf16 v[58:61], v[230:233], v[206:209], v[58:61]
	v_mfma_f32_16x16x32_bf16 v[26:29], v[238:241], v[206:209], v[26:29]
	v_mfma_f32_16x16x32_bf16 v[54:57], v[230:233], v[214:217], v[54:57]
	v_mfma_f32_16x16x32_bf16 v[22:25], v[238:241], v[214:217], v[22:25]
	v_mfma_f32_16x16x32_bf16 v[50:53], v[230:233], v[222:225], v[50:53]
	v_mfma_f32_16x16x32_bf16 v[18:21], v[238:241], v[222:225], v[18:21]
	s_setprio 0
	s_mov_b32 m0, s60
	v_lshl_add_u64 v[174:175], v[242:243], 0, s[88:89]
	s_barrier
	ds_read_b128 v[194:197], v160 offset:49152
	ds_read_b128 v[198:201], v160 offset:50176
	ds_read_b128 v[202:205], v160 offset:51200
	ds_read_b128 v[206:209], v160 offset:52224
	ds_read_b128 v[210:213], v160 offset:53248
	ds_read_b128 v[214:217], v160 offset:54272
	ds_read_b128 v[218:221], v160 offset:55296
	ds_read_b128 v[222:225], v160 offset:56320
	global_load_lds_dwordx4 v[174:175], off
	v_lshl_add_u64 v[174:175], v[244:245], 0, s[88:89]
	s_mov_b32 m0, s61
	s_nop 0
	global_load_lds_dwordx4 v[174:175], off
	s_barrier
	s_waitcnt lgkmcnt(0)
	s_setprio 1
	s_waitcnt lgkmcnt(0)
	v_mfma_f32_16x16x32_bf16 v[110:113], v[154:157], v[194:197], v[110:113]
	v_mfma_f32_16x16x32_bf16 v[78:81], v[166:169], v[194:197], v[78:81]
	v_mfma_f32_16x16x32_bf16 v[106:109], v[154:157], v[202:205], v[106:109]
	v_mfma_f32_16x16x32_bf16 v[74:77], v[166:169], v[202:205], v[74:77]
	v_mfma_f32_16x16x32_bf16 v[98:101], v[154:157], v[210:213], v[98:101]
	v_mfma_f32_16x16x32_bf16 v[70:73], v[166:169], v[210:213], v[70:73]
	v_mfma_f32_16x16x32_bf16 v[94:97], v[154:157], v[218:221], v[94:97]
	v_mfma_f32_16x16x32_bf16 v[62:65], v[166:169], v[218:221], v[62:65]
	v_mfma_f32_16x16x32_bf16 v[110:113], v[162:165], v[198:201], v[110:113]
	v_mfma_f32_16x16x32_bf16 v[78:81], v[170:173], v[198:201], v[78:81]
	v_mfma_f32_16x16x32_bf16 v[106:109], v[162:165], v[206:209], v[106:109]
	v_mfma_f32_16x16x32_bf16 v[74:77], v[170:173], v[206:209], v[74:77]
	v_mfma_f32_16x16x32_bf16 v[98:101], v[162:165], v[214:217], v[98:101]
	v_mfma_f32_16x16x32_bf16 v[70:73], v[170:173], v[214:217], v[70:73]
	v_mfma_f32_16x16x32_bf16 v[94:97], v[162:165], v[222:225], v[94:97]
	v_mfma_f32_16x16x32_bf16 v[62:65], v[170:173], v[222:225], v[62:65]
	s_setprio 0
	s_barrier
	s_add_u32 s0, s48, 0xb0080
	s_addc_u32 s1, s49, 0
	s_add_i32 s14, s15, s36
	v_lshl_add_u64 v[154:155], s[0:1], 0, v[132:133]
	s_mov_b32 m0, s14
	s_nop 0
	global_load_lds_dwordx4 v[154:155], off
	v_lshl_add_u64 v[154:155], s[0:1], 0, v[130:131]
	s_add_i32 m0, s14, 0x2000
	s_nop 0
	global_load_lds_dwordx4 v[154:155], off
	s_waitcnt vmcnt(6)
	s_barrier
;     __device__ __forceinline__ void operator()(Acc& acc, int pm, int pn, int wr, int wc, int fr, int fq) const {
;         const int brow = pm * 256;
;         const bool lat = brow < T_LAT;
;         const float* xin = lat ? xin_lat : xin_ctx;
;         float* xout = lat ? xout_lat : xout_ctx;
;         const int rsub = lat ? 0 : T_LAT;
;         const int mi = lat ? (brow >> 12) : 8;
;         const int c0 = pn * 256 + wc * 32 + fq * 4;
;         const float* gp = modv_l + (size_t)mi * 6144 + gate_i * 1024 + c0;
; #pragma unroll
;         for (int bj = 0; bj < 2; ++bj)
; #pragma unroll
;             for (int n = 0; n < 2; ++n) {
;                 const f32x4 gv = *reinterpret_cast<const f32x4*>(gp + bj * 128 + n * 16);
; #pragma unroll
;                 for (int ai = 0; ai < 2; ++ai)
; #pragma unroll
;                     for (int m = 0; m < 4; ++m) {
;                         const size_t o = (size_t)(brow + ai * 128 + wr * 64 + m * 16 + fr - rsub) * DM + c0 + bj * 128 + n * 16;
;                         const f32x4 xi = *reinterpret_cast<const f32x4*>(xin + o);
;                         const f32x4 a = acc[ai][bj][m][n];
;                         f32x4 r = {xi[0] + gv[0] * a[0], xi[1] + gv[1] * a[1], xi[2] + gv[2] * a[2], xi[3] + gv[3] * a[3]};
;                         *reinterpret_cast<f32x4*>(xout + o) = r;
;                     }
;             }
	s_setprio 1
	v_mfma_f32_16x16x32_bf16 v[46:49], v[226:229], v[194:197], v[46:49]
	v_mfma_f32_16x16x32_bf16 v[14:17], v[234:237], v[194:197], v[14:17]
	v_mfma_f32_16x16x32_bf16 v[42:45], v[226:229], v[202:205], v[42:45]
	v_mfma_f32_16x16x32_bf16 v[10:13], v[234:237], v[202:205], v[10:13]
	v_mfma_f32_16x16x32_bf16 v[34:37], v[226:229], v[210:213], v[34:37]
	v_mfma_f32_16x16x32_bf16 v[6:9], v[234:237], v[210:213], v[6:9]
	v_mfma_f32_16x16x32_bf16 v[30:33], v[226:229], v[218:221], v[30:33]
	v_mfma_f32_16x16x32_bf16 v[2:5], v[234:237], v[218:221], v[2:5]
	v_mfma_f32_16x16x32_bf16 v[46:49], v[230:233], v[198:201], v[46:49]
	v_mfma_f32_16x16x32_bf16 v[14:17], v[238:241], v[198:201], v[14:17]
	v_mfma_f32_16x16x32_bf16 v[42:45], v[230:233], v[206:209], v[42:45]
	v_mfma_f32_16x16x32_bf16 v[10:13], v[238:241], v[206:209], v[10:13]
	v_mfma_f32_16x16x32_bf16 v[34:37], v[230:233], v[214:217], v[34:37]
	v_mfma_f32_16x16x32_bf16 v[6:9], v[238:241], v[214:217], v[6:9]
	v_mfma_f32_16x16x32_bf16 v[30:33], v[230:233], v[222:225], v[30:33]
	v_mfma_f32_16x16x32_bf16 v[2:5], v[238:241], v[222:225], v[2:5]
	s_setprio 0
	s_add_i32 s28, s28, 2
	s_add_u32 s22, s22, 0x100
	s_addc_u32 s23, s23, 0
	s_cmp_gt_u32 s28, 41
	s_mov_b64 s[14:15], s[46:47]
	s_barrier
	s_cbranch_scc0 .LBB0_1649
	s_lshl_b32 s22, s4, 8
	v_readlane_b32 s64, v254, 6
	s_cmpk_lt_i32 s4, 0x80
	v_readlane_b32 s66, v254, 8
	v_readlane_b32 s67, v254, 9
	v_readlane_b32 s68, v254, 10
	v_readlane_b32 s69, v254, 11
	s_cselect_b32 s15, s67, s69
	s_cselect_b32 s14, s66, s68
	s_cselect_b32 s23, 0, 0xffff8000
	s_min_i32 s0, s4, 0x80
	s_ashr_i32 s0, s0, 4
	s_mul_hi_i32 s1, s0, 0x6000
	s_mulk_i32 s0, 0x6000
	s_add_u32 s0, s50, s0
	s_addc_u32 s1, s51, s1
	s_add_i32 s23, s23, s22
	s_add_u32 s0, s0, 0x5000
	s_addc_u32 s1, s1, 0
	v_lshl_or_b32 v154, s7, 8, v159
	v_add_u32_e32 v172, s23, v1
	v_ashrrev_i32_e32 v155, 31, v154
	v_lshl_add_u64 v[156:157], v[154:155], 2, s[0:1]
	global_load_dwordx4 v[162:165], v[156:157], off
	global_load_dwordx4 v[166:169], v[156:157], off offset:64
	global_load_dwordx4 v[192:195], v[156:157], off offset:512
	global_load_dwordx4 v[196:199], v[156:157], off offset:576
	v_lshl_add_u32 v161, v172, 10, v154
	v_lshlrev_b32_e32 v161, 2, v161
	v_add_u32_e32 v170, 0x10000, v161
	v_add_u32_e32 v171, 0x20000, v161
	v_add_u32_e32 v154, 0x30000, v161
	v_add_u32_e32 v155, 0x80000, v161
	v_add_u32_e32 v172, 0x90000, v161
	v_add_u32_e32 v156, 0xa0000, v161
	v_add_u32_e32 v157, 0xb0000, v161
	global_load_dwordx4 v[200:203], v161, s[14:15]
	global_load_dwordx4 v[204:207], v161, s[14:15] offset:64
	global_load_dwordx4 v[208:211], v170, s[14:15]
	global_load_dwordx4 v[212:215], v170, s[14:15] offset:64
	global_load_dwordx4 v[216:219], v171, s[14:15]
	global_load_dwordx4 v[220:223], v171, s[14:15] offset:64
	global_load_dwordx4 v[224:227], v154, s[14:15]
	global_load_dwordx4 v[228:231], v154, s[14:15] offset:64
	global_load_dwordx4 v[232:235], v155, s[14:15]
	global_load_dwordx4 v[236:239], v155, s[14:15] offset:64
	global_load_dwordx4 v[240:243], v172, s[14:15]
	s_and_b64 vcc, exec, s[44:45]
	s_mov_b32 s7, s18
	s_mov_b32 s4, s19
	s_mov_b64 s[52:53], s[12:13]
	v_readlane_b32 s65, v254, 7
	v_readlane_b32 s70, v254, 12
	v_readlane_b32 s71, v254, 13
	s_waitcnt vmcnt(10)
	v_pk_fma_f32 v[126:127], v[126:127], v[162:163], v[200:201]
	v_pk_fma_f32 v[128:129], v[128:129], v[164:165], v[202:203]
	global_store_dwordx4 v161, v[126:129], s[14:15] sc1
	global_load_dwordx4 v[200:203], v172, s[14:15] offset:64
	s_waitcnt vmcnt(11)
	v_pk_fma_f32 v[102:103], v[102:103], v[166:167], v[204:205]
	v_pk_fma_f32 v[104:105], v[104:105], v[168:169], v[206:207]
	global_store_dwordx4 v161, v[102:105], s[14:15] offset:64 sc1
	global_load_dwordx4 v[204:207], v156, s[14:15]
	s_waitcnt vmcnt(12)
	v_pk_fma_f32 v[122:123], v[122:123], v[162:163], v[208:209]
	v_pk_fma_f32 v[124:125], v[124:125], v[164:165], v[210:211]
	global_store_dwordx4 v170, v[122:125], s[14:15] sc1
	global_load_dwordx4 v[208:211], v156, s[14:15] offset:64
	s_waitcnt vmcnt(13)
	v_pk_fma_f32 v[90:91], v[90:91], v[166:167], v[212:213]
	v_pk_fma_f32 v[92:93], v[92:93], v[168:169], v[214:215]
	global_store_dwordx4 v170, v[90:93], s[14:15] offset:64 sc1
	global_load_dwordx4 v[212:215], v157, s[14:15]
	s_waitcnt vmcnt(14)
	v_pk_fma_f32 v[118:119], v[118:119], v[162:163], v[216:217]
	v_pk_fma_f32 v[120:121], v[120:121], v[164:165], v[218:219]
	global_store_dwordx4 v171, v[118:121], s[14:15] sc1
	global_load_dwordx4 v[216:219], v157, s[14:15] offset:64
	s_waitcnt vmcnt(15)
	v_pk_fma_f32 v[86:87], v[86:87], v[166:167], v[220:221]
	v_pk_fma_f32 v[88:89], v[88:89], v[168:169], v[222:223]
	global_store_dwordx4 v171, v[86:89], s[14:15] offset:64 sc1
	global_load_dwordx4 v[220:223], v161, s[14:15] offset:512
	s_waitcnt vmcnt(16)
	v_pk_fma_f32 v[114:115], v[114:115], v[162:163], v[224:225]
	v_pk_fma_f32 v[116:117], v[116:117], v[164:165], v[226:227]
	global_store_dwordx4 v154, v[114:117], s[14:15] sc1
	global_load_dwordx4 v[224:227], v161, s[14:15] offset:576
	s_waitcnt vmcnt(17)
	v_pk_fma_f32 v[82:83], v[82:83], v[166:167], v[228:229]
	v_pk_fma_f32 v[84:85], v[84:85], v[168:169], v[230:231]
	global_store_dwordx4 v154, v[82:85], s[14:15] offset:64 sc1
	global_load_dwordx4 v[228:231], v170, s[14:15] offset:512
	s_waitcnt vmcnt(18)
	v_pk_fma_f32 v[110:111], v[110:111], v[162:163], v[232:233]
	v_pk_fma_f32 v[112:113], v[112:113], v[164:165], v[234:235]
	global_store_dwordx4 v155, v[110:113], s[14:15] sc1
	global_load_dwordx4 v[232:235], v170, s[14:15] offset:576
	s_waitcnt vmcnt(19)
;     __device__ __forceinline__ void operator()(Acc& acc, int pm, int pn, int wr, int wc, int fr, int fq) const {
;     ...
; #pragma unroll
;         for (int bj = 0; bj < 2; ++bj)
; #pragma unroll
;             for (int n = 0; n < 2; ++n) {
;                 const f32x4 gv = *reinterpret_cast<const f32x4*>(gp + bj * 128 + n * 16);
; #pragma unroll
;                 for (int ai = 0; ai < 2; ++ai)
; #pragma unroll
;                     for (int m = 0; m < 4; ++m) {
;                         const size_t o = (size_t)(brow + ai * 128 + wr * 64 + m * 16 + fr - rsub) * DM + c0 + bj * 128 + n * 16;
;                         const f32x4 xi = *reinterpret_cast<const f32x4*>(xin + o);
;                         const f32x4 a = acc[ai][bj][m][n];
;                         f32x4 r = {xi[0] + gv[0] * a[0], xi[1] + gv[1] * a[1], xi[2] + gv[2] * a[2], xi[3] + gv[3] * a[3]};
;                         *reinterpret_cast<f32x4*>(xout + o) = r;
;                     }
;             }
	v_pk_fma_f32 v[78:79], v[78:79], v[166:167], v[236:237]
	v_pk_fma_f32 v[80:81], v[80:81], v[168:169], v[238:239]
	global_store_dwordx4 v155, v[78:81], s[14:15] offset:64 sc1
	global_load_dwordx4 v[236:239], v171, s[14:15] offset:512
	s_waitcnt vmcnt(20)
	v_pk_fma_f32 v[106:107], v[106:107], v[162:163], v[240:241]
	v_pk_fma_f32 v[108:109], v[108:109], v[164:165], v[242:243]
	global_store_dwordx4 v172, v[106:109], s[14:15] sc1
	global_load_dwordx4 v[240:243], v171, s[14:15] offset:576
	s_waitcnt vmcnt(20)
	v_pk_fma_f32 v[74:75], v[74:75], v[166:167], v[200:201]
	v_pk_fma_f32 v[76:77], v[76:77], v[168:169], v[202:203]
	global_store_dwordx4 v172, v[74:77], s[14:15] offset:64 sc1
	global_load_dwordx4 v[200:203], v154, s[14:15] offset:512
	s_waitcnt vmcnt(20)
	v_pk_fma_f32 v[98:99], v[98:99], v[162:163], v[204:205]
	v_pk_fma_f32 v[100:101], v[100:101], v[164:165], v[206:207]
	global_store_dwordx4 v156, v[98:101], s[14:15] sc1
	global_load_dwordx4 v[204:207], v154, s[14:15] offset:576
	s_waitcnt vmcnt(20)
	v_pk_fma_f32 v[70:71], v[70:71], v[166:167], v[208:209]
	v_pk_fma_f32 v[72:73], v[72:73], v[168:169], v[210:211]
	global_store_dwordx4 v156, v[70:73], s[14:15] offset:64 sc1
	global_load_dwordx4 v[208:211], v155, s[14:15] offset:512
	s_waitcnt vmcnt(20)
	v_pk_fma_f32 v[94:95], v[94:95], v[162:163], v[212:213]
	v_pk_fma_f32 v[96:97], v[96:97], v[164:165], v[214:215]
	global_store_dwordx4 v157, v[94:97], s[14:15] sc1
	global_load_dwordx4 v[212:215], v155, s[14:15] offset:576
	s_waitcnt vmcnt(20)
	v_pk_fma_f32 v[62:63], v[62:63], v[166:167], v[216:217]
	v_pk_fma_f32 v[64:65], v[64:65], v[168:169], v[218:219]
	global_store_dwordx4 v157, v[62:65], s[14:15] offset:64 sc1
	global_load_dwordx4 v[216:219], v172, s[14:15] offset:512
	s_waitcnt vmcnt(20)
	v_pk_fma_f32 v[66:67], v[66:67], v[192:193], v[220:221]
	v_pk_fma_f32 v[68:69], v[68:69], v[194:195], v[222:223]
	global_store_dwordx4 v161, v[66:69], s[14:15] offset:512 sc1
	global_load_dwordx4 v[220:223], v172, s[14:15] offset:576
	s_waitcnt vmcnt(20)
	v_pk_fma_f32 v[38:39], v[38:39], v[196:197], v[224:225]
	v_pk_fma_f32 v[40:41], v[40:41], v[198:199], v[226:227]
	global_store_dwordx4 v161, v[38:41], s[14:15] offset:576 sc1
	global_load_dwordx4 v[224:227], v156, s[14:15] offset:512
	s_waitcnt vmcnt(20)
	v_pk_fma_f32 v[58:59], v[58:59], v[192:193], v[228:229]
	v_pk_fma_f32 v[60:61], v[60:61], v[194:195], v[230:231]
	global_store_dwordx4 v170, v[58:61], s[14:15] offset:512 sc1
	global_load_dwordx4 v[228:231], v156, s[14:15] offset:576
	s_waitcnt vmcnt(20)
	v_pk_fma_f32 v[26:27], v[26:27], v[196:197], v[232:233]
	v_pk_fma_f32 v[28:29], v[28:29], v[198:199], v[234:235]
	global_store_dwordx4 v170, v[26:29], s[14:15] offset:576 sc1
	global_load_dwordx4 v[232:235], v157, s[14:15] offset:512
	s_waitcnt vmcnt(20)
	v_pk_fma_f32 v[54:55], v[54:55], v[192:193], v[236:237]
	v_pk_fma_f32 v[56:57], v[56:57], v[194:195], v[238:239]
	global_store_dwordx4 v171, v[54:57], s[14:15] offset:512 sc1
	global_load_dwordx4 v[236:239], v157, s[14:15] offset:576
	s_waitcnt vmcnt(20)
	v_pk_fma_f32 v[22:23], v[22:23], v[196:197], v[240:241]
	v_pk_fma_f32 v[24:25], v[24:25], v[198:199], v[242:243]
	global_store_dwordx4 v171, v[22:25], s[14:15] offset:576 sc1
	s_waitcnt vmcnt(19)
	v_pk_fma_f32 v[50:51], v[50:51], v[192:193], v[200:201]
	v_pk_fma_f32 v[52:53], v[52:53], v[194:195], v[202:203]
	global_store_dwordx4 v154, v[50:53], s[14:15] offset:512 sc1
	s_waitcnt vmcnt(18)
	v_pk_fma_f32 v[18:19], v[18:19], v[196:197], v[204:205]
	v_pk_fma_f32 v[20:21], v[20:21], v[198:199], v[206:207]
	global_store_dwordx4 v154, v[18:21], s[14:15] offset:576 sc1
	s_waitcnt vmcnt(17)
	v_pk_fma_f32 v[46:47], v[46:47], v[192:193], v[208:209]
	v_pk_fma_f32 v[48:49], v[48:49], v[194:195], v[210:211]
	global_store_dwordx4 v155, v[46:49], s[14:15] offset:512 sc1
	s_waitcnt vmcnt(16)
	v_pk_fma_f32 v[14:15], v[14:15], v[196:197], v[212:213]
	v_pk_fma_f32 v[16:17], v[16:17], v[198:199], v[214:215]
	global_store_dwordx4 v155, v[14:17], s[14:15] offset:576 sc1
	s_waitcnt vmcnt(15)
	v_pk_fma_f32 v[42:43], v[42:43], v[192:193], v[216:217]
	v_pk_fma_f32 v[44:45], v[44:45], v[194:195], v[218:219]
	global_store_dwordx4 v172, v[42:45], s[14:15] offset:512 sc1
	s_waitcnt vmcnt(14)
	v_pk_fma_f32 v[10:11], v[10:11], v[196:197], v[220:221]
	v_pk_fma_f32 v[12:13], v[12:13], v[198:199], v[222:223]
	global_store_dwordx4 v172, v[10:13], s[14:15] offset:576 sc1
	s_waitcnt vmcnt(13)
	v_pk_fma_f32 v[34:35], v[34:35], v[192:193], v[224:225]
	v_pk_fma_f32 v[36:37], v[36:37], v[194:195], v[226:227]
	global_store_dwordx4 v156, v[34:37], s[14:15] offset:512 sc1
	s_waitcnt vmcnt(12)
	v_pk_fma_f32 v[6:7], v[6:7], v[196:197], v[228:229]
	v_pk_fma_f32 v[8:9], v[8:9], v[198:199], v[230:231]
	global_store_dwordx4 v156, v[6:9], s[14:15] offset:576 sc1
	s_waitcnt vmcnt(11)
	v_pk_fma_f32 v[30:31], v[30:31], v[192:193], v[232:233]
	v_pk_fma_f32 v[32:33], v[32:33], v[194:195], v[234:235]
	global_store_dwordx4 v157, v[30:33], s[14:15] offset:512 sc1
	s_waitcnt vmcnt(10)
	v_pk_fma_f32 v[2:3], v[2:3], v[196:197], v[236:237]
	v_pk_fma_f32 v[4:5], v[4:5], v[198:199], v[238:239]
	global_store_dwordx4 v157, v[2:5], s[14:15] offset:576 sc1
	s_mov_b64 s[14:15], s[10:11]
	s_mov_b64 s[0:1], 0x5000
	s_cbranch_vccz .LBB0_1642
	s_waitcnt vmcnt(0)
	s_cmpk_gt_u32 s16, 0xff
	s_cbranch_scc1 .LBB0_1653
	s_barrier

; __device__ __forceinline__ int otid() { int t = threadIdx.x; asm volatile("" : "+v"(t)); return t; }
; #define PG8_STAGE(bufoff, gbase) do { _Pragma("unroll") for (int _i = 0; _i < 2; ++_i) \
;         __builtin_amdgcn_global_load_lds((const unsigned*)((const char*)(gbase) + voff[_i]), (LAS unsigned*)(lds + (bufoff) + ldsw + _i * 8192), 16, 0, 0); } while (0)
; #define PG8_WAIT_V(n) asm volatile("s_waitcnt vmcnt(" #n ")" ::: "memory")
; #define PG8_BAR __builtin_amdgcn_s_barrier()
;     ...
;     const int tid = otid(), wid = __builtin_amdgcn_readfirstlane(tid >> 6), lane = tid & 63, wr = wid >> 2, wc = wid & 3, fr = lane & 15, fq = lane >> 4;
;     const int nt = K / GBK;
;     StaticOrder S; if (G < 0) { G = gridDim.x; cidx = blockIdx.x; } S.init(M, N, G, cidx);
;     unsigned voff[2];
; #pragma unroll
;     for (int i = 0; i < 2; ++i) { int R, C; stage_rc(tid * 16 + i * 8192, R, C); voff[i] = (unsigned)(R * K + C) * 2u; }
;     const size_t kstep = (size_t)(GBK * 2);
;     const size_t hstep = (size_t)GHALF * K * 2;
;     const size_t tstep = 2 * hstep;
;     const unsigned ldsw = (unsigned)wid * 1024u;
;     const int aoff = lds_byte(wr * 64 + fr, fq * 8), boff = lds_byte(wc * 32 + fr, fq * 8);
;     ...
;     Unit cur, nxt; int ui = 0;
;     if (!S.next(0, cur)) return;
;     f32x4 acc[2][2][4][2];
; #pragma unroll
;     for (int a = 0; a < 2; ++a)
; #pragma unroll
;         for (int b = 0; b < 2; ++b)
; #pragma unroll
;             for (int m = 0; m < 4; ++m)
; #pragma unroll
;                 for (int n = 0; n < 2; ++n) acc[a][b][m][n] = (f32x4){0.f, 0.f, 0.f, 0.f};
;     bf16x8 At[4][2], B0[2][2], B1[2][2];
;     const char* cA = (const char*)gA + (size_t)cur.pm * tstep; const char* cB = (const char*)gBt + (size_t)cur.pn * tstep;
;     PG8_STAGE(PG8_SB(0, 0), cB); PG8_STAGE(PG8_SA(0, 0), cA); PG8_STAGE(PG8_SB(0, 1), cB + hstep); PG8_STAGE(PG8_SA(0, 1), cA + hstep);
;     if (wr == 1) PG8_BAR;
;     PG8_WAIT_V(4); PG8_BAR;
;     PG8_STAGE(PG8_SB(1, 0), cB + kstep); PG8_STAGE(PG8_SA(1, 0), cA + kstep); PG8_STAGE(PG8_SB(1, 1), cB + hstep + kstep);
;     PG8_WAIT_V(6); PG8_BAR;
.LBB0_1831:
	v_bfe_u32 v154, v14, 4, 2
	v_and_b32_e32 v15, 15, v14
	v_lshlrev_b32_e32 v20, 4, v154
	v_lshlrev_b32_e32 v14, 2, v14
	v_lshl_or_b32 v1, s13, 6, v15
	v_lshl_or_b32 v15, v15, 6, v20
	s_lshl_b32 s0, s13, 13
	v_and_b32_e32 v14, 32, v14
	v_bitop3_b32 v20, v15, s0, v14 bitop3:0xde
	s_lshl_b32 s0, s12, 5
	s_and_b32 s20, s0, 0x60
	s_add_i32 m0, s7, 0x18000
	v_lshl_add_u64 v[2:3], v[2:3], 0, s[88:89]
	v_lshl_add_u64 v[16:17], s[44:45], 0, v[130:131]
	s_lshl_b32 s0, s20, 7
	s_waitcnt vmcnt(4)
	s_barrier
	global_load_lds_dwordx4 v[2:3], off
	v_lshl_add_u64 v[2:3], v[4:5], 0, s[88:89]
	s_add_i32 m0, s7, 0x1a000
	s_add_i32 s22, s7, 0x8000
	s_add_i32 s23, s7, 0xa000
	v_lshl_add_u64 v[18:19], s[44:45], 0, v[132:133]
	v_bitop3_b32 v155, v15, s0, v14 bitop3:0xde
	global_load_lds_dwordx4 v[2:3], off
	v_lshl_add_u64 v[2:3], v[16:17], 0, s[88:89]
	s_mov_b32 m0, s22
	s_add_u32 s0, s10, 0xb0080
	global_load_lds_dwordx4 v[2:3], off
	v_lshl_add_u64 v[2:3], v[18:19], 0, s[88:89]
	s_mov_b32 m0, s23
	s_addc_u32 s1, s11, 0
	global_load_lds_dwordx4 v[2:3], off
	s_add_i32 m0, s7, 0x1c000
	v_lshl_add_u64 v[2:3], s[0:1], 0, v[130:131]
	global_load_lds_dwordx4 v[2:3], off
	v_lshl_add_u64 v[2:3], s[0:1], 0, v[132:133]
	s_add_i32 m0, s7, 0x1e000
	s_movk_i32 s14, 0xb00
	global_load_lds_dwordx4 v[2:3], off
	v_lshrrev_b32_e32 v3, 1, v6
	v_mul_lo_u32 v2, v8, s14
	s_mov_b32 s15, 0xb000
	v_mad_u64_u32 v[2:3], s[0:1], v3, s15, v[2:3]
	v_or_b32_e32 v2, v2, v7
	v_readlane_b32 s12, v254, 28
	v_add_lshl_u32 v2, v2, v9, 1
	v_mov_b32_e32 v3, v0
	v_readlane_b32 s13, v254, 29
	s_waitcnt vmcnt(6)
	s_mov_b32 s28, -2
	v_add_u32_e32 v156, 0, v20
	v_lshl_add_u64 v[150:151], s[12:13], 0, v[2:3]
	v_lshrrev_b32_e32 v3, 1, v10
	v_mul_lo_u32 v2, v12, s14
	v_mad_u64_u32 v[2:3], s[0:1], v3, s15, v[2:3]
	v_or_b32_e32 v2, v2, v11
	v_add_lshl_u32 v2, v2, v13, 1
	v_mov_b32_e32 v3, v0
	v_lshl_add_u64 v[152:153], s[12:13], 0, v[2:3]
	v_mov_b32_e32 v2, 0
	s_mov_b64 s[12:13], 0xb0b0080
	v_mov_b32_e32 v3, v2
	v_mov_b32_e32 v4, v2
	v_mov_b32_e32 v5, v2
	v_mov_b32_e32 v18, v2
	v_mov_b32_e32 v19, v2
	v_mov_b32_e32 v20, v2
	v_mov_b32_e32 v21, v2
	v_mov_b32_e32 v6, v2
	v_mov_b32_e32 v7, v2
	v_mov_b32_e32 v8, v2
	v_mov_b32_e32 v9, v2
	v_mov_b32_e32 v22, v2
	v_mov_b32_e32 v23, v2
	v_mov_b32_e32 v24, v2
	v_mov_b32_e32 v25, v2
	v_mov_b32_e32 v10, v2
	v_mov_b32_e32 v11, v2
	v_mov_b32_e32 v12, v2
	v_mov_b32_e32 v13, v2
	v_mov_b32_e32 v26, v2
	v_mov_b32_e32 v27, v2
	v_mov_b32_e32 v28, v2
	v_mov_b32_e32 v29, v2
	v_mov_b32_e32 v14, v2
	v_mov_b32_e32 v15, v2
	v_mov_b32_e32 v16, v2
	v_mov_b32_e32 v17, v2
	v_mov_b32_e32 v30, v2
	v_mov_b32_e32 v31, v2
	v_mov_b32_e32 v32, v2
	v_mov_b32_e32 v33, v2
	v_mov_b32_e32 v42, v2
	v_mov_b32_e32 v43, v2
	v_mov_b32_e32 v44, v2
	v_mov_b32_e32 v45, v2
	v_mov_b32_e32 v94, v2
	v_mov_b32_e32 v95, v2
	v_mov_b32_e32 v96, v2
	v_mov_b32_e32 v97, v2
	v_mov_b32_e32 v50, v2
	v_mov_b32_e32 v51, v2
	v_mov_b32_e32 v52, v2
	v_mov_b32_e32 v53, v2
	v_mov_b32_e32 v98, v2
	v_mov_b32_e32 v99, v2
	v_mov_b32_e32 v100, v2
	v_mov_b32_e32 v101, v2
	v_mov_b32_e32 v62, v2
	v_mov_b32_e32 v63, v2
	v_mov_b32_e32 v64, v2
	v_mov_b32_e32 v65, v2
	v_mov_b32_e32 v106, v2
	v_mov_b32_e32 v107, v2
	v_mov_b32_e32 v108, v2
	v_mov_b32_e32 v109, v2
	v_mov_b32_e32 v70, v2
	v_mov_b32_e32 v71, v2
	v_mov_b32_e32 v72, v2
	v_mov_b32_e32 v73, v2
	v_mov_b32_e32 v110, v2
	v_mov_b32_e32 v111, v2
	v_mov_b32_e32 v112, v2
	v_mov_b32_e32 v113, v2
	v_mov_b32_e32 v34, v2
	v_mov_b32_e32 v35, v2
	v_mov_b32_e32 v36, v2
	v_mov_b32_e32 v37, v2
	v_mov_b32_e32 v58, v2
	v_mov_b32_e32 v59, v2
	v_mov_b32_e32 v60, v2
	v_mov_b32_e32 v61, v2
	v_mov_b32_e32 v38, v2
	v_mov_b32_e32 v39, v2
	v_mov_b32_e32 v40, v2
	v_mov_b32_e32 v41, v2
	v_mov_b32_e32 v66, v2
	v_mov_b32_e32 v67, v2
	v_mov_b32_e32 v68, v2
	v_mov_b32_e32 v69, v2
	v_mov_b32_e32 v46, v2
	v_mov_b32_e32 v47, v2
	v_mov_b32_e32 v48, v2
	v_mov_b32_e32 v49, v2
	v_mov_b32_e32 v74, v2
	v_mov_b32_e32 v75, v2
	v_mov_b32_e32 v76, v2
	v_mov_b32_e32 v77, v2
	v_mov_b32_e32 v54, v2
	v_mov_b32_e32 v55, v2
	v_mov_b32_e32 v56, v2
	v_mov_b32_e32 v57, v2
	v_mov_b32_e32 v78, v2
	v_mov_b32_e32 v79, v2
	v_mov_b32_e32 v80, v2
	v_mov_b32_e32 v81, v2
	v_mov_b32_e32 v82, v2
	v_mov_b32_e32 v83, v2
	v_mov_b32_e32 v84, v2
	v_mov_b32_e32 v85, v2
	v_mov_b32_e32 v114, v2
	v_mov_b32_e32 v115, v2
	v_mov_b32_e32 v116, v2
	v_mov_b32_e32 v117, v2
	v_mov_b32_e32 v86, v2
	v_mov_b32_e32 v87, v2
	v_mov_b32_e32 v88, v2
	v_mov_b32_e32 v89, v2
	v_mov_b32_e32 v118, v2
	v_mov_b32_e32 v119, v2
	v_mov_b32_e32 v120, v2
	v_mov_b32_e32 v121, v2
	v_mov_b32_e32 v90, v2
	v_mov_b32_e32 v91, v2
	v_mov_b32_e32 v92, v2
	v_mov_b32_e32 v93, v2
	v_mov_b32_e32 v122, v2
	v_mov_b32_e32 v123, v2
	v_mov_b32_e32 v124, v2
	v_mov_b32_e32 v125, v2
	v_mov_b32_e32 v102, v2
	v_mov_b32_e32 v103, v2
	v_mov_b32_e32 v104, v2
	v_mov_b32_e32 v105, v2
	v_mov_b32_e32 v126, v2
	v_mov_b32_e32 v127, v2
	v_mov_b32_e32 v128, v2
	v_mov_b32_e32 v129, v2
	s_barrier
; #define PG8_STAGE(bufoff, gbase) do { _Pragma("unroll") for (int _i = 0; _i < 2; ++_i) \
;         __builtin_amdgcn_global_load_lds((const unsigned*)((const char*)(gbase) + voff[_i]), (LAS unsigned*)(lds + (bufoff) + ldsw + _i * 8192), 16, 0, 0); } while (0)
; #define PG8_LDA(dst, b, h) do { _Pragma("unroll") for (int m = 0; m < 4; ++m) _Pragma("unroll") for (int k = 0; k < 2; ++k) dst[m][k] = *(const LAS bf16x8*)(lds + PG8_SA(b, h) + aoff + m * 2048 + k * 1024); } while (0)
; #define PG8_LDB(dst, b, h) do { _Pragma("unroll") for (int n = 0; n < 2; ++n) _Pragma("unroll") for (int k = 0; k < 2; ++k) dst[n][k] = *(const LAS bf16x8*)(lds + PG8_SB(b, h) + boff + n * 2048 + k * 1024); } while (0)
; #define PG8_WAIT_V(n) asm volatile("s_waitcnt vmcnt(" #n ")" ::: "memory")
; #define PG8_WAIT_L(n) asm volatile("s_waitcnt lgkmcnt(" #n ")" ::: "memory")
; #define PG8_BAR __builtin_amdgcn_s_barrier()
; #define PG8_SCHED __builtin_amdgcn_sched_barrier(0)
;     ...
;         const bool has_next = S.next(ui + 1, nxt);
;         const char* nA = has_next ? (const char*)gA + (size_t)nxt.pm * tstep : cA; const char* nB = has_next ? (const char*)gBt + (size_t)nxt.pn * tstep : cB;
;         for (int t = 0; t < nt; t += 2) {
;             const bool last = (t == nt - 2);
;             const char* a1 = cA + (size_t)(t + 1) * kstep;
;             const char* a2 = last ? nA : cA + (size_t)(t + 2) * kstep; const char* b2 = last ? nB : cB + (size_t)(t + 2) * kstep;
;             const char* a3 = a2 + kstep; const char* b3 = b2 + kstep;
;             PG8_LDB(B0, 0, 0); PG8_SCHED; PG8_LDA(At, 0, 0); PG8_STAGE(PG8_SA(1, 1), a1 + hstep);
;             PG8_WAIT_L(8); PG8_BAR; PG8_WAIT_L(0); PG8_MMA(0, 0, At, B0); PG8_BAR; PG8_SCHED;
;             PG8_LDB(B1, 0, 1); PG8_STAGE(PG8_SB(0, 0), b2);
;             PG8_BAR; PG8_WAIT_L(0); PG8_MMA(0, 1, At, B1); PG8_BAR;
;             PG8_LDA(At, 0, 1); PG8_STAGE(PG8_SA(0, 0), a2);
;             PG8_BAR; PG8_WAIT_L(0); PG8_MMA(1, 0, At, B0); PG8_BAR; PG8_SCHED;
;             PG8_STAGE(PG8_SB(0, 1), b2 + hstep);
;             PG8_WAIT_V(6); PG8_BAR; PG8_MMA(1, 1, At, B1); PG8_BAR;
.LBB0_1832:
	s_add_u32 s0, s12, 0xf4f50080
	s_addc_u32 s1, s13, -1
	s_cmp_lg_u32 s28, 40
	s_cselect_b32 s0, s0, 0
	s_cselect_b32 s1, s1, 0
	s_add_u32 s40, s44, s0
	s_addc_u32 s41, s45, s1
	s_add_i32 s29, 0, 0x10000
	v_add_u32_e32 v157, s29, v155
	ds_read_b128 v[158:161], v157
	ds_read_b128 v[162:165], v157 offset:1024
	ds_read_b128 v[166:169], v157 offset:2048
	ds_read_b128 v[170:173], v157 offset:3072
	s_add_u32 s14, s10, s0
	s_addc_u32 s15, s11, s1
	v_lshl_add_u64 v[174:175], v[150:151], 0, s[12:13]
	s_add_i32 m0, s7, 0xc000
	ds_read_b128 v[194:197], v156
	ds_read_b128 v[198:201], v156 offset:1024
	ds_read_b128 v[202:205], v156 offset:2048
	ds_read_b128 v[206:209], v156 offset:3072
	ds_read_b128 v[210:213], v156 offset:4096
	ds_read_b128 v[214:217], v156 offset:5120
	ds_read_b128 v[218:221], v156 offset:6144
	ds_read_b128 v[222:225], v156 offset:7168
	global_load_lds_dwordx4 v[174:175], off
	v_lshl_add_u64 v[174:175], v[152:153], 0, s[12:13]
	s_add_i32 m0, s7, 0xe000
	s_nop 0
	global_load_lds_dwordx4 v[174:175], off
	s_waitcnt lgkmcnt(8)
	s_barrier
	s_waitcnt lgkmcnt(0)
	s_setprio 1
	s_waitcnt lgkmcnt(0)
	v_mfma_f32_16x16x32_bf16 v[126:129], v[158:161], v[194:197], v[126:129]
	v_mfma_f32_16x16x32_bf16 v[102:105], v[166:169], v[194:197], v[102:105]
	v_mfma_f32_16x16x32_bf16 v[122:125], v[158:161], v[202:205], v[122:125]
	v_mfma_f32_16x16x32_bf16 v[90:93], v[166:169], v[202:205], v[90:93]
	v_mfma_f32_16x16x32_bf16 v[118:121], v[158:161], v[210:213], v[118:121]
	v_mfma_f32_16x16x32_bf16 v[86:89], v[166:169], v[210:213], v[86:89]
	v_mfma_f32_16x16x32_bf16 v[114:117], v[158:161], v[218:221], v[114:117]
	v_mfma_f32_16x16x32_bf16 v[82:85], v[166:169], v[218:221], v[82:85]
	v_mfma_f32_16x16x32_bf16 v[126:129], v[162:165], v[198:201], v[126:129]
	v_mfma_f32_16x16x32_bf16 v[102:105], v[170:173], v[198:201], v[102:105]
	v_mfma_f32_16x16x32_bf16 v[122:125], v[162:165], v[206:209], v[122:125]
	v_mfma_f32_16x16x32_bf16 v[90:93], v[170:173], v[206:209], v[90:93]
	v_mfma_f32_16x16x32_bf16 v[118:121], v[162:165], v[214:217], v[118:121]
	v_mfma_f32_16x16x32_bf16 v[86:89], v[170:173], v[214:217], v[86:89]
	v_mfma_f32_16x16x32_bf16 v[114:117], v[162:165], v[222:225], v[114:117]
	v_mfma_f32_16x16x32_bf16 v[82:85], v[170:173], v[222:225], v[82:85]
	s_setprio 0
	s_barrier
	s_add_i32 s30, 0, 0x14000
	s_add_i32 s0, s29, s4
	v_add_u32_e32 v157, s30, v155
	v_lshl_add_u64 v[174:175], s[14:15], 0, v[130:131]
	s_mov_b32 m0, s0
	ds_read_b128 v[226:229], v157
	ds_read_b128 v[230:233], v157 offset:1024
	ds_read_b128 v[234:237], v157 offset:2048
	ds_read_b128 v[238:241], v157 offset:3072
	global_load_lds_dwordx4 v[174:175], off
	v_lshl_add_u64 v[192:193], s[14:15], 0, v[132:133]
	s_add_i32 m0, s0, 0x2000
	s_nop 0
	global_load_lds_dwordx4 v[192:193], off
	s_barrier
	s_waitcnt lgkmcnt(0)
	s_setprio 1
	s_waitcnt lgkmcnt(0)
	v_mfma_f32_16x16x32_bf16 v[78:81], v[226:229], v[194:197], v[78:81]
	v_mfma_f32_16x16x32_bf16 v[54:57], v[234:237], v[194:197], v[54:57]
	v_mfma_f32_16x16x32_bf16 v[74:77], v[226:229], v[202:205], v[74:77]
	v_mfma_f32_16x16x32_bf16 v[46:49], v[234:237], v[202:205], v[46:49]
	v_mfma_f32_16x16x32_bf16 v[66:69], v[226:229], v[210:213], v[66:69]
	v_mfma_f32_16x16x32_bf16 v[38:41], v[234:237], v[210:213], v[38:41]
	v_mfma_f32_16x16x32_bf16 v[58:61], v[226:229], v[218:221], v[58:61]
	v_mfma_f32_16x16x32_bf16 v[34:37], v[234:237], v[218:221], v[34:37]
	v_mfma_f32_16x16x32_bf16 v[78:81], v[230:233], v[198:201], v[78:81]
	v_mfma_f32_16x16x32_bf16 v[54:57], v[238:241], v[198:201], v[54:57]
	v_mfma_f32_16x16x32_bf16 v[74:77], v[230:233], v[206:209], v[74:77]
	v_mfma_f32_16x16x32_bf16 v[46:49], v[238:241], v[206:209], v[46:49]
	v_mfma_f32_16x16x32_bf16 v[66:69], v[230:233], v[214:217], v[66:69]
	v_mfma_f32_16x16x32_bf16 v[38:41], v[238:241], v[214:217], v[38:41]
	v_mfma_f32_16x16x32_bf16 v[58:61], v[230:233], v[222:225], v[58:61]
	v_mfma_f32_16x16x32_bf16 v[34:37], v[238:241], v[222:225], v[34:37]
	s_setprio 0
	s_mov_b32 m0, s7
	v_lshl_add_u64 v[242:243], s[40:41], 0, v[130:131]
	s_barrier
	ds_read_b128 v[194:197], v156 offset:16384
	ds_read_b128 v[198:201], v156 offset:17408
	ds_read_b128 v[202:205], v156 offset:18432
	ds_read_b128 v[206:209], v156 offset:19456
	ds_read_b128 v[210:213], v156 offset:20480
	ds_read_b128 v[214:217], v156 offset:21504
	ds_read_b128 v[218:221], v156 offset:22528
	ds_read_b128 v[222:225], v156 offset:23552
	global_load_lds_dwordx4 v[242:243], off
	v_lshl_add_u64 v[244:245], s[40:41], 0, v[132:133]
	s_mov_b32 m0, s17
	s_nop 0
	global_load_lds_dwordx4 v[244:245], off
	s_barrier
	s_waitcnt lgkmcnt(0)
	s_setprio 1
	s_waitcnt lgkmcnt(0)
	v_mfma_f32_16x16x32_bf16 v[110:113], v[158:161], v[194:197], v[110:113]
	v_mfma_f32_16x16x32_bf16 v[70:73], v[166:169], v[194:197], v[70:73]
	v_mfma_f32_16x16x32_bf16 v[106:109], v[158:161], v[202:205], v[106:109]
	v_mfma_f32_16x16x32_bf16 v[62:65], v[166:169], v[202:205], v[62:65]
	v_mfma_f32_16x16x32_bf16 v[98:101], v[158:161], v[210:213], v[98:101]
	v_mfma_f32_16x16x32_bf16 v[50:53], v[166:169], v[210:213], v[50:53]
	v_mfma_f32_16x16x32_bf16 v[94:97], v[158:161], v[218:221], v[94:97]
	v_mfma_f32_16x16x32_bf16 v[42:45], v[166:169], v[218:221], v[42:45]
	v_mfma_f32_16x16x32_bf16 v[110:113], v[162:165], v[198:201], v[110:113]
	v_mfma_f32_16x16x32_bf16 v[70:73], v[170:173], v[198:201], v[70:73]
	v_mfma_f32_16x16x32_bf16 v[106:109], v[162:165], v[206:209], v[106:109]
	v_mfma_f32_16x16x32_bf16 v[62:65], v[170:173], v[206:209], v[62:65]
	v_mfma_f32_16x16x32_bf16 v[98:101], v[162:165], v[214:217], v[98:101]
	v_mfma_f32_16x16x32_bf16 v[50:53], v[170:173], v[214:217], v[50:53]
	v_mfma_f32_16x16x32_bf16 v[94:97], v[162:165], v[222:225], v[94:97]
	v_mfma_f32_16x16x32_bf16 v[42:45], v[170:173], v[222:225], v[42:45]
	s_setprio 0
	s_barrier
; #define PG8_STAGE(bufoff, gbase) do { _Pragma("unroll") for (int _i = 0; _i < 2; ++_i) \
;         __builtin_amdgcn_global_load_lds((const unsigned*)((const char*)(gbase) + voff[_i]), (LAS unsigned*)(lds + (bufoff) + ldsw + _i * 8192), 16, 0, 0); } while (0)
; #define PG8_LDA(dst, b, h) do { _Pragma("unroll") for (int m = 0; m < 4; ++m) _Pragma("unroll") for (int k = 0; k < 2; ++k) dst[m][k] = *(const LAS bf16x8*)(lds + PG8_SA(b, h) + aoff + m * 2048 + k * 1024); } while (0)
; #define PG8_LDB(dst, b, h) do { _Pragma("unroll") for (int n = 0; n < 2; ++n) _Pragma("unroll") for (int k = 0; k < 2; ++k) dst[n][k] = *(const LAS bf16x8*)(lds + PG8_SB(b, h) + boff + n * 2048 + k * 1024); } while (0)
; #define PG8_WAIT_V(n) asm volatile("s_waitcnt vmcnt(" #n ")" ::: "memory")
; #define PG8_WAIT_L(n) asm volatile("s_waitcnt lgkmcnt(" #n ")" ::: "memory")
; #define PG8_BAR __builtin_amdgcn_s_barrier()
; #define PG8_SCHED __builtin_amdgcn_sched_barrier(0)
;     ...
;             PG8_WAIT_V(6); PG8_BAR; PG8_MMA(1, 1, At, B1); PG8_BAR;
;             PG8_LDB(B0, 1, 0); PG8_SCHED; PG8_LDA(At, 1, 0); PG8_STAGE(PG8_SA(0, 1), a2 + hstep);
;             PG8_WAIT_L(8); PG8_BAR; PG8_WAIT_L(0); PG8_MMA(0, 0, At, B0); PG8_BAR; PG8_SCHED;
;             PG8_LDB(B1, 1, 1); PG8_STAGE(PG8_SB(1, 0), b3);
;             PG8_BAR; PG8_WAIT_L(0); PG8_MMA(0, 1, At, B1); PG8_BAR;
;             PG8_LDA(At, 1, 1); PG8_STAGE(PG8_SA(1, 0), a3);
;             PG8_BAR; PG8_WAIT_L(0); PG8_MMA(1, 0, At, B0); PG8_BAR; PG8_SCHED;
	s_add_u32 s0, s14, 0xb0000
	s_addc_u32 s1, s15, 0
	s_add_i32 s29, s30, s4
	v_lshl_add_u64 v[158:159], s[0:1], 0, v[130:131]
	s_mov_b32 m0, s29
	s_nop 0
	global_load_lds_dwordx4 v[158:159], off
	v_lshl_add_u64 v[158:159], s[0:1], 0, v[132:133]
	s_add_i32 m0, s29, 0x2000
	s_nop 0
	global_load_lds_dwordx4 v[158:159], off
	s_waitcnt vmcnt(6)
	s_barrier
	s_setprio 1
	v_mfma_f32_16x16x32_bf16 v[30:33], v[226:229], v[194:197], v[30:33]
	v_mfma_f32_16x16x32_bf16 v[14:17], v[234:237], v[194:197], v[14:17]
	v_mfma_f32_16x16x32_bf16 v[26:29], v[226:229], v[202:205], v[26:29]
	v_mfma_f32_16x16x32_bf16 v[10:13], v[234:237], v[202:205], v[10:13]
	v_mfma_f32_16x16x32_bf16 v[22:25], v[226:229], v[210:213], v[22:25]
	v_mfma_f32_16x16x32_bf16 v[6:9], v[234:237], v[210:213], v[6:9]
	v_mfma_f32_16x16x32_bf16 v[18:21], v[226:229], v[218:221], v[18:21]
	v_mfma_f32_16x16x32_bf16 v[2:5], v[234:237], v[218:221], v[2:5]
	v_mfma_f32_16x16x32_bf16 v[30:33], v[230:233], v[198:201], v[30:33]
	v_mfma_f32_16x16x32_bf16 v[14:17], v[238:241], v[198:201], v[14:17]
	v_mfma_f32_16x16x32_bf16 v[26:29], v[230:233], v[206:209], v[26:29]
	v_mfma_f32_16x16x32_bf16 v[10:13], v[238:241], v[206:209], v[10:13]
	v_mfma_f32_16x16x32_bf16 v[22:25], v[230:233], v[214:217], v[22:25]
	v_mfma_f32_16x16x32_bf16 v[6:9], v[238:241], v[214:217], v[6:9]
	v_mfma_f32_16x16x32_bf16 v[18:21], v[230:233], v[222:225], v[18:21]
	v_mfma_f32_16x16x32_bf16 v[2:5], v[238:241], v[222:225], v[2:5]
	s_setprio 0
	s_add_i32 s29, 0, 0x18000
	v_add_u32_e32 v157, s29, v155
	s_barrier
	ds_read_b128 v[158:161], v157
	ds_read_b128 v[162:165], v157 offset:1024
	ds_read_b128 v[166:169], v157 offset:2048
	ds_read_b128 v[170:173], v157 offset:3072
	s_add_u32 s0, s40, 0xb0000
	s_addc_u32 s1, s41, 0
	s_mov_b32 m0, s18
	v_lshl_add_u64 v[226:227], s[0:1], 0, v[130:131]
	ds_read_b128 v[194:197], v156 offset:32768
	ds_read_b128 v[198:201], v156 offset:33792
	ds_read_b128 v[202:205], v156 offset:34816
	ds_read_b128 v[206:209], v156 offset:35840
	ds_read_b128 v[210:213], v156 offset:36864
	ds_read_b128 v[214:217], v156 offset:37888
	ds_read_b128 v[218:221], v156 offset:38912
	ds_read_b128 v[222:225], v156 offset:39936
	global_load_lds_dwordx4 v[226:227], off
	v_lshl_add_u64 v[226:227], s[0:1], 0, v[132:133]
	s_mov_b32 m0, s19
	s_nop 0
	global_load_lds_dwordx4 v[226:227], off
	s_waitcnt lgkmcnt(8)
	s_barrier
	s_waitcnt lgkmcnt(0)
	s_setprio 1
	s_waitcnt lgkmcnt(0)
	v_mfma_f32_16x16x32_bf16 v[126:129], v[158:161], v[194:197], v[126:129]
	v_mfma_f32_16x16x32_bf16 v[102:105], v[166:169], v[194:197], v[102:105]
	v_mfma_f32_16x16x32_bf16 v[122:125], v[158:161], v[202:205], v[122:125]
	v_mfma_f32_16x16x32_bf16 v[90:93], v[166:169], v[202:205], v[90:93]
	v_mfma_f32_16x16x32_bf16 v[118:121], v[158:161], v[210:213], v[118:121]
	v_mfma_f32_16x16x32_bf16 v[86:89], v[166:169], v[210:213], v[86:89]
	v_mfma_f32_16x16x32_bf16 v[114:117], v[158:161], v[218:221], v[114:117]
	v_mfma_f32_16x16x32_bf16 v[82:85], v[166:169], v[218:221], v[82:85]
	v_mfma_f32_16x16x32_bf16 v[126:129], v[162:165], v[198:201], v[126:129]
	v_mfma_f32_16x16x32_bf16 v[102:105], v[170:173], v[198:201], v[102:105]
	v_mfma_f32_16x16x32_bf16 v[122:125], v[162:165], v[206:209], v[122:125]
	v_mfma_f32_16x16x32_bf16 v[90:93], v[170:173], v[206:209], v[90:93]
	v_mfma_f32_16x16x32_bf16 v[118:121], v[162:165], v[214:217], v[118:121]
	v_mfma_f32_16x16x32_bf16 v[86:89], v[170:173], v[214:217], v[86:89]
	v_mfma_f32_16x16x32_bf16 v[114:117], v[162:165], v[222:225], v[114:117]
	v_mfma_f32_16x16x32_bf16 v[82:85], v[170:173], v[222:225], v[82:85]
	s_setprio 0
	s_barrier
	s_add_i32 s30, 0, 0x1c000
	s_add_i32 s0, s29, s4
	v_add_u32_e32 v157, s30, v155
	v_lshl_add_u64 v[174:175], v[174:175], 0, s[88:89]
	s_mov_b32 m0, s0
	ds_read_b128 v[226:229], v157
	ds_read_b128 v[230:233], v157 offset:1024
	ds_read_b128 v[234:237], v157 offset:2048
	ds_read_b128 v[238:241], v157 offset:3072
	global_load_lds_dwordx4 v[174:175], off
	v_lshl_add_u64 v[174:175], v[192:193], 0, s[88:89]
	s_add_i32 m0, s0, 0x2000
	s_nop 0
	global_load_lds_dwordx4 v[174:175], off
	s_barrier
	s_waitcnt lgkmcnt(0)
	s_setprio 1
	s_waitcnt lgkmcnt(0)
	v_mfma_f32_16x16x32_bf16 v[78:81], v[226:229], v[194:197], v[78:81]
	v_mfma_f32_16x16x32_bf16 v[54:57], v[234:237], v[194:197], v[54:57]
	v_mfma_f32_16x16x32_bf16 v[74:77], v[226:229], v[202:205], v[74:77]
	v_mfma_f32_16x16x32_bf16 v[46:49], v[234:237], v[202:205], v[46:49]
	v_mfma_f32_16x16x32_bf16 v[66:69], v[226:229], v[210:213], v[66:69]
	v_mfma_f32_16x16x32_bf16 v[38:41], v[234:237], v[210:213], v[38:41]
	v_mfma_f32_16x16x32_bf16 v[58:61], v[226:229], v[218:221], v[58:61]
	v_mfma_f32_16x16x32_bf16 v[34:37], v[234:237], v[218:221], v[34:37]
	v_mfma_f32_16x16x32_bf16 v[78:81], v[230:233], v[198:201], v[78:81]
	v_mfma_f32_16x16x32_bf16 v[54:57], v[238:241], v[198:201], v[54:57]
	v_mfma_f32_16x16x32_bf16 v[74:77], v[230:233], v[206:209], v[74:77]
	v_mfma_f32_16x16x32_bf16 v[46:49], v[238:241], v[206:209], v[46:49]
	v_mfma_f32_16x16x32_bf16 v[66:69], v[230:233], v[214:217], v[66:69]
	v_mfma_f32_16x16x32_bf16 v[38:41], v[238:241], v[214:217], v[38:41]
	v_mfma_f32_16x16x32_bf16 v[58:61], v[230:233], v[222:225], v[58:61]
	v_mfma_f32_16x16x32_bf16 v[34:37], v[238:241], v[222:225], v[34:37]
	s_setprio 0
	s_mov_b32 m0, s22
	v_lshl_add_u64 v[174:175], v[242:243], 0, s[88:89]
	s_barrier
	ds_read_b128 v[194:197], v156 offset:49152
	ds_read_b128 v[198:201], v156 offset:50176
	ds_read_b128 v[202:205], v156 offset:51200
	ds_read_b128 v[206:209], v156 offset:52224
	ds_read_b128 v[210:213], v156 offset:53248
	ds_read_b128 v[214:217], v156 offset:54272
	ds_read_b128 v[218:221], v156 offset:55296
	ds_read_b128 v[222:225], v156 offset:56320
	global_load_lds_dwordx4 v[174:175], off
	v_lshl_add_u64 v[174:175], v[244:245], 0, s[88:89]
	s_mov_b32 m0, s23
	s_nop 0
	global_load_lds_dwordx4 v[174:175], off
	s_barrier
;     __device__ __forceinline__ void operator()(Acc& acc, int pm, int pn, int wr, int wc, int fr, int fq) const {
;         const int brow = pm * 256;
;         const bool lat = brow < T_LAT;
;         const float* xin = lat ? xin_lat : xin_ctx;
;         float* xout = lat ? xout_lat : xout_ctx;
;         const int rsub = lat ? 0 : T_LAT;
;         const int mi = lat ? (brow >> 12) : 8;
;         const int c0 = pn * 256 + wc * 32 + fq * 4;
;         const float* gp = modv_l + (size_t)mi * 6144 + gate_i * 1024 + c0;
; #pragma unroll
;         for (int bj = 0; bj < 2; ++bj)
; #pragma unroll
;             for (int n = 0; n < 2; ++n) {
;                 const f32x4 gv = *reinterpret_cast<const f32x4*>(gp + bj * 128 + n * 16);
; #pragma unroll
;                 for (int ai = 0; ai < 2; ++ai)
; #pragma unroll
;                     for (int m = 0; m < 4; ++m) {
;                         const size_t o = (size_t)(brow + ai * 128 + wr * 64 + m * 16 + fr - rsub) * DM + c0 + bj * 128 + n * 16;
;                         const f32x4 xi = *reinterpret_cast<const f32x4*>(xin + o);
;                         const f32x4 a = acc[ai][bj][m][n];
;                         f32x4 r = {xi[0] + gv[0] * a[0], xi[1] + gv[1] * a[1], xi[2] + gv[2] * a[2], xi[3] + gv[3] * a[3]};
;                         *reinterpret_cast<f32x4*>(xout + o) = r;
;                     }
;             }
	s_waitcnt lgkmcnt(0)
	s_setprio 1
	s_waitcnt lgkmcnt(0)
	v_mfma_f32_16x16x32_bf16 v[110:113], v[158:161], v[194:197], v[110:113]
	v_mfma_f32_16x16x32_bf16 v[70:73], v[166:169], v[194:197], v[70:73]
	v_mfma_f32_16x16x32_bf16 v[106:109], v[158:161], v[202:205], v[106:109]
	v_mfma_f32_16x16x32_bf16 v[62:65], v[166:169], v[202:205], v[62:65]
	v_mfma_f32_16x16x32_bf16 v[98:101], v[158:161], v[210:213], v[98:101]
	v_mfma_f32_16x16x32_bf16 v[50:53], v[166:169], v[210:213], v[50:53]
	v_mfma_f32_16x16x32_bf16 v[94:97], v[158:161], v[218:221], v[94:97]
	v_mfma_f32_16x16x32_bf16 v[42:45], v[166:169], v[218:221], v[42:45]
	v_mfma_f32_16x16x32_bf16 v[110:113], v[162:165], v[198:201], v[110:113]
	v_mfma_f32_16x16x32_bf16 v[70:73], v[170:173], v[198:201], v[70:73]
	v_mfma_f32_16x16x32_bf16 v[106:109], v[162:165], v[206:209], v[106:109]
	v_mfma_f32_16x16x32_bf16 v[62:65], v[170:173], v[206:209], v[62:65]
	v_mfma_f32_16x16x32_bf16 v[98:101], v[162:165], v[214:217], v[98:101]
	v_mfma_f32_16x16x32_bf16 v[50:53], v[170:173], v[214:217], v[50:53]
	v_mfma_f32_16x16x32_bf16 v[94:97], v[162:165], v[222:225], v[94:97]
	v_mfma_f32_16x16x32_bf16 v[42:45], v[170:173], v[222:225], v[42:45]
	s_setprio 0
	s_barrier
	s_add_u32 s0, s14, 0xb0080
	s_addc_u32 s1, s15, 0
	s_add_i32 s14, s30, s4
	v_lshl_add_u64 v[158:159], s[0:1], 0, v[130:131]
	s_mov_b32 m0, s14
	s_nop 0
	global_load_lds_dwordx4 v[158:159], off
	v_lshl_add_u64 v[158:159], s[0:1], 0, v[132:133]
	s_add_i32 m0, s14, 0x2000
	s_nop 0
	global_load_lds_dwordx4 v[158:159], off
	s_waitcnt vmcnt(6)
	s_barrier
	s_setprio 1
	v_mfma_f32_16x16x32_bf16 v[30:33], v[226:229], v[194:197], v[30:33]
	v_mfma_f32_16x16x32_bf16 v[14:17], v[234:237], v[194:197], v[14:17]
	v_mfma_f32_16x16x32_bf16 v[26:29], v[226:229], v[202:205], v[26:29]
	v_mfma_f32_16x16x32_bf16 v[10:13], v[234:237], v[202:205], v[10:13]
	v_mfma_f32_16x16x32_bf16 v[22:25], v[226:229], v[210:213], v[22:25]
	v_mfma_f32_16x16x32_bf16 v[6:9], v[234:237], v[210:213], v[6:9]
	v_mfma_f32_16x16x32_bf16 v[18:21], v[226:229], v[218:221], v[18:21]
	v_mfma_f32_16x16x32_bf16 v[2:5], v[234:237], v[218:221], v[2:5]
	v_mfma_f32_16x16x32_bf16 v[30:33], v[230:233], v[198:201], v[30:33]
	v_mfma_f32_16x16x32_bf16 v[14:17], v[238:241], v[198:201], v[14:17]
	v_mfma_f32_16x16x32_bf16 v[26:29], v[230:233], v[206:209], v[26:29]
	v_mfma_f32_16x16x32_bf16 v[10:13], v[238:241], v[206:209], v[10:13]
	v_mfma_f32_16x16x32_bf16 v[22:25], v[230:233], v[214:217], v[22:25]
	v_mfma_f32_16x16x32_bf16 v[6:9], v[238:241], v[214:217], v[6:9]
	v_mfma_f32_16x16x32_bf16 v[18:21], v[230:233], v[222:225], v[18:21]
	v_mfma_f32_16x16x32_bf16 v[2:5], v[238:241], v[222:225], v[2:5]
	s_setprio 0
	s_add_i32 s28, s28, 2
	s_add_u32 s12, s12, 0x100
	s_addc_u32 s13, s13, 0
	s_cmp_gt_u32 s28, 41
	s_barrier
	s_cbranch_scc0 .LBB0_1832
	v_readlane_b32 s0, v253, 63
	v_readlane_b32 s64, v254, 6
	v_readlane_b32 s68, v254, 10
	v_readlane_b32 s69, v254, 11
	v_readlane_b32 s65, v254, 7
	v_readlane_b32 s66, v254, 8
	v_readlane_b32 s67, v254, 9
	v_readlane_b32 s70, v254, 12
	v_readlane_b32 s71, v254, 13
	v_mov_b32_e32 v161, v0
	v_lshl_or_b32 v157, v154, 2, s0
	v_or_b32_e32 v157, s20, v157
	v_lshlrev_b32_e32 v160, 2, v157
	v_readlane_b32 s0, v253, 61
	s_nop 1
	v_lshl_add_u64 v[158:159], s[50:51], 0, v[160:161]
	v_add_u32_e32 v162, s0, v1
	s_mov_b64 s[0:1], 0x35000
	v_lshl_add_u64 v[158:159], v[158:159], 0, s[0:1]
	global_load_dwordx4 v[192:195], v[158:159], off
	global_load_dwordx4 v[196:199], v[158:159], off offset:64
	global_load_dwordx4 v[200:203], v[158:159], off offset:512
	global_load_dwordx4 v[204:207], v[158:159], off offset:576
	v_add_u32_e32 v163, 0xffff8000, v162
	v_lshl_or_b32 v164, v163, 12, v160
	v_add_u32_e32 v165, 0x10000, v164
	v_add_u32_e32 v166, 0x20000, v164
	v_add_u32_e32 v167, 0x30000, v164
	v_add_u32_e32 v168, 0x80000, v164
	v_add_u32_e32 v169, 0x90000, v164
	v_add_u32_e32 v170, 0xa0000, v164
	v_add_u32_e32 v171, 0xb0000, v164
	global_load_dwordx4 v[208:211], v164, s[68:69]
	global_load_dwordx4 v[212:215], v164, s[68:69] offset:64
	global_load_dwordx4 v[216:219], v165, s[68:69]
	global_load_dwordx4 v[220:223], v165, s[68:69] offset:64
	global_load_dwordx4 v[224:227], v166, s[68:69]
	global_load_dwordx4 v[228:231], v166, s[68:69] offset:64
	global_load_dwordx4 v[232:235], v167, s[68:69]
	global_load_dwordx4 v[236:239], v167, s[68:69] offset:64
	global_load_dwordx4 v[240:243], v168, s[68:69]
	s_cmpk_lt_u32 s16, 0x100
	s_waitcnt vmcnt(8)
	v_pk_fma_f32 v[126:127], v[126:127], v[192:193], v[208:209]
	v_pk_fma_f32 v[128:129], v[128:129], v[194:195], v[210:211]
	global_store_dwordx4 v164, v[126:129], s[68:69] sc1
	global_load_dwordx4 v[208:211], v168, s[68:69] offset:64
	s_waitcnt vmcnt(9)
	v_pk_fma_f32 v[102:103], v[102:103], v[196:197], v[212:213]
	v_pk_fma_f32 v[104:105], v[104:105], v[198:199], v[214:215]
	global_store_dwordx4 v164, v[102:105], s[68:69] offset:64 sc1
	global_load_dwordx4 v[212:215], v169, s[68:69]
	s_waitcnt vmcnt(10)
	v_pk_fma_f32 v[122:123], v[122:123], v[192:193], v[216:217]
	v_pk_fma_f32 v[124:125], v[124:125], v[194:195], v[218:219]
	global_store_dwordx4 v165, v[122:125], s[68:69] sc1
	global_load_dwordx4 v[216:219], v169, s[68:69] offset:64
	s_waitcnt vmcnt(11)
	v_pk_fma_f32 v[90:91], v[90:91], v[196:197], v[220:221]
	v_pk_fma_f32 v[92:93], v[92:93], v[198:199], v[222:223]
	global_store_dwordx4 v165, v[90:93], s[68:69] offset:64 sc1
	global_load_dwordx4 v[220:223], v170, s[68:69]
	s_waitcnt vmcnt(12)
	v_pk_fma_f32 v[118:119], v[118:119], v[192:193], v[224:225]
	v_pk_fma_f32 v[120:121], v[120:121], v[194:195], v[226:227]
	global_store_dwordx4 v166, v[118:121], s[68:69] sc1
	global_load_dwordx4 v[224:227], v170, s[68:69] offset:64
	s_waitcnt vmcnt(13)
;     __device__ __forceinline__ void operator()(Acc& acc, int pm, int pn, int wr, int wc, int fr, int fq) const {
;     ...
; #pragma unroll
;         for (int bj = 0; bj < 2; ++bj)
; #pragma unroll
;             for (int n = 0; n < 2; ++n) {
;                 const f32x4 gv = *reinterpret_cast<const f32x4*>(gp + bj * 128 + n * 16);
; #pragma unroll
;                 for (int ai = 0; ai < 2; ++ai)
; #pragma unroll
;                     for (int m = 0; m < 4; ++m) {
;                         const size_t o = (size_t)(brow + ai * 128 + wr * 64 + m * 16 + fr - rsub) * DM + c0 + bj * 128 + n * 16;
;                         const f32x4 xi = *reinterpret_cast<const f32x4*>(xin + o);
;                         const f32x4 a = acc[ai][bj][m][n];
;                         f32x4 r = {xi[0] + gv[0] * a[0], xi[1] + gv[1] * a[1], xi[2] + gv[2] * a[2], xi[3] + gv[3] * a[3]};
;                         *reinterpret_cast<f32x4*>(xout + o) = r;
;                     }
;             }
	v_pk_fma_f32 v[86:87], v[86:87], v[196:197], v[228:229]
	v_pk_fma_f32 v[88:89], v[88:89], v[198:199], v[230:231]
	global_store_dwordx4 v166, v[86:89], s[68:69] offset:64 sc1
	global_load_dwordx4 v[228:231], v171, s[68:69]
	s_waitcnt vmcnt(14)
	v_pk_fma_f32 v[114:115], v[114:115], v[192:193], v[232:233]
	v_pk_fma_f32 v[116:117], v[116:117], v[194:195], v[234:235]
	global_store_dwordx4 v167, v[114:117], s[68:69] sc1
	global_load_dwordx4 v[232:235], v171, s[68:69] offset:64
	s_waitcnt vmcnt(15)
	v_pk_fma_f32 v[82:83], v[82:83], v[196:197], v[236:237]
	v_pk_fma_f32 v[84:85], v[84:85], v[198:199], v[238:239]
	global_store_dwordx4 v167, v[82:85], s[68:69] offset:64 sc1
	global_load_dwordx4 v[236:239], v164, s[68:69] offset:512
	s_waitcnt vmcnt(16)
	v_pk_fma_f32 v[110:111], v[110:111], v[192:193], v[240:241]
	v_pk_fma_f32 v[112:113], v[112:113], v[194:195], v[242:243]
	global_store_dwordx4 v168, v[110:113], s[68:69] sc1
	global_load_dwordx4 v[240:243], v164, s[68:69] offset:576
	s_waitcnt vmcnt(16)
	v_pk_fma_f32 v[70:71], v[70:71], v[196:197], v[208:209]
	v_pk_fma_f32 v[72:73], v[72:73], v[198:199], v[210:211]
	global_store_dwordx4 v168, v[70:73], s[68:69] offset:64 sc1
	global_load_dwordx4 v[208:211], v165, s[68:69] offset:512
	s_waitcnt vmcnt(16)
	v_pk_fma_f32 v[106:107], v[106:107], v[192:193], v[212:213]
	v_pk_fma_f32 v[108:109], v[108:109], v[194:195], v[214:215]
	global_store_dwordx4 v169, v[106:109], s[68:69] sc1
	global_load_dwordx4 v[212:215], v165, s[68:69] offset:576
	s_waitcnt vmcnt(16)
	v_pk_fma_f32 v[62:63], v[62:63], v[196:197], v[216:217]
	v_pk_fma_f32 v[64:65], v[64:65], v[198:199], v[218:219]
	global_store_dwordx4 v169, v[62:65], s[68:69] offset:64 sc1
	global_load_dwordx4 v[216:219], v166, s[68:69] offset:512
	s_waitcnt vmcnt(16)
	v_pk_fma_f32 v[98:99], v[98:99], v[192:193], v[220:221]
	v_pk_fma_f32 v[100:101], v[100:101], v[194:195], v[222:223]
	global_store_dwordx4 v170, v[98:101], s[68:69] sc1
	global_load_dwordx4 v[220:223], v166, s[68:69] offset:576
	s_waitcnt vmcnt(16)
	v_pk_fma_f32 v[50:51], v[50:51], v[196:197], v[224:225]
	v_pk_fma_f32 v[52:53], v[52:53], v[198:199], v[226:227]
	global_store_dwordx4 v170, v[50:53], s[68:69] offset:64 sc1
	global_load_dwordx4 v[224:227], v167, s[68:69] offset:512
	s_waitcnt vmcnt(16)
	v_pk_fma_f32 v[94:95], v[94:95], v[192:193], v[228:229]
	v_pk_fma_f32 v[96:97], v[96:97], v[194:195], v[230:231]
	global_store_dwordx4 v171, v[94:97], s[68:69] sc1
	global_load_dwordx4 v[228:231], v167, s[68:69] offset:576
	s_waitcnt vmcnt(16)
	v_pk_fma_f32 v[42:43], v[42:43], v[196:197], v[232:233]
	v_pk_fma_f32 v[44:45], v[44:45], v[198:199], v[234:235]
	global_store_dwordx4 v171, v[42:45], s[68:69] offset:64 sc1
	global_load_dwordx4 v[232:235], v168, s[68:69] offset:512
	s_waitcnt vmcnt(16)
	v_pk_fma_f32 v[78:79], v[78:79], v[200:201], v[236:237]
	v_pk_fma_f32 v[80:81], v[80:81], v[202:203], v[238:239]
	global_store_dwordx4 v164, v[78:81], s[68:69] offset:512 sc1
	global_load_dwordx4 v[236:239], v168, s[68:69] offset:576
	s_waitcnt vmcnt(16)
	v_pk_fma_f32 v[54:55], v[54:55], v[204:205], v[240:241]
	v_pk_fma_f32 v[56:57], v[56:57], v[206:207], v[242:243]
	global_store_dwordx4 v164, v[54:57], s[68:69] offset:576 sc1
	global_load_dwordx4 v[240:243], v169, s[68:69] offset:512
	s_waitcnt vmcnt(16)
	v_pk_fma_f32 v[74:75], v[74:75], v[200:201], v[208:209]
	v_pk_fma_f32 v[76:77], v[76:77], v[202:203], v[210:211]
	global_store_dwordx4 v165, v[74:77], s[68:69] offset:512 sc1
	global_load_dwordx4 v[208:211], v169, s[68:69] offset:576
	s_waitcnt vmcnt(16)
	v_pk_fma_f32 v[46:47], v[46:47], v[204:205], v[212:213]
	v_pk_fma_f32 v[48:49], v[48:49], v[206:207], v[214:215]
	global_store_dwordx4 v165, v[46:49], s[68:69] offset:576 sc1
	global_load_dwordx4 v[212:215], v170, s[68:69] offset:512
	s_waitcnt vmcnt(16)
	v_pk_fma_f32 v[66:67], v[66:67], v[200:201], v[216:217]
	v_pk_fma_f32 v[68:69], v[68:69], v[202:203], v[218:219]
	global_store_dwordx4 v166, v[66:69], s[68:69] offset:512 sc1
	global_load_dwordx4 v[216:219], v170, s[68:69] offset:576
	s_waitcnt vmcnt(16)
	v_pk_fma_f32 v[38:39], v[38:39], v[204:205], v[220:221]
	v_pk_fma_f32 v[40:41], v[40:41], v[206:207], v[222:223]
	global_store_dwordx4 v166, v[38:41], s[68:69] offset:576 sc1
	global_load_dwordx4 v[220:223], v171, s[68:69] offset:512
	s_waitcnt vmcnt(16)
	v_pk_fma_f32 v[58:59], v[58:59], v[200:201], v[224:225]
	v_pk_fma_f32 v[60:61], v[60:61], v[202:203], v[226:227]
	global_store_dwordx4 v167, v[58:61], s[68:69] offset:512 sc1
	global_load_dwordx4 v[224:227], v171, s[68:69] offset:576
	s_waitcnt vmcnt(16)
	v_pk_fma_f32 v[34:35], v[34:35], v[204:205], v[228:229]
	v_pk_fma_f32 v[36:37], v[36:37], v[206:207], v[230:231]
	global_store_dwordx4 v167, v[34:37], s[68:69] offset:576 sc1
	s_waitcnt vmcnt(15)
	v_pk_fma_f32 v[30:31], v[30:31], v[200:201], v[232:233]
	v_pk_fma_f32 v[32:33], v[32:33], v[202:203], v[234:235]
	global_store_dwordx4 v168, v[30:33], s[68:69] offset:512 sc1
	s_waitcnt vmcnt(14)
	v_pk_fma_f32 v[14:15], v[14:15], v[204:205], v[236:237]
	v_pk_fma_f32 v[16:17], v[16:17], v[206:207], v[238:239]
	global_store_dwordx4 v168, v[14:17], s[68:69] offset:576 sc1
	s_waitcnt vmcnt(13)
	v_pk_fma_f32 v[26:27], v[26:27], v[200:201], v[240:241]
	v_pk_fma_f32 v[28:29], v[28:29], v[202:203], v[242:243]
	global_store_dwordx4 v169, v[26:29], s[68:69] offset:512 sc1
	s_waitcnt vmcnt(12)
	v_pk_fma_f32 v[10:11], v[10:11], v[204:205], v[208:209]
	v_pk_fma_f32 v[12:13], v[12:13], v[206:207], v[210:211]
	global_store_dwordx4 v169, v[10:13], s[68:69] offset:576 sc1
	s_waitcnt vmcnt(11)
	v_pk_fma_f32 v[22:23], v[22:23], v[200:201], v[212:213]
	v_pk_fma_f32 v[24:25], v[24:25], v[202:203], v[214:215]
	global_store_dwordx4 v170, v[22:25], s[68:69] offset:512 sc1
	s_waitcnt vmcnt(10)
	v_pk_fma_f32 v[6:7], v[6:7], v[204:205], v[216:217]
	v_pk_fma_f32 v[8:9], v[8:9], v[206:207], v[218:219]
	global_store_dwordx4 v170, v[6:9], s[68:69] offset:576 sc1
	s_waitcnt vmcnt(9)
	v_pk_fma_f32 v[18:19], v[18:19], v[200:201], v[220:221]
	v_pk_fma_f32 v[20:21], v[20:21], v[202:203], v[222:223]
	global_store_dwordx4 v171, v[18:21], s[68:69] offset:512 sc1
	s_waitcnt vmcnt(8)
	v_pk_fma_f32 v[2:3], v[2:3], v[204:205], v[224:225]
	v_pk_fma_f32 v[4:5], v[4:5], v[206:207], v[226:227]
	global_store_dwordx4 v171, v[2:5], s[68:69] offset:576 sc1
	s_mov_b32 s0, 0xf80b0000
	s_mov_b32 s1, -1
	s_waitcnt vmcnt(0)
	s_cbranch_scc0 .LBB0_1835
	s_barrier
